# GEMM K-loops: removed the 64 back-to-back s_setprio 0/1 toggles in the middle of each MFMA phase (v11 SSD wait fix + conv_ffn waits kept)
# speedup vs baseline: 1.0008x; 1.0008x over previous
.LBB0_463:
	s_add_u32 s2, s0, 0xfffc0080
	s_addc_u32 s3, s1, -1
	s_cmp_eq_u32 s63, 12
	s_cselect_b32 s21, s17, s3
	s_cselect_b32 s20, s57, s2
	s_cselect_b32 s3, s19, s62
	s_cselect_b32 s2, s58, s59
	s_add_i32 s66, 0, 0x10000
	s_add_i32 s69, 0, 0x14000
	v_add_u32_e32 v154, s66, v152
	v_add_u32_e32 v170, s69, v152
	ds_read_b128 v[130:133], v154
	ds_read_b128 v[134:137], v154 offset:1024
	ds_read_b128 v[148:151], v154 offset:2048
	ds_read_b128 v[154:157], v154 offset:3072
	ds_read_b128 v[158:161], v170
	ds_read_b128 v[162:165], v170 offset:1024
	ds_read_b128 v[166:169], v170 offset:2048
	ds_read_b128 v[170:173], v170 offset:3072
	v_lshl_add_u64 v[194:195], s[0:1], 0, v[144:145]
	s_add_i32 m0, s37, 0xc000
	ds_read_b128 v[174:177], v153
	ds_read_b128 v[178:181], v153 offset:1024
	ds_read_b128 v[182:185], v153 offset:2048
	ds_read_b128 v[186:189], v153 offset:3072
	ds_read_b128 v[190:193], v153 offset:4096
	ds_read_b128 v[198:201], v153 offset:5120
	ds_read_b128 v[202:205], v153 offset:6144
	ds_read_b128 v[206:209], v153 offset:7168
	global_load_lds_dwordx4 v[194:195], off
	v_lshl_add_u64 v[194:195], s[0:1], 0, v[146:147]
	s_add_i32 m0, s37, 0xe000
	s_nop 0
	global_load_lds_dwordx4 v[194:195], off
	s_waitcnt vmcnt(8)
	s_waitcnt lgkmcnt(0)
	s_barrier
	s_setprio 1
	s_waitcnt lgkmcnt(0)
	v_mfma_f32_16x16x32_bf16 v[126:129], v[130:133], v[174:177], v[126:129]
	v_mfma_f32_16x16x32_bf16 v[122:125], v[148:151], v[174:177], v[122:125]
	v_mfma_f32_16x16x32_bf16 v[110:113], v[130:133], v[182:185], v[110:113]
	v_mfma_f32_16x16x32_bf16 v[106:109], v[148:151], v[182:185], v[106:109]
	v_mfma_f32_16x16x32_bf16 v[94:97], v[130:133], v[190:193], v[94:97]
	v_mfma_f32_16x16x32_bf16 v[90:93], v[148:151], v[190:193], v[90:93]
	v_mfma_f32_16x16x32_bf16 v[78:81], v[130:133], v[202:205], v[78:81]
	v_mfma_f32_16x16x32_bf16 v[74:77], v[148:151], v[202:205], v[74:77]
	v_mfma_f32_16x16x32_bf16 v[126:129], v[134:137], v[178:181], v[126:129]
	v_mfma_f32_16x16x32_bf16 v[122:125], v[154:157], v[178:181], v[122:125]
	v_mfma_f32_16x16x32_bf16 v[110:113], v[134:137], v[186:189], v[110:113]
	v_mfma_f32_16x16x32_bf16 v[106:109], v[154:157], v[186:189], v[106:109]
	v_mfma_f32_16x16x32_bf16 v[94:97], v[134:137], v[198:201], v[94:97]
	v_mfma_f32_16x16x32_bf16 v[90:93], v[154:157], v[198:201], v[90:93]
	v_mfma_f32_16x16x32_bf16 v[78:81], v[134:137], v[206:209], v[78:81]
	v_mfma_f32_16x16x32_bf16 v[74:77], v[154:157], v[206:209], v[74:77]
	v_mfma_f32_16x16x32_bf16 v[118:121], v[158:161], v[174:177], v[118:121]
	v_mfma_f32_16x16x32_bf16 v[114:117], v[166:169], v[174:177], v[114:117]
	v_mfma_f32_16x16x32_bf16 v[102:105], v[158:161], v[182:185], v[102:105]
	v_mfma_f32_16x16x32_bf16 v[98:101], v[166:169], v[182:185], v[98:101]
	v_mfma_f32_16x16x32_bf16 v[86:89], v[158:161], v[190:193], v[86:89]
	v_mfma_f32_16x16x32_bf16 v[82:85], v[166:169], v[190:193], v[82:85]
	v_mfma_f32_16x16x32_bf16 v[70:73], v[158:161], v[202:205], v[70:73]
	v_mfma_f32_16x16x32_bf16 v[66:69], v[166:169], v[202:205], v[66:69]
	v_mfma_f32_16x16x32_bf16 v[118:121], v[162:165], v[178:181], v[118:121]
	v_mfma_f32_16x16x32_bf16 v[114:117], v[170:173], v[178:181], v[114:117]
	v_mfma_f32_16x16x32_bf16 v[102:105], v[162:165], v[186:189], v[102:105]
	v_mfma_f32_16x16x32_bf16 v[98:101], v[170:173], v[186:189], v[98:101]
	v_mfma_f32_16x16x32_bf16 v[86:89], v[162:165], v[198:201], v[86:89]
	v_mfma_f32_16x16x32_bf16 v[82:85], v[170:173], v[198:201], v[82:85]
	v_mfma_f32_16x16x32_bf16 v[70:73], v[162:165], v[206:209], v[70:73]
	v_mfma_f32_16x16x32_bf16 v[66:69], v[170:173], v[206:209], v[66:69]
	s_setprio 0
	s_barrier
	s_add_i32 s66, s66, s36
	v_lshl_add_u64 v[194:195], s[2:3], 0, v[64:65]
	s_mov_b32 m0, s66
	ds_read_b128 v[174:177], v153 offset:16384
	ds_read_b128 v[178:181], v153 offset:17408
	ds_read_b128 v[182:185], v153 offset:18432
	ds_read_b128 v[186:189], v153 offset:19456
	ds_read_b128 v[190:193], v153 offset:20480
	ds_read_b128 v[198:201], v153 offset:21504
	ds_read_b128 v[202:205], v153 offset:22528
	ds_read_b128 v[206:209], v153 offset:23552
	global_load_lds_dwordx4 v[194:195], off
	s_add_i32 m0, s66, 0x2000
	s_add_u32 s70, s2, 0x40000
	v_lshl_add_u64 v[196:197], s[2:3], 0, v[138:139]
	s_addc_u32 s71, s3, 0
	s_add_i32 s66, s69, s36
	global_load_lds_dwordx4 v[196:197], off
	v_lshl_add_u64 v[210:211], s[70:71], 0, v[64:65]
	s_mov_b32 m0, s66
	v_lshl_add_u64 v[212:213], s[20:21], 0, v[140:141]
	global_load_lds_dwordx4 v[210:211], off
	v_lshl_add_u64 v[210:211], s[70:71], 0, v[138:139]
	s_add_i32 m0, s66, 0x2000
	s_nop 0
	global_load_lds_dwordx4 v[210:211], off
	v_lshl_add_u64 v[210:211], s[20:21], 0, v[142:143]
	s_mov_b32 m0, s37
	s_nop 0
	global_load_lds_dwordx4 v[210:211], off
	s_mov_b32 m0, s38
	s_nop 0
	global_load_lds_dwordx4 v[212:213], off
	s_waitcnt vmcnt(8)
	s_waitcnt lgkmcnt(0)
	s_barrier
	s_setprio 1
	s_waitcnt lgkmcnt(0)
	v_mfma_f32_16x16x32_bf16 v[60:63], v[130:133], v[174:177], v[60:63]
	v_mfma_f32_16x16x32_bf16 v[56:59], v[148:151], v[174:177], v[56:59]
	v_mfma_f32_16x16x32_bf16 v[44:47], v[130:133], v[182:185], v[44:47]
	v_mfma_f32_16x16x32_bf16 v[40:43], v[148:151], v[182:185], v[40:43]
	v_mfma_f32_16x16x32_bf16 v[28:31], v[130:133], v[190:193], v[28:31]
	v_mfma_f32_16x16x32_bf16 v[24:27], v[148:151], v[190:193], v[24:27]
	v_mfma_f32_16x16x32_bf16 v[12:15], v[130:133], v[202:205], v[12:15]
	v_mfma_f32_16x16x32_bf16 v[8:11], v[148:151], v[202:205], v[8:11]
	v_mfma_f32_16x16x32_bf16 v[60:63], v[134:137], v[178:181], v[60:63]
	v_mfma_f32_16x16x32_bf16 v[56:59], v[154:157], v[178:181], v[56:59]
	v_mfma_f32_16x16x32_bf16 v[44:47], v[134:137], v[186:189], v[44:47]
	v_mfma_f32_16x16x32_bf16 v[40:43], v[154:157], v[186:189], v[40:43]
	v_mfma_f32_16x16x32_bf16 v[28:31], v[134:137], v[198:201], v[28:31]
	v_mfma_f32_16x16x32_bf16 v[24:27], v[154:157], v[198:201], v[24:27]
	v_mfma_f32_16x16x32_bf16 v[12:15], v[134:137], v[206:209], v[12:15]
	v_mfma_f32_16x16x32_bf16 v[8:11], v[154:157], v[206:209], v[8:11]
	v_mfma_f32_16x16x32_bf16 v[52:55], v[158:161], v[174:177], v[52:55]
	v_mfma_f32_16x16x32_bf16 v[48:51], v[166:169], v[174:177], v[48:51]
	v_mfma_f32_16x16x32_bf16 v[36:39], v[158:161], v[182:185], v[36:39]
	v_mfma_f32_16x16x32_bf16 v[32:35], v[166:169], v[182:185], v[32:35]
	v_mfma_f32_16x16x32_bf16 v[20:23], v[158:161], v[190:193], v[20:23]
	v_mfma_f32_16x16x32_bf16 v[16:19], v[166:169], v[190:193], v[16:19]
	v_mfma_f32_16x16x32_bf16 v[4:7], v[158:161], v[202:205], v[4:7]
	v_mfma_f32_16x16x32_bf16 v[0:3], v[166:169], v[202:205], v[0:3]
	v_mfma_f32_16x16x32_bf16 v[52:55], v[162:165], v[178:181], v[52:55]
	v_mfma_f32_16x16x32_bf16 v[48:51], v[170:173], v[178:181], v[48:51]
	v_mfma_f32_16x16x32_bf16 v[36:39], v[162:165], v[186:189], v[36:39]
	v_mfma_f32_16x16x32_bf16 v[32:35], v[170:173], v[186:189], v[32:35]
	v_mfma_f32_16x16x32_bf16 v[20:23], v[162:165], v[198:201], v[20:23]
	v_mfma_f32_16x16x32_bf16 v[16:19], v[170:173], v[198:201], v[16:19]
	v_mfma_f32_16x16x32_bf16 v[4:7], v[162:165], v[206:209], v[4:7]
	v_mfma_f32_16x16x32_bf16 v[0:3], v[170:173], v[206:209], v[0:3]
	s_setprio 0
	s_barrier
	s_add_i32 s66, 0, 0x18000
	s_add_i32 s69, 0, 0x1c000
	v_add_u32_e32 v154, s66, v152
	v_add_u32_e32 v170, s69, v152
	ds_read_b128 v[130:133], v154
	ds_read_b128 v[134:137], v154 offset:1024
	ds_read_b128 v[148:151], v154 offset:2048
	ds_read_b128 v[154:157], v154 offset:3072
	ds_read_b128 v[158:161], v170
	ds_read_b128 v[162:165], v170 offset:1024
	ds_read_b128 v[166:169], v170 offset:2048
	ds_read_b128 v[170:173], v170 offset:3072
	s_add_u32 s20, s20, 0x40000
	s_addc_u32 s21, s21, 0
	s_mov_b32 m0, s39
	v_lshl_add_u64 v[214:215], s[20:21], 0, v[142:143]
	ds_read_b128 v[174:177], v153 offset:32768
	ds_read_b128 v[178:181], v153 offset:33792
	ds_read_b128 v[182:185], v153 offset:34816
	ds_read_b128 v[186:189], v153 offset:35840
	ds_read_b128 v[190:193], v153 offset:36864
	ds_read_b128 v[198:201], v153 offset:37888
	ds_read_b128 v[202:205], v153 offset:38912
	ds_read_b128 v[206:209], v153 offset:39936
	global_load_lds_dwordx4 v[214:215], off
	v_lshl_add_u64 v[214:215], s[20:21], 0, v[140:141]
	s_mov_b32 m0, s43
	s_nop 0
	global_load_lds_dwordx4 v[214:215], off
	s_waitcnt vmcnt(8)
	s_waitcnt lgkmcnt(0)
	s_barrier
	s_setprio 1
	s_waitcnt lgkmcnt(0)
	v_mfma_f32_16x16x32_bf16 v[126:129], v[130:133], v[174:177], v[126:129]
	v_mfma_f32_16x16x32_bf16 v[122:125], v[148:151], v[174:177], v[122:125]
	v_mfma_f32_16x16x32_bf16 v[110:113], v[130:133], v[182:185], v[110:113]
	v_mfma_f32_16x16x32_bf16 v[106:109], v[148:151], v[182:185], v[106:109]
	v_mfma_f32_16x16x32_bf16 v[94:97], v[130:133], v[190:193], v[94:97]
	v_mfma_f32_16x16x32_bf16 v[90:93], v[148:151], v[190:193], v[90:93]
	v_mfma_f32_16x16x32_bf16 v[78:81], v[130:133], v[202:205], v[78:81]
	v_mfma_f32_16x16x32_bf16 v[74:77], v[148:151], v[202:205], v[74:77]
	v_mfma_f32_16x16x32_bf16 v[126:129], v[134:137], v[178:181], v[126:129]
	v_mfma_f32_16x16x32_bf16 v[122:125], v[154:157], v[178:181], v[122:125]
	v_mfma_f32_16x16x32_bf16 v[110:113], v[134:137], v[186:189], v[110:113]
	v_mfma_f32_16x16x32_bf16 v[106:109], v[154:157], v[186:189], v[106:109]
	v_mfma_f32_16x16x32_bf16 v[94:97], v[134:137], v[198:201], v[94:97]
	v_mfma_f32_16x16x32_bf16 v[90:93], v[154:157], v[198:201], v[90:93]
	v_mfma_f32_16x16x32_bf16 v[78:81], v[134:137], v[206:209], v[78:81]
	v_mfma_f32_16x16x32_bf16 v[74:77], v[154:157], v[206:209], v[74:77]
	v_mfma_f32_16x16x32_bf16 v[118:121], v[158:161], v[174:177], v[118:121]
	v_mfma_f32_16x16x32_bf16 v[114:117], v[166:169], v[174:177], v[114:117]
	v_mfma_f32_16x16x32_bf16 v[102:105], v[158:161], v[182:185], v[102:105]
	v_mfma_f32_16x16x32_bf16 v[98:101], v[166:169], v[182:185], v[98:101]
	v_mfma_f32_16x16x32_bf16 v[86:89], v[158:161], v[190:193], v[86:89]
	v_mfma_f32_16x16x32_bf16 v[82:85], v[166:169], v[190:193], v[82:85]
	v_mfma_f32_16x16x32_bf16 v[70:73], v[158:161], v[202:205], v[70:73]
	v_mfma_f32_16x16x32_bf16 v[66:69], v[166:169], v[202:205], v[66:69]
	v_mfma_f32_16x16x32_bf16 v[118:121], v[162:165], v[178:181], v[118:121]
	v_mfma_f32_16x16x32_bf16 v[114:117], v[170:173], v[178:181], v[114:117]
	v_mfma_f32_16x16x32_bf16 v[102:105], v[162:165], v[186:189], v[102:105]
	v_mfma_f32_16x16x32_bf16 v[98:101], v[170:173], v[186:189], v[98:101]
	v_mfma_f32_16x16x32_bf16 v[86:89], v[162:165], v[198:201], v[86:89]
	v_mfma_f32_16x16x32_bf16 v[82:85], v[170:173], v[198:201], v[82:85]
	v_mfma_f32_16x16x32_bf16 v[70:73], v[162:165], v[206:209], v[70:73]
	v_mfma_f32_16x16x32_bf16 v[66:69], v[170:173], v[206:209], v[66:69]
	s_setprio 0
	s_barrier
	s_add_i32 s20, s66, s36
	v_lshl_add_u64 v[194:195], v[194:195], 0, s[96:97]
	s_mov_b32 m0, s20
	ds_read_b128 v[174:177], v153 offset:49152
	ds_read_b128 v[178:181], v153 offset:50176
	ds_read_b128 v[182:185], v153 offset:51200
	ds_read_b128 v[186:189], v153 offset:52224
	ds_read_b128 v[190:193], v153 offset:53248
	ds_read_b128 v[198:201], v153 offset:54272
	ds_read_b128 v[202:205], v153 offset:55296
	ds_read_b128 v[206:209], v153 offset:56320
	global_load_lds_dwordx4 v[194:195], off
	s_add_i32 m0, s20, 0x2000
	s_add_u32 s2, s2, 0x40080
	v_lshl_add_u64 v[194:195], v[196:197], 0, s[96:97]
	s_addc_u32 s3, s3, 0
	s_add_i32 s20, s69, s36
	global_load_lds_dwordx4 v[194:195], off
	v_lshl_add_u64 v[194:195], s[2:3], 0, v[64:65]
	s_mov_b32 m0, s20
	s_nop 0
	global_load_lds_dwordx4 v[194:195], off
	v_lshl_add_u64 v[194:195], s[2:3], 0, v[138:139]
	s_add_i32 m0, s20, 0x2000
	s_nop 0
	global_load_lds_dwordx4 v[194:195], off
	v_lshl_add_u64 v[194:195], v[210:211], 0, s[96:97]
	s_mov_b32 m0, s51
	s_nop 0
	global_load_lds_dwordx4 v[194:195], off
	v_lshl_add_u64 v[194:195], v[212:213], 0, s[96:97]
	s_mov_b32 m0, s52
	s_nop 0
	global_load_lds_dwordx4 v[194:195], off
	s_waitcnt vmcnt(8)
	s_waitcnt lgkmcnt(0)
	s_barrier
	s_setprio 1
	s_waitcnt lgkmcnt(0)
	v_mfma_f32_16x16x32_bf16 v[60:63], v[130:133], v[174:177], v[60:63]
	v_mfma_f32_16x16x32_bf16 v[56:59], v[148:151], v[174:177], v[56:59]
	v_mfma_f32_16x16x32_bf16 v[44:47], v[130:133], v[182:185], v[44:47]
	v_mfma_f32_16x16x32_bf16 v[40:43], v[148:151], v[182:185], v[40:43]
	v_mfma_f32_16x16x32_bf16 v[28:31], v[130:133], v[190:193], v[28:31]
	v_mfma_f32_16x16x32_bf16 v[24:27], v[148:151], v[190:193], v[24:27]
	v_mfma_f32_16x16x32_bf16 v[12:15], v[130:133], v[202:205], v[12:15]
	v_mfma_f32_16x16x32_bf16 v[8:11], v[148:151], v[202:205], v[8:11]
	v_mfma_f32_16x16x32_bf16 v[60:63], v[134:137], v[178:181], v[60:63]
	v_mfma_f32_16x16x32_bf16 v[56:59], v[154:157], v[178:181], v[56:59]
	v_mfma_f32_16x16x32_bf16 v[44:47], v[134:137], v[186:189], v[44:47]
	v_mfma_f32_16x16x32_bf16 v[40:43], v[154:157], v[186:189], v[40:43]
	v_mfma_f32_16x16x32_bf16 v[28:31], v[134:137], v[198:201], v[28:31]
	v_mfma_f32_16x16x32_bf16 v[24:27], v[154:157], v[198:201], v[24:27]
	v_mfma_f32_16x16x32_bf16 v[12:15], v[134:137], v[206:209], v[12:15]
	v_mfma_f32_16x16x32_bf16 v[8:11], v[154:157], v[206:209], v[8:11]
	v_mfma_f32_16x16x32_bf16 v[52:55], v[158:161], v[174:177], v[52:55]
	v_mfma_f32_16x16x32_bf16 v[48:51], v[166:169], v[174:177], v[48:51]
	v_mfma_f32_16x16x32_bf16 v[36:39], v[158:161], v[182:185], v[36:39]
	v_mfma_f32_16x16x32_bf16 v[32:35], v[166:169], v[182:185], v[32:35]
	v_mfma_f32_16x16x32_bf16 v[20:23], v[158:161], v[190:193], v[20:23]
	v_mfma_f32_16x16x32_bf16 v[16:19], v[166:169], v[190:193], v[16:19]
	v_mfma_f32_16x16x32_bf16 v[4:7], v[158:161], v[202:205], v[4:7]
	v_mfma_f32_16x16x32_bf16 v[0:3], v[166:169], v[202:205], v[0:3]
	v_mfma_f32_16x16x32_bf16 v[52:55], v[162:165], v[178:181], v[52:55]
	v_mfma_f32_16x16x32_bf16 v[48:51], v[170:173], v[178:181], v[48:51]
	v_mfma_f32_16x16x32_bf16 v[36:39], v[162:165], v[186:189], v[36:39]
	v_mfma_f32_16x16x32_bf16 v[32:35], v[170:173], v[186:189], v[32:35]
	v_mfma_f32_16x16x32_bf16 v[20:23], v[162:165], v[198:201], v[20:23]
	v_mfma_f32_16x16x32_bf16 v[16:19], v[170:173], v[198:201], v[16:19]
	v_mfma_f32_16x16x32_bf16 v[4:7], v[162:165], v[206:209], v[4:7]
	v_mfma_f32_16x16x32_bf16 v[0:3], v[170:173], v[206:209], v[0:3]
	s_setprio 0
	s_barrier
	s_add_i32 s63, s63, 2
	s_add_u32 s0, s0, 0x100
	s_addc_u32 s1, s1, 0
	s_add_u32 s59, s59, 0x100
	s_addc_u32 s62, s62, 0
	s_cmp_gt_u32 s63, 13
	s_cbranch_scc0 .LBB0_463
	s_and_b64 vcc, exec, s[12:13]
	s_cbranch_vccz .LBB0_466
	s_barrier

.LBB0_1306:
	s_add_u32 s2, s0, 0xfffc0080
	s_addc_u32 s3, s1, -1
	s_cmp_eq_u32 s69, 12
	s_cselect_b32 s23, s19, s3
	s_cselect_b32 s22, s59, s2
	s_cselect_b32 s3, s21, s66
	s_cselect_b32 s2, s62, s63
	s_add_i32 s70, 0, 0x10000
	s_add_i32 s76, 0, 0x14000
	v_add_u32_e32 v118, s70, v242
	v_add_u32_e32 v154, s76, v242
	ds_read_b128 v[82:85], v118
	ds_read_b128 v[94:97], v118 offset:1024
	ds_read_b128 v[110:113], v118 offset:2048
	ds_read_b128 v[118:121], v118 offset:3072
	ds_read_b128 v[130:133], v154
	ds_read_b128 v[142:145], v154 offset:1024
	ds_read_b128 v[150:153], v154 offset:2048
	ds_read_b128 v[154:157], v154 offset:3072
	v_lshl_add_u64 v[194:195], s[0:1], 0, v[204:205]
	s_add_i32 m0, s7, 0xc000
	ds_read_b128 v[162:165], v243
	ds_read_b128 v[166:169], v243 offset:1024
	ds_read_b128 v[170:173], v243 offset:2048
	ds_read_b128 v[174:177], v243 offset:3072
	ds_read_b128 v[178:181], v243 offset:4096
	ds_read_b128 v[182:185], v243 offset:5120
	ds_read_b128 v[186:189], v243 offset:6144
	ds_read_b128 v[190:193], v243 offset:7168
	global_load_lds_dwordx4 v[194:195], off
	v_lshl_add_u64 v[194:195], s[0:1], 0, v[206:207]
	s_add_i32 m0, s7, 0xe000
	s_nop 0
	global_load_lds_dwordx4 v[194:195], off
	s_waitcnt vmcnt(8)
	s_waitcnt lgkmcnt(0)
	s_barrier
	s_setprio 1
	s_waitcnt lgkmcnt(0)
	v_mfma_f32_16x16x32_bf16 v[158:161], v[82:85], v[162:165], v[158:161]
	v_mfma_f32_16x16x32_bf16 v[146:149], v[110:113], v[162:165], v[146:149]
	v_mfma_f32_16x16x32_bf16 v[126:129], v[82:85], v[170:173], v[126:129]
	v_mfma_f32_16x16x32_bf16 v[122:125], v[110:113], v[170:173], v[122:125]
	v_mfma_f32_16x16x32_bf16 v[102:105], v[82:85], v[178:181], v[102:105]
	v_mfma_f32_16x16x32_bf16 v[98:101], v[110:113], v[178:181], v[98:101]
	v_mfma_f32_16x16x32_bf16 v[78:81], v[82:85], v[186:189], v[78:81]
	v_mfma_f32_16x16x32_bf16 v[74:77], v[110:113], v[186:189], v[74:77]
	v_mfma_f32_16x16x32_bf16 v[158:161], v[94:97], v[166:169], v[158:161]
	v_mfma_f32_16x16x32_bf16 v[146:149], v[118:121], v[166:169], v[146:149]
	v_mfma_f32_16x16x32_bf16 v[126:129], v[94:97], v[174:177], v[126:129]
	v_mfma_f32_16x16x32_bf16 v[122:125], v[118:121], v[174:177], v[122:125]
	v_mfma_f32_16x16x32_bf16 v[102:105], v[94:97], v[182:185], v[102:105]
	v_mfma_f32_16x16x32_bf16 v[98:101], v[118:121], v[182:185], v[98:101]
	v_mfma_f32_16x16x32_bf16 v[78:81], v[94:97], v[190:193], v[78:81]
	v_mfma_f32_16x16x32_bf16 v[74:77], v[118:121], v[190:193], v[74:77]
	v_mfma_f32_16x16x32_bf16 v[138:141], v[130:133], v[162:165], v[138:141]
	v_mfma_f32_16x16x32_bf16 v[134:137], v[150:153], v[162:165], v[134:137]
	v_mfma_f32_16x16x32_bf16 v[114:117], v[130:133], v[170:173], v[114:117]
	v_mfma_f32_16x16x32_bf16 v[106:109], v[150:153], v[170:173], v[106:109]
	v_mfma_f32_16x16x32_bf16 v[90:93], v[130:133], v[178:181], v[90:93]
	v_mfma_f32_16x16x32_bf16 v[86:89], v[150:153], v[178:181], v[86:89]
	v_mfma_f32_16x16x32_bf16 v[70:73], v[130:133], v[186:189], v[70:73]
	v_mfma_f32_16x16x32_bf16 v[66:69], v[150:153], v[186:189], v[66:69]
	v_mfma_f32_16x16x32_bf16 v[138:141], v[142:145], v[166:169], v[138:141]
	v_mfma_f32_16x16x32_bf16 v[134:137], v[154:157], v[166:169], v[134:137]
	v_mfma_f32_16x16x32_bf16 v[114:117], v[142:145], v[174:177], v[114:117]
	v_mfma_f32_16x16x32_bf16 v[106:109], v[154:157], v[174:177], v[106:109]
	v_mfma_f32_16x16x32_bf16 v[90:93], v[142:145], v[182:185], v[90:93]
	v_mfma_f32_16x16x32_bf16 v[86:89], v[154:157], v[182:185], v[86:89]
	v_mfma_f32_16x16x32_bf16 v[70:73], v[142:145], v[190:193], v[70:73]
	v_mfma_f32_16x16x32_bf16 v[66:69], v[154:157], v[190:193], v[66:69]
	s_setprio 0
	s_barrier
	s_add_i32 s70, s70, s38
	v_lshl_add_u64 v[194:195], s[2:3], 0, v[64:65]
	s_mov_b32 m0, s70
	ds_read_b128 v[162:165], v243 offset:16384
	ds_read_b128 v[166:169], v243 offset:17408
	ds_read_b128 v[170:173], v243 offset:18432
	ds_read_b128 v[174:177], v243 offset:19456
	ds_read_b128 v[178:181], v243 offset:20480
	ds_read_b128 v[182:185], v243 offset:21504
	ds_read_b128 v[186:189], v243 offset:22528
	ds_read_b128 v[190:193], v243 offset:23552
	global_load_lds_dwordx4 v[194:195], off
	s_add_i32 m0, s70, 0x2000
	s_add_u32 s70, s2, 0x40000
	v_lshl_add_u64 v[196:197], s[2:3], 0, v[202:203]
	s_addc_u32 s71, s3, 0
	s_add_i32 s76, s76, s38
	global_load_lds_dwordx4 v[196:197], off
	v_lshl_add_u64 v[208:209], s[70:71], 0, v[64:65]
	s_mov_b32 m0, s76
	v_lshl_add_u64 v[210:211], s[22:23], 0, v[200:201]
	global_load_lds_dwordx4 v[208:209], off
	v_lshl_add_u64 v[208:209], s[70:71], 0, v[202:203]
	s_add_i32 m0, s76, 0x2000
	s_nop 0
	global_load_lds_dwordx4 v[208:209], off
	v_lshl_add_u64 v[208:209], s[22:23], 0, v[198:199]
	s_mov_b32 m0, s7
	s_nop 0
	global_load_lds_dwordx4 v[208:209], off
	s_mov_b32 m0, s9
	s_nop 0
	global_load_lds_dwordx4 v[210:211], off
	s_waitcnt vmcnt(8)
	s_waitcnt lgkmcnt(0)
	s_barrier
	s_setprio 1
	s_waitcnt lgkmcnt(0)
	v_mfma_f32_16x16x32_bf16 v[60:63], v[82:85], v[162:165], v[60:63]
	v_mfma_f32_16x16x32_bf16 v[56:59], v[110:113], v[162:165], v[56:59]
	v_mfma_f32_16x16x32_bf16 v[44:47], v[82:85], v[170:173], v[44:47]
	v_mfma_f32_16x16x32_bf16 v[40:43], v[110:113], v[170:173], v[40:43]
	v_mfma_f32_16x16x32_bf16 v[28:31], v[82:85], v[178:181], v[28:31]
	v_mfma_f32_16x16x32_bf16 v[24:27], v[110:113], v[178:181], v[24:27]
	v_mfma_f32_16x16x32_bf16 v[12:15], v[82:85], v[186:189], v[12:15]
	v_mfma_f32_16x16x32_bf16 v[8:11], v[110:113], v[186:189], v[8:11]
	v_mfma_f32_16x16x32_bf16 v[60:63], v[94:97], v[166:169], v[60:63]
	v_mfma_f32_16x16x32_bf16 v[56:59], v[118:121], v[166:169], v[56:59]
	v_mfma_f32_16x16x32_bf16 v[44:47], v[94:97], v[174:177], v[44:47]
	v_mfma_f32_16x16x32_bf16 v[40:43], v[118:121], v[174:177], v[40:43]
	v_mfma_f32_16x16x32_bf16 v[28:31], v[94:97], v[182:185], v[28:31]
	v_mfma_f32_16x16x32_bf16 v[24:27], v[118:121], v[182:185], v[24:27]
	v_mfma_f32_16x16x32_bf16 v[12:15], v[94:97], v[190:193], v[12:15]
	v_mfma_f32_16x16x32_bf16 v[8:11], v[118:121], v[190:193], v[8:11]
	v_mfma_f32_16x16x32_bf16 v[52:55], v[130:133], v[162:165], v[52:55]
	v_mfma_f32_16x16x32_bf16 v[48:51], v[150:153], v[162:165], v[48:51]
	v_mfma_f32_16x16x32_bf16 v[36:39], v[130:133], v[170:173], v[36:39]
	v_mfma_f32_16x16x32_bf16 v[32:35], v[150:153], v[170:173], v[32:35]
	v_mfma_f32_16x16x32_bf16 v[20:23], v[130:133], v[178:181], v[20:23]
	v_mfma_f32_16x16x32_bf16 v[16:19], v[150:153], v[178:181], v[16:19]
	v_mfma_f32_16x16x32_bf16 v[4:7], v[130:133], v[186:189], v[4:7]
	v_mfma_f32_16x16x32_bf16 v[0:3], v[150:153], v[186:189], v[0:3]
	v_mfma_f32_16x16x32_bf16 v[52:55], v[142:145], v[166:169], v[52:55]
	v_mfma_f32_16x16x32_bf16 v[48:51], v[154:157], v[166:169], v[48:51]
	v_mfma_f32_16x16x32_bf16 v[36:39], v[142:145], v[174:177], v[36:39]
	v_mfma_f32_16x16x32_bf16 v[32:35], v[154:157], v[174:177], v[32:35]
	v_mfma_f32_16x16x32_bf16 v[20:23], v[142:145], v[182:185], v[20:23]
	v_mfma_f32_16x16x32_bf16 v[16:19], v[154:157], v[182:185], v[16:19]
	v_mfma_f32_16x16x32_bf16 v[4:7], v[142:145], v[190:193], v[4:7]
	v_mfma_f32_16x16x32_bf16 v[0:3], v[154:157], v[190:193], v[0:3]
	s_setprio 0
	s_barrier
	s_add_i32 s70, 0, 0x18000
	s_add_i32 s71, 0, 0x1c000
	v_add_u32_e32 v118, s70, v242
	v_add_u32_e32 v154, s71, v242
	ds_read_b128 v[82:85], v118
	ds_read_b128 v[94:97], v118 offset:1024
	ds_read_b128 v[110:113], v118 offset:2048
	ds_read_b128 v[118:121], v118 offset:3072
	ds_read_b128 v[130:133], v154
	ds_read_b128 v[142:145], v154 offset:1024
	ds_read_b128 v[150:153], v154 offset:2048
	ds_read_b128 v[154:157], v154 offset:3072
	s_add_u32 s22, s22, 0x40000
	s_addc_u32 s23, s23, 0
	s_mov_b32 m0, s39
	v_lshl_add_u64 v[212:213], s[22:23], 0, v[198:199]
	ds_read_b128 v[162:165], v243 offset:32768
	ds_read_b128 v[166:169], v243 offset:33792
	ds_read_b128 v[170:173], v243 offset:34816
	ds_read_b128 v[174:177], v243 offset:35840
	ds_read_b128 v[178:181], v243 offset:36864
	ds_read_b128 v[182:185], v243 offset:37888
	ds_read_b128 v[186:189], v243 offset:38912
	ds_read_b128 v[190:193], v243 offset:39936
	global_load_lds_dwordx4 v[212:213], off
	v_lshl_add_u64 v[212:213], s[22:23], 0, v[200:201]
	s_mov_b32 m0, s47
	s_nop 0
	global_load_lds_dwordx4 v[212:213], off
	s_waitcnt vmcnt(8)
	s_waitcnt lgkmcnt(0)
	s_barrier
	s_setprio 1
	s_waitcnt lgkmcnt(0)
	v_mfma_f32_16x16x32_bf16 v[158:161], v[82:85], v[162:165], v[158:161]
	v_mfma_f32_16x16x32_bf16 v[146:149], v[110:113], v[162:165], v[146:149]
	v_mfma_f32_16x16x32_bf16 v[126:129], v[82:85], v[170:173], v[126:129]
	v_mfma_f32_16x16x32_bf16 v[122:125], v[110:113], v[170:173], v[122:125]
	v_mfma_f32_16x16x32_bf16 v[102:105], v[82:85], v[178:181], v[102:105]
	v_mfma_f32_16x16x32_bf16 v[98:101], v[110:113], v[178:181], v[98:101]
	v_mfma_f32_16x16x32_bf16 v[78:81], v[82:85], v[186:189], v[78:81]
	v_mfma_f32_16x16x32_bf16 v[74:77], v[110:113], v[186:189], v[74:77]
	v_mfma_f32_16x16x32_bf16 v[158:161], v[94:97], v[166:169], v[158:161]
	v_mfma_f32_16x16x32_bf16 v[146:149], v[118:121], v[166:169], v[146:149]
	v_mfma_f32_16x16x32_bf16 v[126:129], v[94:97], v[174:177], v[126:129]
	v_mfma_f32_16x16x32_bf16 v[122:125], v[118:121], v[174:177], v[122:125]
	v_mfma_f32_16x16x32_bf16 v[102:105], v[94:97], v[182:185], v[102:105]
	v_mfma_f32_16x16x32_bf16 v[98:101], v[118:121], v[182:185], v[98:101]
	v_mfma_f32_16x16x32_bf16 v[78:81], v[94:97], v[190:193], v[78:81]
	v_mfma_f32_16x16x32_bf16 v[74:77], v[118:121], v[190:193], v[74:77]
	v_mfma_f32_16x16x32_bf16 v[138:141], v[130:133], v[162:165], v[138:141]
	v_mfma_f32_16x16x32_bf16 v[134:137], v[150:153], v[162:165], v[134:137]
	v_mfma_f32_16x16x32_bf16 v[114:117], v[130:133], v[170:173], v[114:117]
	v_mfma_f32_16x16x32_bf16 v[106:109], v[150:153], v[170:173], v[106:109]
	v_mfma_f32_16x16x32_bf16 v[90:93], v[130:133], v[178:181], v[90:93]
	v_mfma_f32_16x16x32_bf16 v[86:89], v[150:153], v[178:181], v[86:89]
	v_mfma_f32_16x16x32_bf16 v[70:73], v[130:133], v[186:189], v[70:73]
	v_mfma_f32_16x16x32_bf16 v[66:69], v[150:153], v[186:189], v[66:69]
	v_mfma_f32_16x16x32_bf16 v[138:141], v[142:145], v[166:169], v[138:141]
	v_mfma_f32_16x16x32_bf16 v[134:137], v[154:157], v[166:169], v[134:137]
	v_mfma_f32_16x16x32_bf16 v[114:117], v[142:145], v[174:177], v[114:117]
	v_mfma_f32_16x16x32_bf16 v[106:109], v[154:157], v[174:177], v[106:109]
	v_mfma_f32_16x16x32_bf16 v[90:93], v[142:145], v[182:185], v[90:93]
	v_mfma_f32_16x16x32_bf16 v[86:89], v[154:157], v[182:185], v[86:89]
	v_mfma_f32_16x16x32_bf16 v[70:73], v[142:145], v[190:193], v[70:73]
	v_mfma_f32_16x16x32_bf16 v[66:69], v[154:157], v[190:193], v[66:69]
	s_setprio 0
	s_barrier
	s_add_i32 s22, s70, s38
	v_lshl_add_u64 v[194:195], v[194:195], 0, s[96:97]
	s_mov_b32 m0, s22
	ds_read_b128 v[162:165], v243 offset:49152
	ds_read_b128 v[166:169], v243 offset:50176
	ds_read_b128 v[170:173], v243 offset:51200
	ds_read_b128 v[174:177], v243 offset:52224
	ds_read_b128 v[178:181], v243 offset:53248
	ds_read_b128 v[182:185], v243 offset:54272
	ds_read_b128 v[186:189], v243 offset:55296
	ds_read_b128 v[190:193], v243 offset:56320
	global_load_lds_dwordx4 v[194:195], off
	s_add_i32 m0, s22, 0x2000
	s_add_u32 s2, s2, 0x40080
	v_lshl_add_u64 v[194:195], v[196:197], 0, s[96:97]
	s_addc_u32 s3, s3, 0
	s_add_i32 s22, s71, s38
	global_load_lds_dwordx4 v[194:195], off
	v_lshl_add_u64 v[194:195], s[2:3], 0, v[64:65]
	s_mov_b32 m0, s22
	s_nop 0
	global_load_lds_dwordx4 v[194:195], off
	v_lshl_add_u64 v[194:195], s[2:3], 0, v[202:203]
	s_add_i32 m0, s22, 0x2000
	s_nop 0
	global_load_lds_dwordx4 v[194:195], off
	v_lshl_add_u64 v[194:195], v[208:209], 0, s[96:97]
	s_mov_b32 m0, s52
	s_nop 0
	global_load_lds_dwordx4 v[194:195], off
	v_lshl_add_u64 v[194:195], v[210:211], 0, s[96:97]
	s_mov_b32 m0, s53
	s_nop 0
	global_load_lds_dwordx4 v[194:195], off
	s_waitcnt vmcnt(8)
	s_waitcnt lgkmcnt(0)
	s_barrier
	s_setprio 1
	s_waitcnt lgkmcnt(0)
	v_mfma_f32_16x16x32_bf16 v[60:63], v[82:85], v[162:165], v[60:63]
	v_mfma_f32_16x16x32_bf16 v[56:59], v[110:113], v[162:165], v[56:59]
	v_mfma_f32_16x16x32_bf16 v[44:47], v[82:85], v[170:173], v[44:47]
	v_mfma_f32_16x16x32_bf16 v[40:43], v[110:113], v[170:173], v[40:43]
	v_mfma_f32_16x16x32_bf16 v[28:31], v[82:85], v[178:181], v[28:31]
	v_mfma_f32_16x16x32_bf16 v[24:27], v[110:113], v[178:181], v[24:27]
	v_mfma_f32_16x16x32_bf16 v[12:15], v[82:85], v[186:189], v[12:15]
	v_mfma_f32_16x16x32_bf16 v[8:11], v[110:113], v[186:189], v[8:11]
	v_mfma_f32_16x16x32_bf16 v[60:63], v[94:97], v[166:169], v[60:63]
	v_mfma_f32_16x16x32_bf16 v[56:59], v[118:121], v[166:169], v[56:59]
	v_mfma_f32_16x16x32_bf16 v[44:47], v[94:97], v[174:177], v[44:47]
	v_mfma_f32_16x16x32_bf16 v[40:43], v[118:121], v[174:177], v[40:43]
	v_mfma_f32_16x16x32_bf16 v[28:31], v[94:97], v[182:185], v[28:31]
	v_mfma_f32_16x16x32_bf16 v[24:27], v[118:121], v[182:185], v[24:27]
	v_mfma_f32_16x16x32_bf16 v[12:15], v[94:97], v[190:193], v[12:15]
	v_mfma_f32_16x16x32_bf16 v[8:11], v[118:121], v[190:193], v[8:11]
	v_mfma_f32_16x16x32_bf16 v[52:55], v[130:133], v[162:165], v[52:55]
	v_mfma_f32_16x16x32_bf16 v[48:51], v[150:153], v[162:165], v[48:51]
	v_mfma_f32_16x16x32_bf16 v[36:39], v[130:133], v[170:173], v[36:39]
	v_mfma_f32_16x16x32_bf16 v[32:35], v[150:153], v[170:173], v[32:35]
	v_mfma_f32_16x16x32_bf16 v[20:23], v[130:133], v[178:181], v[20:23]
	v_mfma_f32_16x16x32_bf16 v[16:19], v[150:153], v[178:181], v[16:19]
	v_mfma_f32_16x16x32_bf16 v[4:7], v[130:133], v[186:189], v[4:7]
	v_mfma_f32_16x16x32_bf16 v[0:3], v[150:153], v[186:189], v[0:3]
	v_mfma_f32_16x16x32_bf16 v[52:55], v[142:145], v[166:169], v[52:55]
	v_mfma_f32_16x16x32_bf16 v[48:51], v[154:157], v[166:169], v[48:51]
	v_mfma_f32_16x16x32_bf16 v[36:39], v[142:145], v[174:177], v[36:39]
	v_mfma_f32_16x16x32_bf16 v[32:35], v[154:157], v[174:177], v[32:35]
	v_mfma_f32_16x16x32_bf16 v[20:23], v[142:145], v[182:185], v[20:23]
	v_mfma_f32_16x16x32_bf16 v[16:19], v[154:157], v[182:185], v[16:19]
	v_mfma_f32_16x16x32_bf16 v[4:7], v[142:145], v[190:193], v[4:7]
	v_mfma_f32_16x16x32_bf16 v[0:3], v[154:157], v[190:193], v[0:3]
	s_setprio 0
	s_barrier
	s_add_i32 s69, s69, 2
	s_add_u32 s0, s0, 0x100
	s_addc_u32 s1, s1, 0
	s_add_u32 s63, s63, 0x100
	s_addc_u32 s66, s66, 0
	s_cmp_gt_u32 s69, 13
	s_cbranch_scc0 .LBB0_1306
	s_and_b64 vcc, exec, s[16:17]
	s_cbranch_vccz .LBB0_1309
	s_barrier

.LBB0_1585:
	s_add_i32 s52, 0, 0x14000
	s_add_i32 s51, 0, 0x10000
	v_add_u32_e32 v212, s52, v136
	v_add_u32_e32 v213, s51, v136
	ds_read_b128 v[0:3], v212 offset:3072
	ds_read_b128 v[4:7], v212 offset:2048
	ds_read_b128 v[8:11], v212 offset:1024
	ds_read_b128 v[12:15], v212
	ds_read_b128 v[16:19], v213 offset:3072
	ds_read_b128 v[20:23], v213 offset:2048
	ds_read_b128 v[24:27], v213 offset:1024
	ds_read_b128 v[28:31], v213
	s_add_u32 s48, s16, 0x80080
	s_addc_u32 s49, s17, 0
	s_add_i32 s53, s26, 0xc000
	v_lshl_add_u64 v[66:67], s[48:49], 0, v[134:135]
	s_mov_b32 m0, s53
	s_add_i32 s11, s26, 0xe000
	ds_read_b128 v[32:35], v137
	ds_read_b128 v[36:39], v137 offset:1024
	ds_read_b128 v[40:43], v137 offset:2048
	ds_read_b128 v[44:47], v137 offset:3072
	ds_read_b128 v[48:51], v137 offset:4096
	ds_read_b128 v[52:55], v137 offset:5120
	ds_read_b128 v[56:59], v137 offset:6144
	ds_read_b128 v[60:63], v137 offset:7168
	global_load_lds_dwordx4 v[66:67], off
	v_lshl_add_u64 v[66:67], s[48:49], 0, v[132:133]
	s_mov_b32 m0, s11
	s_nop 0
	global_load_lds_dwordx4 v[66:67], off
	s_waitcnt vmcnt(8)
	s_waitcnt lgkmcnt(0)
	s_barrier
	s_setprio 1
	s_waitcnt lgkmcnt(0)
	v_mfma_f32_16x16x32_bf16 v[66:69], v[28:31], v[32:35], 0
	v_mfma_f32_16x16x32_bf16 v[70:73], v[20:23], v[32:35], 0
	v_mfma_f32_16x16x32_bf16 v[74:77], v[28:31], v[40:43], 0
	v_mfma_f32_16x16x32_bf16 v[78:81], v[20:23], v[40:43], 0
	v_mfma_f32_16x16x32_bf16 v[82:85], v[28:31], v[48:51], 0
	v_mfma_f32_16x16x32_bf16 v[86:89], v[20:23], v[48:51], 0
	v_mfma_f32_16x16x32_bf16 v[90:93], v[28:31], v[56:59], 0
	v_mfma_f32_16x16x32_bf16 v[94:97], v[20:23], v[56:59], 0
	v_mfma_f32_16x16x32_bf16 v[66:69], v[24:27], v[36:39], v[66:69]
	v_mfma_f32_16x16x32_bf16 v[70:73], v[16:19], v[36:39], v[70:73]
	v_mfma_f32_16x16x32_bf16 v[74:77], v[24:27], v[44:47], v[74:77]
	v_mfma_f32_16x16x32_bf16 v[78:81], v[16:19], v[44:47], v[78:81]
	v_mfma_f32_16x16x32_bf16 v[82:85], v[24:27], v[52:55], v[82:85]
	v_mfma_f32_16x16x32_bf16 v[86:89], v[16:19], v[52:55], v[86:89]
	v_mfma_f32_16x16x32_bf16 v[90:93], v[24:27], v[60:63], v[90:93]
	v_mfma_f32_16x16x32_bf16 v[94:97], v[16:19], v[60:63], v[94:97]
	v_mfma_f32_16x16x32_bf16 v[98:101], v[12:15], v[32:35], 0
	v_mfma_f32_16x16x32_bf16 v[32:35], v[4:7], v[32:35], 0
	v_mfma_f32_16x16x32_bf16 v[98:101], v[8:11], v[36:39], v[98:101]
	v_mfma_f32_16x16x32_bf16 v[32:35], v[0:3], v[36:39], v[32:35]
	v_mfma_f32_16x16x32_bf16 v[36:39], v[12:15], v[40:43], 0
	v_mfma_f32_16x16x32_bf16 v[40:43], v[4:7], v[40:43], 0
	v_mfma_f32_16x16x32_bf16 v[36:39], v[8:11], v[44:47], v[36:39]
	v_mfma_f32_16x16x32_bf16 v[40:43], v[0:3], v[44:47], v[40:43]
	v_mfma_f32_16x16x32_bf16 v[44:47], v[12:15], v[48:51], 0
	v_mfma_f32_16x16x32_bf16 v[48:51], v[4:7], v[48:51], 0
	v_mfma_f32_16x16x32_bf16 v[44:47], v[8:11], v[52:55], v[44:47]
	v_mfma_f32_16x16x32_bf16 v[48:51], v[0:3], v[52:55], v[48:51]
	v_mfma_f32_16x16x32_bf16 v[52:55], v[12:15], v[56:59], 0
	v_mfma_f32_16x16x32_bf16 v[56:59], v[4:7], v[56:59], 0
	v_mfma_f32_16x16x32_bf16 v[52:55], v[8:11], v[60:63], v[52:55]
	v_mfma_f32_16x16x32_bf16 v[56:59], v[0:3], v[60:63], v[56:59]
	s_setprio 0
	s_barrier
	s_add_i32 s51, s51, s25
	v_lshl_add_u64 v[194:195], s[18:19], 0, v[64:65]
	s_mov_b64 s[58:59], 0x100
	s_add_i32 s43, s51, 0x2000
	v_lshl_add_u64 v[138:139], v[194:195], 0, s[58:59]
	s_mov_b32 m0, s51
	v_lshl_add_u64 v[196:197], s[18:19], 0, v[130:131]
	s_add_u32 s54, s18, 0x80100
	ds_read_b128 v[60:63], v137 offset:16384
	ds_read_b128 v[102:105], v137 offset:17408
	ds_read_b128 v[106:109], v137 offset:18432
	ds_read_b128 v[110:113], v137 offset:19456
	ds_read_b128 v[114:117], v137 offset:20480
	ds_read_b128 v[118:121], v137 offset:21504
	ds_read_b128 v[122:125], v137 offset:22528
	ds_read_b128 v[126:129], v137 offset:23552
	global_load_lds_dwordx4 v[138:139], off
	v_lshl_add_u64 v[138:139], v[196:197], 0, s[58:59]
	s_mov_b32 m0, s43
	s_addc_u32 s55, s19, 0
	s_add_i32 s48, s52, s25
	global_load_lds_dwordx4 v[138:139], off
	v_lshl_add_u64 v[138:139], s[54:55], 0, v[64:65]
	s_mov_b32 m0, s48
	s_add_i32 s49, s48, 0x2000
	global_load_lds_dwordx4 v[138:139], off
	v_lshl_add_u64 v[138:139], s[54:55], 0, v[130:131]
	s_mov_b32 m0, s49
	v_lshl_add_u64 v[206:207], s[16:17], 0, v[134:135]
	global_load_lds_dwordx4 v[138:139], off
	v_lshl_add_u64 v[138:139], v[206:207], 0, s[58:59]
	s_mov_b32 m0, s26
	v_lshl_add_u64 v[208:209], s[16:17], 0, v[132:133]
	global_load_lds_dwordx4 v[138:139], off
	v_lshl_add_u64 v[138:139], v[208:209], 0, s[58:59]
	s_mov_b32 m0, s27
	s_nop 0
	global_load_lds_dwordx4 v[138:139], off
	s_waitcnt vmcnt(8)
	s_waitcnt lgkmcnt(0)
	s_barrier
	s_setprio 1
	s_waitcnt lgkmcnt(0)
	v_mfma_f32_16x16x32_bf16 v[138:141], v[28:31], v[60:63], 0
	v_mfma_f32_16x16x32_bf16 v[142:145], v[20:23], v[60:63], 0
	v_mfma_f32_16x16x32_bf16 v[146:149], v[28:31], v[106:109], 0
	v_mfma_f32_16x16x32_bf16 v[150:153], v[20:23], v[106:109], 0
	v_mfma_f32_16x16x32_bf16 v[154:157], v[28:31], v[114:117], 0
	v_mfma_f32_16x16x32_bf16 v[158:161], v[20:23], v[114:117], 0
	v_mfma_f32_16x16x32_bf16 v[28:31], v[28:31], v[122:125], 0
	v_mfma_f32_16x16x32_bf16 v[20:23], v[20:23], v[122:125], 0
	v_mfma_f32_16x16x32_bf16 v[138:141], v[24:27], v[102:105], v[138:141]
	v_mfma_f32_16x16x32_bf16 v[142:145], v[16:19], v[102:105], v[142:145]
	v_mfma_f32_16x16x32_bf16 v[146:149], v[24:27], v[110:113], v[146:149]
	v_mfma_f32_16x16x32_bf16 v[150:153], v[16:19], v[110:113], v[150:153]
	v_mfma_f32_16x16x32_bf16 v[154:157], v[24:27], v[118:121], v[154:157]
	v_mfma_f32_16x16x32_bf16 v[158:161], v[16:19], v[118:121], v[158:161]
	v_mfma_f32_16x16x32_bf16 v[24:27], v[24:27], v[126:129], v[28:31]
	v_mfma_f32_16x16x32_bf16 v[16:19], v[16:19], v[126:129], v[20:23]
	v_mfma_f32_16x16x32_bf16 v[20:23], v[12:15], v[60:63], 0
	v_mfma_f32_16x16x32_bf16 v[28:31], v[4:7], v[60:63], 0
	v_mfma_f32_16x16x32_bf16 v[20:23], v[8:11], v[102:105], v[20:23]
	v_mfma_f32_16x16x32_bf16 v[28:31], v[0:3], v[102:105], v[28:31]
	v_mfma_f32_16x16x32_bf16 v[60:63], v[12:15], v[106:109], 0
	v_mfma_f32_16x16x32_bf16 v[102:105], v[4:7], v[106:109], 0
	v_mfma_f32_16x16x32_bf16 v[60:63], v[8:11], v[110:113], v[60:63]
	v_mfma_f32_16x16x32_bf16 v[102:105], v[0:3], v[110:113], v[102:105]
	v_mfma_f32_16x16x32_bf16 v[106:109], v[12:15], v[114:117], 0
	v_mfma_f32_16x16x32_bf16 v[110:113], v[4:7], v[114:117], 0
	v_mfma_f32_16x16x32_bf16 v[12:15], v[12:15], v[122:125], 0
	v_mfma_f32_16x16x32_bf16 v[4:7], v[4:7], v[122:125], 0
	v_mfma_f32_16x16x32_bf16 v[106:109], v[8:11], v[118:121], v[106:109]
	v_mfma_f32_16x16x32_bf16 v[110:113], v[0:3], v[118:121], v[110:113]
	v_mfma_f32_16x16x32_bf16 v[8:11], v[8:11], v[126:129], v[12:15]
	v_mfma_f32_16x16x32_bf16 v[0:3], v[0:3], v[126:129], v[4:7]
	s_setprio 0
	s_barrier
	s_add_i32 s52, 0, 0x18000
	s_add_i32 s57, 0, 0x1c000
	v_add_u32_e32 v214, s52, v136
	v_add_u32_e32 v222, s57, v136
	ds_read_b128 v[4:7], v214
	ds_read_b128 v[12:15], v214 offset:1024
	ds_read_b128 v[114:117], v214 offset:2048
	ds_read_b128 v[118:121], v214 offset:3072
	ds_read_b128 v[122:125], v222
	ds_read_b128 v[126:129], v222 offset:1024
	ds_read_b128 v[162:165], v222 offset:2048
	ds_read_b128 v[166:169], v222 offset:3072
	s_add_u32 s54, s16, 0x80100
	s_addc_u32 s55, s17, 0
	s_mov_b32 m0, s28
	v_lshl_add_u64 v[210:211], s[54:55], 0, v[134:135]
	ds_read_b128 v[170:173], v137 offset:32768
	ds_read_b128 v[174:177], v137 offset:33792
	ds_read_b128 v[178:181], v137 offset:34816
	ds_read_b128 v[182:185], v137 offset:35840
	ds_read_b128 v[186:189], v137 offset:36864
	ds_read_b128 v[190:193], v137 offset:37888
	ds_read_b128 v[198:201], v137 offset:38912
	ds_read_b128 v[202:205], v137 offset:39936
	global_load_lds_dwordx4 v[210:211], off
	v_lshl_add_u64 v[210:211], s[54:55], 0, v[132:133]
	s_mov_b32 m0, s29
	s_nop 0
	global_load_lds_dwordx4 v[210:211], off
	s_waitcnt vmcnt(8)
	s_waitcnt lgkmcnt(0)
	s_barrier
	s_setprio 1
	s_waitcnt lgkmcnt(0)
	v_mfma_f32_16x16x32_bf16 v[66:69], v[4:7], v[170:173], v[66:69]
	v_mfma_f32_16x16x32_bf16 v[70:73], v[114:117], v[170:173], v[70:73]
	v_mfma_f32_16x16x32_bf16 v[74:77], v[4:7], v[178:181], v[74:77]
	v_mfma_f32_16x16x32_bf16 v[78:81], v[114:117], v[178:181], v[78:81]
	v_mfma_f32_16x16x32_bf16 v[82:85], v[4:7], v[186:189], v[82:85]
	v_mfma_f32_16x16x32_bf16 v[86:89], v[114:117], v[186:189], v[86:89]
	v_mfma_f32_16x16x32_bf16 v[90:93], v[4:7], v[198:201], v[90:93]
	v_mfma_f32_16x16x32_bf16 v[94:97], v[114:117], v[198:201], v[94:97]
	v_mfma_f32_16x16x32_bf16 v[66:69], v[12:15], v[174:177], v[66:69]
	v_mfma_f32_16x16x32_bf16 v[70:73], v[118:121], v[174:177], v[70:73]
	v_mfma_f32_16x16x32_bf16 v[74:77], v[12:15], v[182:185], v[74:77]
	v_mfma_f32_16x16x32_bf16 v[78:81], v[118:121], v[182:185], v[78:81]
	v_mfma_f32_16x16x32_bf16 v[82:85], v[12:15], v[190:193], v[82:85]
	v_mfma_f32_16x16x32_bf16 v[86:89], v[118:121], v[190:193], v[86:89]
	v_mfma_f32_16x16x32_bf16 v[90:93], v[12:15], v[202:205], v[90:93]
	v_mfma_f32_16x16x32_bf16 v[94:97], v[118:121], v[202:205], v[94:97]
	v_mfma_f32_16x16x32_bf16 v[98:101], v[122:125], v[170:173], v[98:101]
	v_mfma_f32_16x16x32_bf16 v[32:35], v[162:165], v[170:173], v[32:35]
	v_mfma_f32_16x16x32_bf16 v[36:39], v[122:125], v[178:181], v[36:39]
	v_mfma_f32_16x16x32_bf16 v[40:43], v[162:165], v[178:181], v[40:43]
	v_mfma_f32_16x16x32_bf16 v[44:47], v[122:125], v[186:189], v[44:47]
	v_mfma_f32_16x16x32_bf16 v[48:51], v[162:165], v[186:189], v[48:51]
	v_mfma_f32_16x16x32_bf16 v[52:55], v[122:125], v[198:201], v[52:55]
	v_mfma_f32_16x16x32_bf16 v[56:59], v[162:165], v[198:201], v[56:59]
	v_mfma_f32_16x16x32_bf16 v[98:101], v[126:129], v[174:177], v[98:101]
	v_mfma_f32_16x16x32_bf16 v[32:35], v[166:169], v[174:177], v[32:35]
	v_mfma_f32_16x16x32_bf16 v[36:39], v[126:129], v[182:185], v[36:39]
	v_mfma_f32_16x16x32_bf16 v[40:43], v[166:169], v[182:185], v[40:43]
	v_mfma_f32_16x16x32_bf16 v[44:47], v[126:129], v[190:193], v[44:47]
	v_mfma_f32_16x16x32_bf16 v[48:51], v[166:169], v[190:193], v[48:51]
	v_mfma_f32_16x16x32_bf16 v[52:55], v[126:129], v[202:205], v[52:55]
	v_mfma_f32_16x16x32_bf16 v[56:59], v[166:169], v[202:205], v[56:59]
	s_setprio 0
	s_barrier
	s_add_i32 s54, s52, s25
	s_mov_b64 s[70:71], 0x180
	s_add_i32 s52, s54, 0x2000
	v_lshl_add_u64 v[194:195], v[194:195], 0, s[70:71]
	s_mov_b32 m0, s54
	s_add_u32 s58, s18, 0x80180
	ds_read_b128 v[170:173], v137 offset:49152
	ds_read_b128 v[174:177], v137 offset:50176
	ds_read_b128 v[178:181], v137 offset:51200
	ds_read_b128 v[182:185], v137 offset:52224
	ds_read_b128 v[186:189], v137 offset:53248
	ds_read_b128 v[190:193], v137 offset:54272
	ds_read_b128 v[198:201], v137 offset:55296
	ds_read_b128 v[202:205], v137 offset:56320
	global_load_lds_dwordx4 v[194:195], off
	v_lshl_add_u64 v[194:195], v[196:197], 0, s[70:71]
	s_mov_b32 m0, s52
	s_addc_u32 s59, s19, 0
	s_add_i32 s18, s57, s25
	global_load_lds_dwordx4 v[194:195], off
	v_lshl_add_u64 v[194:195], s[58:59], 0, v[64:65]
	s_mov_b32 m0, s18
	s_add_i32 s19, s18, 0x2000
	global_load_lds_dwordx4 v[194:195], off
	v_lshl_add_u64 v[194:195], s[58:59], 0, v[130:131]
	s_mov_b32 m0, s19
	s_nop 0
	global_load_lds_dwordx4 v[194:195], off
	v_lshl_add_u64 v[194:195], v[206:207], 0, s[70:71]
	s_mov_b32 m0, s35
	s_nop 0
	global_load_lds_dwordx4 v[194:195], off
	v_lshl_add_u64 v[194:195], v[208:209], 0, s[70:71]
	s_mov_b32 m0, s36
	s_nop 0
	global_load_lds_dwordx4 v[194:195], off
	s_waitcnt vmcnt(8)
	s_waitcnt lgkmcnt(0)
	s_barrier
	s_setprio 1
	s_waitcnt lgkmcnt(0)
	v_mfma_f32_16x16x32_bf16 v[138:141], v[4:7], v[170:173], v[138:141]
	v_mfma_f32_16x16x32_bf16 v[146:149], v[4:7], v[178:181], v[146:149]
	v_mfma_f32_16x16x32_bf16 v[154:157], v[4:7], v[186:189], v[154:157]
	v_mfma_f32_16x16x32_bf16 v[4:7], v[4:7], v[198:201], v[24:27]
	v_mfma_f32_16x16x32_bf16 v[138:141], v[12:15], v[174:177], v[138:141]
	v_mfma_f32_16x16x32_bf16 v[146:149], v[12:15], v[182:185], v[146:149]
	v_mfma_f32_16x16x32_bf16 v[154:157], v[12:15], v[190:193], v[154:157]
	v_mfma_f32_16x16x32_bf16 v[4:7], v[12:15], v[202:205], v[4:7]
	v_mfma_f32_16x16x32_bf16 v[12:15], v[114:117], v[198:201], v[16:19]
	v_mfma_f32_16x16x32_bf16 v[142:145], v[114:117], v[170:173], v[142:145]
	v_mfma_f32_16x16x32_bf16 v[150:153], v[114:117], v[178:181], v[150:153]
	v_mfma_f32_16x16x32_bf16 v[158:161], v[114:117], v[186:189], v[158:161]
	v_mfma_f32_16x16x32_bf16 v[12:15], v[118:121], v[202:205], v[12:15]
	v_mfma_f32_16x16x32_bf16 v[142:145], v[118:121], v[174:177], v[142:145]
	v_mfma_f32_16x16x32_bf16 v[150:153], v[118:121], v[182:185], v[150:153]
	v_mfma_f32_16x16x32_bf16 v[158:161], v[118:121], v[190:193], v[158:161]
	v_mfma_f32_16x16x32_bf16 v[16:19], v[122:125], v[170:173], v[20:23]
	v_mfma_f32_16x16x32_bf16 v[20:23], v[162:165], v[170:173], v[28:31]
	v_mfma_f32_16x16x32_bf16 v[24:27], v[122:125], v[178:181], v[60:63]
	v_mfma_f32_16x16x32_bf16 v[28:31], v[162:165], v[178:181], v[102:105]
	v_mfma_f32_16x16x32_bf16 v[60:63], v[122:125], v[186:189], v[106:109]
	v_mfma_f32_16x16x32_bf16 v[102:105], v[162:165], v[186:189], v[110:113]
	v_mfma_f32_16x16x32_bf16 v[8:11], v[122:125], v[198:201], v[8:11]
	v_mfma_f32_16x16x32_bf16 v[0:3], v[162:165], v[198:201], v[0:3]
	v_mfma_f32_16x16x32_bf16 v[16:19], v[126:129], v[174:177], v[16:19]
	v_mfma_f32_16x16x32_bf16 v[20:23], v[166:169], v[174:177], v[20:23]
	v_mfma_f32_16x16x32_bf16 v[24:27], v[126:129], v[182:185], v[24:27]
	v_mfma_f32_16x16x32_bf16 v[28:31], v[166:169], v[182:185], v[28:31]
	v_mfma_f32_16x16x32_bf16 v[60:63], v[126:129], v[190:193], v[60:63]
	v_mfma_f32_16x16x32_bf16 v[102:105], v[166:169], v[190:193], v[102:105]
	v_mfma_f32_16x16x32_bf16 v[8:11], v[126:129], v[202:205], v[8:11]
	v_mfma_f32_16x16x32_bf16 v[0:3], v[166:169], v[202:205], v[0:3]
	s_setprio 0
	s_barrier
	ds_read_b128 v[106:109], v213
	ds_read_b128 v[110:113], v213 offset:1024
	ds_read_b128 v[114:117], v213 offset:2048
	ds_read_b128 v[118:121], v213 offset:3072
	ds_read_b128 v[122:125], v212
	ds_read_b128 v[126:129], v212 offset:1024
	ds_read_b128 v[162:165], v212 offset:2048
	ds_read_b128 v[166:169], v212 offset:3072
	s_add_u32 s16, s16, 0x80180
	s_addc_u32 s17, s17, 0
	s_mov_b32 m0, s53
	v_lshl_add_u64 v[194:195], s[16:17], 0, v[134:135]
	ds_read_b128 v[170:173], v137
	ds_read_b128 v[174:177], v137 offset:1024
	ds_read_b128 v[178:181], v137 offset:2048
	ds_read_b128 v[182:185], v137 offset:3072
	ds_read_b128 v[186:189], v137 offset:4096
	ds_read_b128 v[190:193], v137 offset:5120
	ds_read_b128 v[198:201], v137 offset:6144
	ds_read_b128 v[202:205], v137 offset:7168
	global_load_lds_dwordx4 v[194:195], off
	v_lshl_add_u64 v[194:195], s[16:17], 0, v[132:133]
	s_mov_b32 m0, s11
	s_nop 0
	global_load_lds_dwordx4 v[194:195], off
	s_waitcnt vmcnt(8)
	s_waitcnt lgkmcnt(0)
	s_barrier
	s_setprio 1
	s_waitcnt lgkmcnt(0)
	v_mfma_f32_16x16x32_bf16 v[66:69], v[106:109], v[170:173], v[66:69]
	v_mfma_f32_16x16x32_bf16 v[70:73], v[114:117], v[170:173], v[70:73]
	v_mfma_f32_16x16x32_bf16 v[74:77], v[106:109], v[178:181], v[74:77]
	v_mfma_f32_16x16x32_bf16 v[78:81], v[114:117], v[178:181], v[78:81]
	v_mfma_f32_16x16x32_bf16 v[82:85], v[106:109], v[186:189], v[82:85]
	v_mfma_f32_16x16x32_bf16 v[86:89], v[114:117], v[186:189], v[86:89]
	v_mfma_f32_16x16x32_bf16 v[90:93], v[106:109], v[198:201], v[90:93]
	v_mfma_f32_16x16x32_bf16 v[94:97], v[114:117], v[198:201], v[94:97]
	v_mfma_f32_16x16x32_bf16 v[66:69], v[110:113], v[174:177], v[66:69]
	v_mfma_f32_16x16x32_bf16 v[70:73], v[118:121], v[174:177], v[70:73]
	v_mfma_f32_16x16x32_bf16 v[74:77], v[110:113], v[182:185], v[74:77]
	v_mfma_f32_16x16x32_bf16 v[78:81], v[118:121], v[182:185], v[78:81]
	v_mfma_f32_16x16x32_bf16 v[82:85], v[110:113], v[190:193], v[82:85]
	v_mfma_f32_16x16x32_bf16 v[86:89], v[118:121], v[190:193], v[86:89]
	v_mfma_f32_16x16x32_bf16 v[90:93], v[110:113], v[202:205], v[90:93]
	v_mfma_f32_16x16x32_bf16 v[94:97], v[118:121], v[202:205], v[94:97]
	v_mfma_f32_16x16x32_bf16 v[40:43], v[162:165], v[178:181], v[40:43]
	v_mfma_f32_16x16x32_bf16 v[98:101], v[122:125], v[170:173], v[98:101]
	v_mfma_f32_16x16x32_bf16 v[32:35], v[162:165], v[170:173], v[32:35]
	v_mfma_f32_16x16x32_bf16 v[170:173], v[166:169], v[182:185], v[40:43]
	v_mfma_f32_16x16x32_bf16 v[40:43], v[122:125], v[186:189], v[44:47]
	v_mfma_f32_16x16x32_bf16 v[98:101], v[126:129], v[174:177], v[98:101]
	v_mfma_f32_16x16x32_bf16 v[32:35], v[166:169], v[174:177], v[32:35]
	v_mfma_f32_16x16x32_bf16 v[174:177], v[126:129], v[190:193], v[40:43]
	v_mfma_f32_16x16x32_bf16 v[40:43], v[162:165], v[186:189], v[48:51]
	v_mfma_f32_16x16x32_bf16 v[36:39], v[122:125], v[178:181], v[36:39]
	v_mfma_f32_16x16x32_bf16 v[48:51], v[166:169], v[190:193], v[40:43]
	v_mfma_f32_16x16x32_bf16 v[40:43], v[122:125], v[198:201], v[52:55]
	v_mfma_f32_16x16x32_bf16 v[36:39], v[126:129], v[182:185], v[36:39]
	v_mfma_f32_16x16x32_bf16 v[52:55], v[126:129], v[202:205], v[40:43]
	v_mfma_f32_16x16x32_bf16 v[40:43], v[162:165], v[198:201], v[56:59]
	v_mfma_f32_16x16x32_bf16 v[178:181], v[166:169], v[202:205], v[40:43]
	s_setprio 0
	s_barrier
	s_mov_b32 m0, s51
	v_lshl_add_u64 v[194:195], s[14:15], 0, v[64:65]
	s_add_u32 s16, s14, 0x80000
	s_nop 1
	ds_read_b128 v[40:43], v137 offset:16384
	ds_read_b128 v[44:47], v137 offset:17408
	ds_read_b128 v[56:59], v137 offset:18432
	ds_read_b128 v[182:185], v137 offset:19456
	ds_read_b128 v[186:189], v137 offset:20480
	ds_read_b128 v[190:193], v137 offset:21504
	ds_read_b128 v[198:201], v137 offset:22528
	ds_read_b128 v[202:205], v137 offset:23552
	global_load_lds_dwordx4 v[194:195], off
	v_lshl_add_u64 v[196:197], s[14:15], 0, v[130:131]
	s_mov_b32 m0, s43
	s_addc_u32 s17, s15, 0
	global_load_lds_dwordx4 v[196:197], off
	v_lshl_add_u64 v[206:207], s[16:17], 0, v[64:65]
	s_mov_b32 m0, s48
	v_lshl_add_u64 v[238:239], s[12:13], 0, v[134:135]
	global_load_lds_dwordx4 v[206:207], off
	v_lshl_add_u64 v[206:207], s[16:17], 0, v[130:131]
	s_mov_b32 m0, s49
	v_lshl_add_u64 v[240:241], s[12:13], 0, v[132:133]
	global_load_lds_dwordx4 v[206:207], off
	s_mov_b32 m0, s26
	s_nop 0
	global_load_lds_dwordx4 v[238:239], off
	s_mov_b32 m0, s27
	s_nop 0
	global_load_lds_dwordx4 v[240:241], off
	s_waitcnt vmcnt(8)
	s_waitcnt lgkmcnt(0)
	s_barrier
	s_setprio 1
	s_waitcnt lgkmcnt(0)
	v_mfma_f32_16x16x32_bf16 v[4:7], v[106:109], v[198:201], v[4:7]
	v_mfma_f32_16x16x32_bf16 v[12:15], v[114:117], v[198:201], v[12:15]
	v_mfma_f32_16x16x32_bf16 v[138:141], v[106:109], v[40:43], v[138:141]
	v_mfma_f32_16x16x32_bf16 v[142:145], v[114:117], v[40:43], v[142:145]
	v_mfma_f32_16x16x32_bf16 v[146:149], v[106:109], v[56:59], v[146:149]
	v_mfma_f32_16x16x32_bf16 v[150:153], v[114:117], v[56:59], v[150:153]
	v_mfma_f32_16x16x32_bf16 v[154:157], v[106:109], v[186:189], v[154:157]
	v_mfma_f32_16x16x32_bf16 v[158:161], v[114:117], v[186:189], v[158:161]
	v_mfma_f32_16x16x32_bf16 v[4:7], v[110:113], v[202:205], v[4:7]
	v_mfma_f32_16x16x32_bf16 v[114:117], v[118:121], v[202:205], v[12:15]
	v_mfma_f32_16x16x32_bf16 v[138:141], v[110:113], v[44:47], v[138:141]
	v_mfma_f32_16x16x32_bf16 v[142:145], v[118:121], v[44:47], v[142:145]
	v_mfma_f32_16x16x32_bf16 v[146:149], v[110:113], v[182:185], v[146:149]
	v_mfma_f32_16x16x32_bf16 v[150:153], v[118:121], v[182:185], v[150:153]
	v_mfma_f32_16x16x32_bf16 v[154:157], v[110:113], v[190:193], v[154:157]
	v_mfma_f32_16x16x32_bf16 v[158:161], v[118:121], v[190:193], v[158:161]
	v_mfma_f32_16x16x32_bf16 v[12:15], v[122:125], v[40:43], v[16:19]
	v_mfma_f32_16x16x32_bf16 v[16:19], v[126:129], v[44:47], v[12:15]
	v_mfma_f32_16x16x32_bf16 v[12:15], v[162:165], v[40:43], v[20:23]
	v_mfma_f32_16x16x32_bf16 v[20:23], v[166:169], v[44:47], v[12:15]
	v_mfma_f32_16x16x32_bf16 v[12:15], v[122:125], v[56:59], v[24:27]
	v_mfma_f32_16x16x32_bf16 v[206:209], v[126:129], v[182:185], v[12:15]
	v_mfma_f32_16x16x32_bf16 v[12:15], v[162:165], v[56:59], v[28:31]
	v_mfma_f32_16x16x32_bf16 v[182:185], v[166:169], v[182:185], v[12:15]
	v_mfma_f32_16x16x32_bf16 v[12:15], v[122:125], v[186:189], v[60:63]
	v_mfma_f32_16x16x32_bf16 v[210:213], v[126:129], v[190:193], v[12:15]
	v_mfma_f32_16x16x32_bf16 v[12:15], v[162:165], v[186:189], v[102:105]
	v_mfma_f32_16x16x32_bf16 v[8:11], v[122:125], v[198:201], v[8:11]
	v_mfma_f32_16x16x32_bf16 v[0:3], v[162:165], v[198:201], v[0:3]
	v_mfma_f32_16x16x32_bf16 v[186:189], v[166:169], v[190:193], v[12:15]
	v_mfma_f32_16x16x32_bf16 v[190:193], v[126:129], v[202:205], v[8:11]
	v_mfma_f32_16x16x32_bf16 v[162:165], v[166:169], v[202:205], v[0:3]
	s_setprio 0
	s_barrier
	s_nop 2
	ds_read_b128 v[0:3], v214
	ds_read_b128 v[118:121], v214 offset:1024
	ds_read_b128 v[166:169], v214 offset:2048
	ds_read_b128 v[198:201], v214 offset:3072
	ds_read_b128 v[202:205], v222
	ds_read_b128 v[214:217], v222 offset:1024
	ds_read_b128 v[218:221], v222 offset:2048
	ds_read_b128 v[222:225], v222 offset:3072
	s_add_u32 s16, s12, 0x80000
	s_addc_u32 s17, s13, 0
	s_mov_b32 m0, s28
	v_lshl_add_u64 v[8:9], s[16:17], 0, v[134:135]
	ds_read_b128 v[24:27], v137 offset:32768
	ds_read_b128 v[28:31], v137 offset:33792
	ds_read_b128 v[56:59], v137 offset:34816
	ds_read_b128 v[60:63], v137 offset:35840
	ds_read_b128 v[102:105], v137 offset:36864
	ds_read_b128 v[242:245], v137 offset:37888
	ds_read_b128 v[246:249], v137 offset:38912
	ds_read_b128 v[228:231], v137 offset:39936
	global_load_lds_dwordx4 v[8:9], off
	v_lshl_add_u64 v[8:9], s[16:17], 0, v[132:133]
	s_mov_b32 m0, s29
	s_nop 0
	global_load_lds_dwordx4 v[8:9], off
	s_waitcnt vmcnt(8)
	s_waitcnt lgkmcnt(0)
	s_barrier
	s_setprio 1
	s_waitcnt lgkmcnt(0)
	v_mfma_f32_16x16x32_bf16 v[8:11], v[0:3], v[24:27], v[66:69]
	v_mfma_f32_16x16x32_bf16 v[106:109], v[118:121], v[28:31], v[8:11]
	v_mfma_f32_16x16x32_bf16 v[8:11], v[166:169], v[24:27], v[70:73]
	v_mfma_f32_16x16x32_bf16 v[110:113], v[198:201], v[28:31], v[8:11]
	v_mfma_f32_16x16x32_bf16 v[8:11], v[0:3], v[56:59], v[74:77]
	v_mfma_f32_16x16x32_bf16 v[74:77], v[118:121], v[60:63], v[8:11]
	v_mfma_f32_16x16x32_bf16 v[8:11], v[166:169], v[56:59], v[78:81]
	v_mfma_f32_16x16x32_bf16 v[78:81], v[198:201], v[60:63], v[8:11]
	v_mfma_f32_16x16x32_bf16 v[8:11], v[0:3], v[102:105], v[82:85]
	v_mfma_f32_16x16x32_bf16 v[40:43], v[118:121], v[242:245], v[8:11]
	v_mfma_f32_16x16x32_bf16 v[8:11], v[166:169], v[102:105], v[86:89]
	v_mfma_f32_16x16x32_bf16 v[44:47], v[198:201], v[242:245], v[8:11]
	v_mfma_f32_16x16x32_bf16 v[8:11], v[0:3], v[246:249], v[90:93]
	v_mfma_f32_16x16x32_bf16 v[12:15], v[166:169], v[246:249], v[94:97]
	v_mfma_f32_16x16x32_bf16 v[8:11], v[118:121], v[228:231], v[8:11]
	v_mfma_f32_16x16x32_bf16 v[12:15], v[198:201], v[228:231], v[12:15]
	v_mfma_f32_16x16x32_bf16 v[66:69], v[202:205], v[24:27], v[98:101]
	v_mfma_f32_16x16x32_bf16 v[24:27], v[218:221], v[24:27], v[32:35]
	v_mfma_f32_16x16x32_bf16 v[126:129], v[222:225], v[28:31], v[24:27]
	v_mfma_f32_16x16x32_bf16 v[24:27], v[202:205], v[56:59], v[36:39]
	v_mfma_f32_16x16x32_bf16 v[90:93], v[214:217], v[60:63], v[24:27]
	v_mfma_f32_16x16x32_bf16 v[24:27], v[218:221], v[56:59], v[170:173]
	v_mfma_f32_16x16x32_bf16 v[94:97], v[222:225], v[60:63], v[24:27]
	v_mfma_f32_16x16x32_bf16 v[24:27], v[202:205], v[102:105], v[174:177]
	v_mfma_f32_16x16x32_bf16 v[56:59], v[214:217], v[242:245], v[24:27]
	v_mfma_f32_16x16x32_bf16 v[24:27], v[218:221], v[102:105], v[48:51]
	v_mfma_f32_16x16x32_bf16 v[122:125], v[214:217], v[28:31], v[66:69]
	v_mfma_f32_16x16x32_bf16 v[60:63], v[222:225], v[242:245], v[24:27]
	v_mfma_f32_16x16x32_bf16 v[24:27], v[202:205], v[246:249], v[52:55]
	v_mfma_f32_16x16x32_bf16 v[28:31], v[218:221], v[246:249], v[178:181]
	v_mfma_f32_16x16x32_bf16 v[24:27], v[214:217], v[228:231], v[24:27]
	v_mfma_f32_16x16x32_bf16 v[28:31], v[222:225], v[228:231], v[28:31]
	s_setprio 0
	s_barrier
	s_mov_b32 m0, s54
	v_lshl_add_u64 v[32:33], v[194:195], 0, s[96:97]
	s_add_u32 s16, s14, 0x80080
	ds_read_b128 v[48:51], v137 offset:49152
	ds_read_b128 v[52:55], v137 offset:50176
	ds_read_b128 v[86:89], v137 offset:51200
	ds_read_b128 v[170:173], v137 offset:52224
	ds_read_b128 v[174:177], v137 offset:53248
	ds_read_b128 v[178:181], v137 offset:54272
	ds_read_b128 v[228:231], v137 offset:55296
	ds_read_b128 v[242:245], v137 offset:56320
	global_load_lds_dwordx4 v[32:33], off
	v_lshl_add_u64 v[32:33], v[196:197], 0, s[96:97]
	s_mov_b32 m0, s52
	s_addc_u32 s17, s15, 0
	global_load_lds_dwordx4 v[32:33], off
	v_lshl_add_u64 v[32:33], s[16:17], 0, v[64:65]
	s_mov_b32 m0, s18
	s_nop 0
	global_load_lds_dwordx4 v[32:33], off
	v_lshl_add_u64 v[32:33], s[16:17], 0, v[130:131]
	s_mov_b32 m0, s19
	s_nop 0
	global_load_lds_dwordx4 v[32:33], off
	v_lshl_add_u64 v[32:33], v[238:239], 0, s[96:97]
	s_mov_b32 m0, s35
	s_nop 0
	global_load_lds_dwordx4 v[32:33], off
	v_lshl_add_u64 v[32:33], v[240:241], 0, s[96:97]
	s_mov_b32 m0, s36
	s_nop 0
	global_load_lds_dwordx4 v[32:33], off
	s_waitcnt vmcnt(8)
	s_waitcnt lgkmcnt(0)
	s_barrier
	s_setprio 1
	s_waitcnt lgkmcnt(0)
	v_mfma_f32_16x16x32_bf16 v[32:35], v[0:3], v[48:51], v[138:141]
	v_mfma_f32_16x16x32_bf16 v[98:101], v[118:121], v[52:55], v[32:35]
	v_mfma_f32_16x16x32_bf16 v[32:35], v[166:169], v[48:51], v[142:145]
	v_mfma_f32_16x16x32_bf16 v[102:105], v[198:201], v[52:55], v[32:35]
	v_mfma_f32_16x16x32_bf16 v[32:35], v[0:3], v[86:89], v[146:149]
	v_mfma_f32_16x16x32_bf16 v[66:69], v[118:121], v[170:173], v[32:35]
	v_mfma_f32_16x16x32_bf16 v[32:35], v[166:169], v[86:89], v[150:153]
	v_mfma_f32_16x16x32_bf16 v[70:73], v[198:201], v[170:173], v[32:35]
	v_mfma_f32_16x16x32_bf16 v[32:35], v[0:3], v[174:177], v[154:157]
	v_mfma_f32_16x16x32_bf16 v[36:39], v[166:169], v[174:177], v[158:161]
	v_mfma_f32_16x16x32_bf16 v[0:3], v[0:3], v[228:231], v[4:7]
	v_mfma_f32_16x16x32_bf16 v[4:7], v[166:169], v[228:231], v[114:117]
	v_mfma_f32_16x16x32_bf16 v[32:35], v[118:121], v[178:181], v[32:35]
	v_mfma_f32_16x16x32_bf16 v[36:39], v[198:201], v[178:181], v[36:39]
	v_mfma_f32_16x16x32_bf16 v[0:3], v[118:121], v[242:245], v[0:3]
	v_mfma_f32_16x16x32_bf16 v[4:7], v[198:201], v[242:245], v[4:7]
	v_mfma_f32_16x16x32_bf16 v[16:19], v[202:205], v[48:51], v[16:19]
	v_mfma_f32_16x16x32_bf16 v[114:117], v[214:217], v[52:55], v[16:19]
	v_mfma_f32_16x16x32_bf16 v[16:19], v[218:221], v[48:51], v[20:23]
	v_mfma_f32_16x16x32_bf16 v[118:121], v[222:225], v[52:55], v[16:19]
	v_mfma_f32_16x16x32_bf16 v[16:19], v[202:205], v[86:89], v[206:209]
	v_mfma_f32_16x16x32_bf16 v[82:85], v[214:217], v[170:173], v[16:19]
	v_mfma_f32_16x16x32_bf16 v[16:19], v[218:221], v[86:89], v[182:185]
	v_mfma_f32_16x16x32_bf16 v[86:89], v[222:225], v[170:173], v[16:19]
	v_mfma_f32_16x16x32_bf16 v[16:19], v[202:205], v[174:177], v[210:213]
	v_mfma_f32_16x16x32_bf16 v[48:51], v[214:217], v[178:181], v[16:19]
	v_mfma_f32_16x16x32_bf16 v[16:19], v[218:221], v[174:177], v[186:189]
	v_mfma_f32_16x16x32_bf16 v[52:55], v[222:225], v[178:181], v[16:19]
	v_mfma_f32_16x16x32_bf16 v[16:19], v[202:205], v[228:231], v[190:193]
	v_mfma_f32_16x16x32_bf16 v[20:23], v[218:221], v[228:231], v[162:165]
	v_mfma_f32_16x16x32_bf16 v[16:19], v[214:217], v[242:245], v[16:19]
	v_mfma_f32_16x16x32_bf16 v[20:23], v[222:225], v[242:245], v[20:23]
	s_setprio 0
	s_barrier
	s_andn2_b64 vcc, exec, s[8:9]
	s_cbranch_vccnz .LBB0_1587
	s_barrier

.LBB0_1606:
	s_add_i32 s43, 0, 0x14000
	s_add_i32 s41, 0, 0x10000
	v_add_u32_e32 v212, s43, v136
	v_add_u32_e32 v213, s41, v136
	ds_read_b128 v[0:3], v212 offset:3072
	ds_read_b128 v[4:7], v212 offset:2048
	ds_read_b128 v[8:11], v212 offset:1024
	ds_read_b128 v[12:15], v212
	ds_read_b128 v[16:19], v213 offset:3072
	ds_read_b128 v[20:23], v213 offset:2048
	ds_read_b128 v[24:27], v213 offset:1024
	ds_read_b128 v[28:31], v213
	s_add_u32 s48, s16, 0x40080
	s_addc_u32 s49, s17, 0
	s_add_i32 s52, s26, 0xc000
	v_lshl_add_u64 v[66:67], s[48:49], 0, v[134:135]
	s_mov_b32 m0, s52
	s_add_i32 s11, s26, 0xe000
	ds_read_b128 v[32:35], v137
	ds_read_b128 v[36:39], v137 offset:1024
	ds_read_b128 v[40:43], v137 offset:2048
	ds_read_b128 v[44:47], v137 offset:3072
	ds_read_b128 v[48:51], v137 offset:4096
	ds_read_b128 v[52:55], v137 offset:5120
	ds_read_b128 v[56:59], v137 offset:6144
	ds_read_b128 v[60:63], v137 offset:7168
	global_load_lds_dwordx4 v[66:67], off
	v_lshl_add_u64 v[66:67], s[48:49], 0, v[132:133]
	s_mov_b32 m0, s11
	s_nop 0
	global_load_lds_dwordx4 v[66:67], off
	s_waitcnt vmcnt(8)
	s_waitcnt lgkmcnt(0)
	s_barrier
	s_setprio 1
	s_waitcnt lgkmcnt(0)
	v_mfma_f32_16x16x32_bf16 v[66:69], v[28:31], v[32:35], 0
	v_mfma_f32_16x16x32_bf16 v[70:73], v[20:23], v[32:35], 0
	v_mfma_f32_16x16x32_bf16 v[74:77], v[28:31], v[40:43], 0
	v_mfma_f32_16x16x32_bf16 v[78:81], v[20:23], v[40:43], 0
	v_mfma_f32_16x16x32_bf16 v[82:85], v[28:31], v[48:51], 0
	v_mfma_f32_16x16x32_bf16 v[86:89], v[20:23], v[48:51], 0
	v_mfma_f32_16x16x32_bf16 v[90:93], v[28:31], v[56:59], 0
	v_mfma_f32_16x16x32_bf16 v[94:97], v[20:23], v[56:59], 0
	v_mfma_f32_16x16x32_bf16 v[66:69], v[24:27], v[36:39], v[66:69]
	v_mfma_f32_16x16x32_bf16 v[70:73], v[16:19], v[36:39], v[70:73]
	v_mfma_f32_16x16x32_bf16 v[74:77], v[24:27], v[44:47], v[74:77]
	v_mfma_f32_16x16x32_bf16 v[78:81], v[16:19], v[44:47], v[78:81]
	v_mfma_f32_16x16x32_bf16 v[82:85], v[24:27], v[52:55], v[82:85]
	v_mfma_f32_16x16x32_bf16 v[86:89], v[16:19], v[52:55], v[86:89]
	v_mfma_f32_16x16x32_bf16 v[90:93], v[24:27], v[60:63], v[90:93]
	v_mfma_f32_16x16x32_bf16 v[94:97], v[16:19], v[60:63], v[94:97]
	v_mfma_f32_16x16x32_bf16 v[98:101], v[12:15], v[32:35], 0
	v_mfma_f32_16x16x32_bf16 v[32:35], v[4:7], v[32:35], 0
	v_mfma_f32_16x16x32_bf16 v[98:101], v[8:11], v[36:39], v[98:101]
	v_mfma_f32_16x16x32_bf16 v[32:35], v[0:3], v[36:39], v[32:35]
	v_mfma_f32_16x16x32_bf16 v[36:39], v[12:15], v[40:43], 0
	v_mfma_f32_16x16x32_bf16 v[40:43], v[4:7], v[40:43], 0
	v_mfma_f32_16x16x32_bf16 v[36:39], v[8:11], v[44:47], v[36:39]
	v_mfma_f32_16x16x32_bf16 v[40:43], v[0:3], v[44:47], v[40:43]
	v_mfma_f32_16x16x32_bf16 v[44:47], v[12:15], v[48:51], 0
	v_mfma_f32_16x16x32_bf16 v[48:51], v[4:7], v[48:51], 0
	v_mfma_f32_16x16x32_bf16 v[44:47], v[8:11], v[52:55], v[44:47]
	v_mfma_f32_16x16x32_bf16 v[48:51], v[0:3], v[52:55], v[48:51]
	v_mfma_f32_16x16x32_bf16 v[52:55], v[12:15], v[56:59], 0
	v_mfma_f32_16x16x32_bf16 v[56:59], v[4:7], v[56:59], 0
	v_mfma_f32_16x16x32_bf16 v[52:55], v[8:11], v[60:63], v[52:55]
	v_mfma_f32_16x16x32_bf16 v[56:59], v[0:3], v[60:63], v[56:59]
	s_setprio 0
	s_barrier
	s_add_i32 s49, s41, s25
	v_lshl_add_u64 v[194:195], s[18:19], 0, v[64:65]
	s_mov_b64 s[58:59], 0x100
	s_add_i32 s41, s49, 0x2000
	v_lshl_add_u64 v[138:139], v[194:195], 0, s[58:59]
	s_mov_b32 m0, s49
	v_lshl_add_u64 v[196:197], s[18:19], 0, v[130:131]
	s_add_u32 s54, s18, 0x40100
	ds_read_b128 v[60:63], v137 offset:16384
	ds_read_b128 v[102:105], v137 offset:17408
	ds_read_b128 v[106:109], v137 offset:18432
	ds_read_b128 v[110:113], v137 offset:19456
	ds_read_b128 v[114:117], v137 offset:20480
	ds_read_b128 v[118:121], v137 offset:21504
	ds_read_b128 v[122:125], v137 offset:22528
	ds_read_b128 v[126:129], v137 offset:23552
	global_load_lds_dwordx4 v[138:139], off
	v_lshl_add_u64 v[138:139], v[196:197], 0, s[58:59]
	s_mov_b32 m0, s41
	s_addc_u32 s55, s19, 0
	s_add_i32 s43, s43, s25
	global_load_lds_dwordx4 v[138:139], off
	v_lshl_add_u64 v[138:139], s[54:55], 0, v[64:65]
	s_mov_b32 m0, s43
	s_add_i32 s48, s43, 0x2000
	global_load_lds_dwordx4 v[138:139], off
	v_lshl_add_u64 v[138:139], s[54:55], 0, v[130:131]
	s_mov_b32 m0, s48
	v_lshl_add_u64 v[206:207], s[16:17], 0, v[134:135]
	global_load_lds_dwordx4 v[138:139], off
	v_lshl_add_u64 v[138:139], v[206:207], 0, s[58:59]
	s_mov_b32 m0, s26
	v_lshl_add_u64 v[208:209], s[16:17], 0, v[132:133]
	global_load_lds_dwordx4 v[138:139], off
	v_lshl_add_u64 v[138:139], v[208:209], 0, s[58:59]
	s_mov_b32 m0, s27
	s_nop 0
	global_load_lds_dwordx4 v[138:139], off
	s_waitcnt vmcnt(8)
	s_waitcnt lgkmcnt(0)
	s_barrier
	s_setprio 1
	s_waitcnt lgkmcnt(0)
	v_mfma_f32_16x16x32_bf16 v[138:141], v[28:31], v[60:63], 0
	v_mfma_f32_16x16x32_bf16 v[142:145], v[20:23], v[60:63], 0
	v_mfma_f32_16x16x32_bf16 v[146:149], v[28:31], v[106:109], 0
	v_mfma_f32_16x16x32_bf16 v[150:153], v[20:23], v[106:109], 0
	v_mfma_f32_16x16x32_bf16 v[154:157], v[28:31], v[114:117], 0
	v_mfma_f32_16x16x32_bf16 v[158:161], v[20:23], v[114:117], 0
	v_mfma_f32_16x16x32_bf16 v[28:31], v[28:31], v[122:125], 0
	v_mfma_f32_16x16x32_bf16 v[20:23], v[20:23], v[122:125], 0
	v_mfma_f32_16x16x32_bf16 v[138:141], v[24:27], v[102:105], v[138:141]
	v_mfma_f32_16x16x32_bf16 v[142:145], v[16:19], v[102:105], v[142:145]
	v_mfma_f32_16x16x32_bf16 v[146:149], v[24:27], v[110:113], v[146:149]
	v_mfma_f32_16x16x32_bf16 v[150:153], v[16:19], v[110:113], v[150:153]
	v_mfma_f32_16x16x32_bf16 v[154:157], v[24:27], v[118:121], v[154:157]
	v_mfma_f32_16x16x32_bf16 v[158:161], v[16:19], v[118:121], v[158:161]
	v_mfma_f32_16x16x32_bf16 v[24:27], v[24:27], v[126:129], v[28:31]
	v_mfma_f32_16x16x32_bf16 v[16:19], v[16:19], v[126:129], v[20:23]
	v_mfma_f32_16x16x32_bf16 v[20:23], v[12:15], v[60:63], 0
	v_mfma_f32_16x16x32_bf16 v[28:31], v[4:7], v[60:63], 0
	v_mfma_f32_16x16x32_bf16 v[20:23], v[8:11], v[102:105], v[20:23]
	v_mfma_f32_16x16x32_bf16 v[28:31], v[0:3], v[102:105], v[28:31]
	v_mfma_f32_16x16x32_bf16 v[60:63], v[12:15], v[106:109], 0
	v_mfma_f32_16x16x32_bf16 v[102:105], v[4:7], v[106:109], 0
	v_mfma_f32_16x16x32_bf16 v[60:63], v[8:11], v[110:113], v[60:63]
	v_mfma_f32_16x16x32_bf16 v[102:105], v[0:3], v[110:113], v[102:105]
	v_mfma_f32_16x16x32_bf16 v[106:109], v[12:15], v[114:117], 0
	v_mfma_f32_16x16x32_bf16 v[110:113], v[4:7], v[114:117], 0
	v_mfma_f32_16x16x32_bf16 v[12:15], v[12:15], v[122:125], 0
	v_mfma_f32_16x16x32_bf16 v[4:7], v[4:7], v[122:125], 0
	v_mfma_f32_16x16x32_bf16 v[106:109], v[8:11], v[118:121], v[106:109]
	v_mfma_f32_16x16x32_bf16 v[110:113], v[0:3], v[118:121], v[110:113]
	v_mfma_f32_16x16x32_bf16 v[8:11], v[8:11], v[126:129], v[12:15]
	v_mfma_f32_16x16x32_bf16 v[0:3], v[0:3], v[126:129], v[4:7]
	s_setprio 0
	s_barrier
	s_add_i32 s53, 0, 0x18000
	s_add_i32 s57, 0, 0x1c000
	v_add_u32_e32 v214, s53, v136
	v_add_u32_e32 v222, s57, v136
	ds_read_b128 v[4:7], v214
	ds_read_b128 v[12:15], v214 offset:1024
	ds_read_b128 v[114:117], v214 offset:2048
	ds_read_b128 v[118:121], v214 offset:3072
	ds_read_b128 v[122:125], v222
	ds_read_b128 v[126:129], v222 offset:1024
	ds_read_b128 v[162:165], v222 offset:2048
	ds_read_b128 v[166:169], v222 offset:3072
	s_add_u32 s54, s16, 0x40100
	s_addc_u32 s55, s17, 0
	s_mov_b32 m0, s28
	v_lshl_add_u64 v[210:211], s[54:55], 0, v[134:135]
	ds_read_b128 v[170:173], v137 offset:32768
	ds_read_b128 v[174:177], v137 offset:33792
	ds_read_b128 v[178:181], v137 offset:34816
	ds_read_b128 v[182:185], v137 offset:35840
	ds_read_b128 v[186:189], v137 offset:36864
	ds_read_b128 v[190:193], v137 offset:37888
	ds_read_b128 v[198:201], v137 offset:38912
	ds_read_b128 v[202:205], v137 offset:39936
	global_load_lds_dwordx4 v[210:211], off
	v_lshl_add_u64 v[210:211], s[54:55], 0, v[132:133]
	s_mov_b32 m0, s29
	s_nop 0
	global_load_lds_dwordx4 v[210:211], off
	s_waitcnt vmcnt(8)
	s_waitcnt lgkmcnt(0)
	s_barrier
	s_setprio 1
	s_waitcnt lgkmcnt(0)
	v_mfma_f32_16x16x32_bf16 v[66:69], v[4:7], v[170:173], v[66:69]
	v_mfma_f32_16x16x32_bf16 v[70:73], v[114:117], v[170:173], v[70:73]
	v_mfma_f32_16x16x32_bf16 v[74:77], v[4:7], v[178:181], v[74:77]
	v_mfma_f32_16x16x32_bf16 v[78:81], v[114:117], v[178:181], v[78:81]
	v_mfma_f32_16x16x32_bf16 v[82:85], v[4:7], v[186:189], v[82:85]
	v_mfma_f32_16x16x32_bf16 v[86:89], v[114:117], v[186:189], v[86:89]
	v_mfma_f32_16x16x32_bf16 v[90:93], v[4:7], v[198:201], v[90:93]
	v_mfma_f32_16x16x32_bf16 v[94:97], v[114:117], v[198:201], v[94:97]
	v_mfma_f32_16x16x32_bf16 v[66:69], v[12:15], v[174:177], v[66:69]
	v_mfma_f32_16x16x32_bf16 v[70:73], v[118:121], v[174:177], v[70:73]
	v_mfma_f32_16x16x32_bf16 v[74:77], v[12:15], v[182:185], v[74:77]
	v_mfma_f32_16x16x32_bf16 v[78:81], v[118:121], v[182:185], v[78:81]
	v_mfma_f32_16x16x32_bf16 v[82:85], v[12:15], v[190:193], v[82:85]
	v_mfma_f32_16x16x32_bf16 v[86:89], v[118:121], v[190:193], v[86:89]
	v_mfma_f32_16x16x32_bf16 v[90:93], v[12:15], v[202:205], v[90:93]
	v_mfma_f32_16x16x32_bf16 v[94:97], v[118:121], v[202:205], v[94:97]
	v_mfma_f32_16x16x32_bf16 v[98:101], v[122:125], v[170:173], v[98:101]
	v_mfma_f32_16x16x32_bf16 v[32:35], v[162:165], v[170:173], v[32:35]
	v_mfma_f32_16x16x32_bf16 v[36:39], v[122:125], v[178:181], v[36:39]
	v_mfma_f32_16x16x32_bf16 v[40:43], v[162:165], v[178:181], v[40:43]
	v_mfma_f32_16x16x32_bf16 v[44:47], v[122:125], v[186:189], v[44:47]
	v_mfma_f32_16x16x32_bf16 v[48:51], v[162:165], v[186:189], v[48:51]
	v_mfma_f32_16x16x32_bf16 v[52:55], v[122:125], v[198:201], v[52:55]
	v_mfma_f32_16x16x32_bf16 v[56:59], v[162:165], v[198:201], v[56:59]
	v_mfma_f32_16x16x32_bf16 v[98:101], v[126:129], v[174:177], v[98:101]
	v_mfma_f32_16x16x32_bf16 v[32:35], v[166:169], v[174:177], v[32:35]
	v_mfma_f32_16x16x32_bf16 v[36:39], v[126:129], v[182:185], v[36:39]
	v_mfma_f32_16x16x32_bf16 v[40:43], v[166:169], v[182:185], v[40:43]
	v_mfma_f32_16x16x32_bf16 v[44:47], v[126:129], v[190:193], v[44:47]
	v_mfma_f32_16x16x32_bf16 v[48:51], v[166:169], v[190:193], v[48:51]
	v_mfma_f32_16x16x32_bf16 v[52:55], v[126:129], v[202:205], v[52:55]
	v_mfma_f32_16x16x32_bf16 v[56:59], v[166:169], v[202:205], v[56:59]
	s_setprio 0
	s_barrier
	s_add_i32 s53, s53, s25
	s_mov_b64 s[58:59], 0x180
	s_add_i32 s51, s53, 0x2000
	v_lshl_add_u64 v[194:195], v[194:195], 0, s[58:59]
	s_mov_b32 m0, s53
	s_add_u32 s54, s18, 0x40180
	ds_read_b128 v[170:173], v137 offset:49152
	ds_read_b128 v[174:177], v137 offset:50176
	ds_read_b128 v[178:181], v137 offset:51200
	ds_read_b128 v[182:185], v137 offset:52224
	ds_read_b128 v[186:189], v137 offset:53248
	ds_read_b128 v[190:193], v137 offset:54272
	ds_read_b128 v[198:201], v137 offset:55296
	ds_read_b128 v[202:205], v137 offset:56320
	global_load_lds_dwordx4 v[194:195], off
	v_lshl_add_u64 v[194:195], v[196:197], 0, s[58:59]
	s_mov_b32 m0, s51
	s_addc_u32 s55, s19, 0
	s_add_i32 s18, s57, s25
	global_load_lds_dwordx4 v[194:195], off
	v_lshl_add_u64 v[194:195], s[54:55], 0, v[64:65]
	s_mov_b32 m0, s18
	s_add_i32 s19, s18, 0x2000
	global_load_lds_dwordx4 v[194:195], off
	v_lshl_add_u64 v[194:195], s[54:55], 0, v[130:131]
	s_mov_b32 m0, s19
	s_nop 0
	global_load_lds_dwordx4 v[194:195], off
	v_lshl_add_u64 v[194:195], v[206:207], 0, s[58:59]
	s_mov_b32 m0, s35
	s_nop 0
	global_load_lds_dwordx4 v[194:195], off
	v_lshl_add_u64 v[194:195], v[208:209], 0, s[58:59]
	s_mov_b32 m0, s36
	s_nop 0
	global_load_lds_dwordx4 v[194:195], off
	s_waitcnt vmcnt(8)
	s_waitcnt lgkmcnt(0)
	s_barrier
	s_setprio 1
	s_waitcnt lgkmcnt(0)
	v_mfma_f32_16x16x32_bf16 v[138:141], v[4:7], v[170:173], v[138:141]
	v_mfma_f32_16x16x32_bf16 v[146:149], v[4:7], v[178:181], v[146:149]
	v_mfma_f32_16x16x32_bf16 v[154:157], v[4:7], v[186:189], v[154:157]
	v_mfma_f32_16x16x32_bf16 v[4:7], v[4:7], v[198:201], v[24:27]
	v_mfma_f32_16x16x32_bf16 v[138:141], v[12:15], v[174:177], v[138:141]
	v_mfma_f32_16x16x32_bf16 v[146:149], v[12:15], v[182:185], v[146:149]
	v_mfma_f32_16x16x32_bf16 v[154:157], v[12:15], v[190:193], v[154:157]
	v_mfma_f32_16x16x32_bf16 v[4:7], v[12:15], v[202:205], v[4:7]
	v_mfma_f32_16x16x32_bf16 v[12:15], v[114:117], v[198:201], v[16:19]
	v_mfma_f32_16x16x32_bf16 v[142:145], v[114:117], v[170:173], v[142:145]
	v_mfma_f32_16x16x32_bf16 v[150:153], v[114:117], v[178:181], v[150:153]
	v_mfma_f32_16x16x32_bf16 v[158:161], v[114:117], v[186:189], v[158:161]
	v_mfma_f32_16x16x32_bf16 v[12:15], v[118:121], v[202:205], v[12:15]
	v_mfma_f32_16x16x32_bf16 v[142:145], v[118:121], v[174:177], v[142:145]
	v_mfma_f32_16x16x32_bf16 v[150:153], v[118:121], v[182:185], v[150:153]
	v_mfma_f32_16x16x32_bf16 v[158:161], v[118:121], v[190:193], v[158:161]
	v_mfma_f32_16x16x32_bf16 v[16:19], v[122:125], v[170:173], v[20:23]
	v_mfma_f32_16x16x32_bf16 v[20:23], v[162:165], v[170:173], v[28:31]
	v_mfma_f32_16x16x32_bf16 v[24:27], v[122:125], v[178:181], v[60:63]
	v_mfma_f32_16x16x32_bf16 v[28:31], v[162:165], v[178:181], v[102:105]
	v_mfma_f32_16x16x32_bf16 v[60:63], v[122:125], v[186:189], v[106:109]
	v_mfma_f32_16x16x32_bf16 v[102:105], v[162:165], v[186:189], v[110:113]
	v_mfma_f32_16x16x32_bf16 v[8:11], v[122:125], v[198:201], v[8:11]
	v_mfma_f32_16x16x32_bf16 v[0:3], v[162:165], v[198:201], v[0:3]
	v_mfma_f32_16x16x32_bf16 v[16:19], v[126:129], v[174:177], v[16:19]
	v_mfma_f32_16x16x32_bf16 v[20:23], v[166:169], v[174:177], v[20:23]
	v_mfma_f32_16x16x32_bf16 v[24:27], v[126:129], v[182:185], v[24:27]
	v_mfma_f32_16x16x32_bf16 v[28:31], v[166:169], v[182:185], v[28:31]
	v_mfma_f32_16x16x32_bf16 v[60:63], v[126:129], v[190:193], v[60:63]
	v_mfma_f32_16x16x32_bf16 v[102:105], v[166:169], v[190:193], v[102:105]
	v_mfma_f32_16x16x32_bf16 v[8:11], v[126:129], v[202:205], v[8:11]
	v_mfma_f32_16x16x32_bf16 v[0:3], v[166:169], v[202:205], v[0:3]
	s_setprio 0
	s_barrier
	ds_read_b128 v[106:109], v213
	ds_read_b128 v[110:113], v213 offset:1024
	ds_read_b128 v[114:117], v213 offset:2048
	ds_read_b128 v[118:121], v213 offset:3072
	ds_read_b128 v[122:125], v212
	ds_read_b128 v[126:129], v212 offset:1024
	ds_read_b128 v[162:165], v212 offset:2048
	ds_read_b128 v[166:169], v212 offset:3072
	s_add_u32 s16, s16, 0x40180
	s_addc_u32 s17, s17, 0
	s_mov_b32 m0, s52
	v_lshl_add_u64 v[194:195], s[16:17], 0, v[134:135]
	ds_read_b128 v[170:173], v137
	ds_read_b128 v[174:177], v137 offset:1024
	ds_read_b128 v[178:181], v137 offset:2048
	ds_read_b128 v[182:185], v137 offset:3072
	ds_read_b128 v[186:189], v137 offset:4096
	ds_read_b128 v[190:193], v137 offset:5120
	ds_read_b128 v[198:201], v137 offset:6144
	ds_read_b128 v[202:205], v137 offset:7168
	global_load_lds_dwordx4 v[194:195], off
	v_lshl_add_u64 v[194:195], s[16:17], 0, v[132:133]
	s_mov_b32 m0, s11
	s_nop 0
	global_load_lds_dwordx4 v[194:195], off
	s_waitcnt vmcnt(8)
	s_waitcnt lgkmcnt(0)
	s_barrier
	s_setprio 1
	s_waitcnt lgkmcnt(0)
	v_mfma_f32_16x16x32_bf16 v[66:69], v[106:109], v[170:173], v[66:69]
	v_mfma_f32_16x16x32_bf16 v[70:73], v[114:117], v[170:173], v[70:73]
	v_mfma_f32_16x16x32_bf16 v[74:77], v[106:109], v[178:181], v[74:77]
	v_mfma_f32_16x16x32_bf16 v[78:81], v[114:117], v[178:181], v[78:81]
	v_mfma_f32_16x16x32_bf16 v[82:85], v[106:109], v[186:189], v[82:85]
	v_mfma_f32_16x16x32_bf16 v[86:89], v[114:117], v[186:189], v[86:89]
	v_mfma_f32_16x16x32_bf16 v[90:93], v[106:109], v[198:201], v[90:93]
	v_mfma_f32_16x16x32_bf16 v[94:97], v[114:117], v[198:201], v[94:97]
	v_mfma_f32_16x16x32_bf16 v[66:69], v[110:113], v[174:177], v[66:69]
	v_mfma_f32_16x16x32_bf16 v[70:73], v[118:121], v[174:177], v[70:73]
	v_mfma_f32_16x16x32_bf16 v[74:77], v[110:113], v[182:185], v[74:77]
	v_mfma_f32_16x16x32_bf16 v[78:81], v[118:121], v[182:185], v[78:81]
	v_mfma_f32_16x16x32_bf16 v[82:85], v[110:113], v[190:193], v[82:85]
	v_mfma_f32_16x16x32_bf16 v[86:89], v[118:121], v[190:193], v[86:89]
	v_mfma_f32_16x16x32_bf16 v[90:93], v[110:113], v[202:205], v[90:93]
	v_mfma_f32_16x16x32_bf16 v[94:97], v[118:121], v[202:205], v[94:97]
	v_mfma_f32_16x16x32_bf16 v[40:43], v[162:165], v[178:181], v[40:43]
	v_mfma_f32_16x16x32_bf16 v[98:101], v[122:125], v[170:173], v[98:101]
	v_mfma_f32_16x16x32_bf16 v[32:35], v[162:165], v[170:173], v[32:35]
	v_mfma_f32_16x16x32_bf16 v[170:173], v[166:169], v[182:185], v[40:43]
	v_mfma_f32_16x16x32_bf16 v[40:43], v[122:125], v[186:189], v[44:47]
	v_mfma_f32_16x16x32_bf16 v[98:101], v[126:129], v[174:177], v[98:101]
	v_mfma_f32_16x16x32_bf16 v[32:35], v[166:169], v[174:177], v[32:35]
	v_mfma_f32_16x16x32_bf16 v[174:177], v[126:129], v[190:193], v[40:43]
	v_mfma_f32_16x16x32_bf16 v[40:43], v[162:165], v[186:189], v[48:51]
	v_mfma_f32_16x16x32_bf16 v[36:39], v[122:125], v[178:181], v[36:39]
	v_mfma_f32_16x16x32_bf16 v[48:51], v[166:169], v[190:193], v[40:43]
	v_mfma_f32_16x16x32_bf16 v[40:43], v[122:125], v[198:201], v[52:55]
	v_mfma_f32_16x16x32_bf16 v[36:39], v[126:129], v[182:185], v[36:39]
	v_mfma_f32_16x16x32_bf16 v[52:55], v[126:129], v[202:205], v[40:43]
	v_mfma_f32_16x16x32_bf16 v[40:43], v[162:165], v[198:201], v[56:59]
	v_mfma_f32_16x16x32_bf16 v[178:181], v[166:169], v[202:205], v[40:43]
	s_setprio 0
	s_barrier
	s_mov_b32 m0, s49
	v_lshl_add_u64 v[194:195], s[14:15], 0, v[64:65]
	s_add_u32 s16, s14, 0x40000
	s_nop 1
	ds_read_b128 v[40:43], v137 offset:16384
	ds_read_b128 v[44:47], v137 offset:17408
	ds_read_b128 v[56:59], v137 offset:18432
	ds_read_b128 v[182:185], v137 offset:19456
	ds_read_b128 v[186:189], v137 offset:20480
	ds_read_b128 v[190:193], v137 offset:21504
	ds_read_b128 v[198:201], v137 offset:22528
	ds_read_b128 v[202:205], v137 offset:23552
	global_load_lds_dwordx4 v[194:195], off
	v_lshl_add_u64 v[196:197], s[14:15], 0, v[130:131]
	s_mov_b32 m0, s41
	s_addc_u32 s17, s15, 0
	global_load_lds_dwordx4 v[196:197], off
	v_lshl_add_u64 v[206:207], s[16:17], 0, v[64:65]
	s_mov_b32 m0, s43
	v_lshl_add_u64 v[238:239], s[12:13], 0, v[134:135]
	global_load_lds_dwordx4 v[206:207], off
	v_lshl_add_u64 v[206:207], s[16:17], 0, v[130:131]
	s_mov_b32 m0, s48
	v_lshl_add_u64 v[240:241], s[12:13], 0, v[132:133]
	global_load_lds_dwordx4 v[206:207], off
	s_mov_b32 m0, s26
	s_nop 0
	global_load_lds_dwordx4 v[238:239], off
	s_mov_b32 m0, s27
	s_nop 0
	global_load_lds_dwordx4 v[240:241], off
	s_waitcnt vmcnt(8)
	s_waitcnt lgkmcnt(0)
	s_barrier
	s_setprio 1
	s_waitcnt lgkmcnt(0)
	v_mfma_f32_16x16x32_bf16 v[4:7], v[106:109], v[198:201], v[4:7]
	v_mfma_f32_16x16x32_bf16 v[12:15], v[114:117], v[198:201], v[12:15]
	v_mfma_f32_16x16x32_bf16 v[138:141], v[106:109], v[40:43], v[138:141]
	v_mfma_f32_16x16x32_bf16 v[142:145], v[114:117], v[40:43], v[142:145]
	v_mfma_f32_16x16x32_bf16 v[146:149], v[106:109], v[56:59], v[146:149]
	v_mfma_f32_16x16x32_bf16 v[150:153], v[114:117], v[56:59], v[150:153]
	v_mfma_f32_16x16x32_bf16 v[154:157], v[106:109], v[186:189], v[154:157]
	v_mfma_f32_16x16x32_bf16 v[158:161], v[114:117], v[186:189], v[158:161]
	v_mfma_f32_16x16x32_bf16 v[4:7], v[110:113], v[202:205], v[4:7]
	v_mfma_f32_16x16x32_bf16 v[114:117], v[118:121], v[202:205], v[12:15]
	v_mfma_f32_16x16x32_bf16 v[138:141], v[110:113], v[44:47], v[138:141]
	v_mfma_f32_16x16x32_bf16 v[142:145], v[118:121], v[44:47], v[142:145]
	v_mfma_f32_16x16x32_bf16 v[146:149], v[110:113], v[182:185], v[146:149]
	v_mfma_f32_16x16x32_bf16 v[150:153], v[118:121], v[182:185], v[150:153]
	v_mfma_f32_16x16x32_bf16 v[154:157], v[110:113], v[190:193], v[154:157]
	v_mfma_f32_16x16x32_bf16 v[158:161], v[118:121], v[190:193], v[158:161]
	v_mfma_f32_16x16x32_bf16 v[12:15], v[122:125], v[40:43], v[16:19]
	v_mfma_f32_16x16x32_bf16 v[16:19], v[126:129], v[44:47], v[12:15]
	v_mfma_f32_16x16x32_bf16 v[12:15], v[162:165], v[40:43], v[20:23]
	v_mfma_f32_16x16x32_bf16 v[20:23], v[166:169], v[44:47], v[12:15]
	v_mfma_f32_16x16x32_bf16 v[12:15], v[122:125], v[56:59], v[24:27]
	v_mfma_f32_16x16x32_bf16 v[206:209], v[126:129], v[182:185], v[12:15]
	v_mfma_f32_16x16x32_bf16 v[12:15], v[162:165], v[56:59], v[28:31]
	v_mfma_f32_16x16x32_bf16 v[182:185], v[166:169], v[182:185], v[12:15]
	v_mfma_f32_16x16x32_bf16 v[12:15], v[122:125], v[186:189], v[60:63]
	v_mfma_f32_16x16x32_bf16 v[210:213], v[126:129], v[190:193], v[12:15]
	v_mfma_f32_16x16x32_bf16 v[12:15], v[162:165], v[186:189], v[102:105]
	v_mfma_f32_16x16x32_bf16 v[8:11], v[122:125], v[198:201], v[8:11]
	v_mfma_f32_16x16x32_bf16 v[0:3], v[162:165], v[198:201], v[0:3]
	v_mfma_f32_16x16x32_bf16 v[186:189], v[166:169], v[190:193], v[12:15]
	v_mfma_f32_16x16x32_bf16 v[190:193], v[126:129], v[202:205], v[8:11]
	v_mfma_f32_16x16x32_bf16 v[162:165], v[166:169], v[202:205], v[0:3]
	s_setprio 0
	s_barrier
	s_nop 2
	ds_read_b128 v[0:3], v214
	ds_read_b128 v[118:121], v214 offset:1024
	ds_read_b128 v[166:169], v214 offset:2048
	ds_read_b128 v[198:201], v214 offset:3072
	ds_read_b128 v[202:205], v222
	ds_read_b128 v[214:217], v222 offset:1024
	ds_read_b128 v[218:221], v222 offset:2048
	ds_read_b128 v[222:225], v222 offset:3072
	s_add_u32 s16, s12, 0x40000
	s_addc_u32 s17, s13, 0
	s_mov_b32 m0, s28
	v_lshl_add_u64 v[8:9], s[16:17], 0, v[134:135]
	ds_read_b128 v[24:27], v137 offset:32768
	ds_read_b128 v[28:31], v137 offset:33792
	ds_read_b128 v[56:59], v137 offset:34816
	ds_read_b128 v[60:63], v137 offset:35840
	ds_read_b128 v[102:105], v137 offset:36864
	ds_read_b128 v[228:231], v137 offset:37888
	ds_read_b128 v[242:245], v137 offset:38912
	ds_read_b128 v[246:249], v137 offset:39936
	global_load_lds_dwordx4 v[8:9], off
	v_lshl_add_u64 v[8:9], s[16:17], 0, v[132:133]
	s_mov_b32 m0, s29
	s_nop 0
	global_load_lds_dwordx4 v[8:9], off
	s_waitcnt vmcnt(8)
	s_waitcnt lgkmcnt(0)
	s_barrier
	s_setprio 1
	s_waitcnt lgkmcnt(0)
	v_mfma_f32_16x16x32_bf16 v[8:11], v[0:3], v[24:27], v[66:69]
	v_mfma_f32_16x16x32_bf16 v[106:109], v[118:121], v[28:31], v[8:11]
	v_mfma_f32_16x16x32_bf16 v[8:11], v[166:169], v[24:27], v[70:73]
	v_mfma_f32_16x16x32_bf16 v[110:113], v[198:201], v[28:31], v[8:11]
	v_mfma_f32_16x16x32_bf16 v[8:11], v[0:3], v[56:59], v[74:77]
	v_mfma_f32_16x16x32_bf16 v[74:77], v[118:121], v[60:63], v[8:11]
	v_mfma_f32_16x16x32_bf16 v[8:11], v[166:169], v[56:59], v[78:81]
	v_mfma_f32_16x16x32_bf16 v[78:81], v[198:201], v[60:63], v[8:11]
	v_mfma_f32_16x16x32_bf16 v[8:11], v[0:3], v[102:105], v[82:85]
	v_mfma_f32_16x16x32_bf16 v[40:43], v[118:121], v[228:231], v[8:11]
	v_mfma_f32_16x16x32_bf16 v[8:11], v[166:169], v[102:105], v[86:89]
	v_mfma_f32_16x16x32_bf16 v[44:47], v[198:201], v[228:231], v[8:11]
	v_mfma_f32_16x16x32_bf16 v[8:11], v[0:3], v[242:245], v[90:93]
	v_mfma_f32_16x16x32_bf16 v[12:15], v[166:169], v[242:245], v[94:97]
	v_mfma_f32_16x16x32_bf16 v[8:11], v[118:121], v[246:249], v[8:11]
	v_mfma_f32_16x16x32_bf16 v[12:15], v[198:201], v[246:249], v[12:15]
	v_mfma_f32_16x16x32_bf16 v[66:69], v[202:205], v[24:27], v[98:101]
	v_mfma_f32_16x16x32_bf16 v[24:27], v[218:221], v[24:27], v[32:35]
	v_mfma_f32_16x16x32_bf16 v[126:129], v[222:225], v[28:31], v[24:27]
	v_mfma_f32_16x16x32_bf16 v[24:27], v[202:205], v[56:59], v[36:39]
	v_mfma_f32_16x16x32_bf16 v[90:93], v[214:217], v[60:63], v[24:27]
	v_mfma_f32_16x16x32_bf16 v[24:27], v[218:221], v[56:59], v[170:173]
	v_mfma_f32_16x16x32_bf16 v[94:97], v[222:225], v[60:63], v[24:27]
	v_mfma_f32_16x16x32_bf16 v[24:27], v[202:205], v[102:105], v[174:177]
	v_mfma_f32_16x16x32_bf16 v[56:59], v[214:217], v[228:231], v[24:27]
	v_mfma_f32_16x16x32_bf16 v[24:27], v[218:221], v[102:105], v[48:51]
	v_mfma_f32_16x16x32_bf16 v[122:125], v[214:217], v[28:31], v[66:69]
	v_mfma_f32_16x16x32_bf16 v[60:63], v[222:225], v[228:231], v[24:27]
	v_mfma_f32_16x16x32_bf16 v[24:27], v[202:205], v[242:245], v[52:55]
	v_mfma_f32_16x16x32_bf16 v[28:31], v[218:221], v[242:245], v[178:181]
	v_mfma_f32_16x16x32_bf16 v[24:27], v[214:217], v[246:249], v[24:27]
	v_mfma_f32_16x16x32_bf16 v[28:31], v[222:225], v[246:249], v[28:31]
	s_setprio 0
	s_barrier
	s_mov_b32 m0, s53
	v_lshl_add_u64 v[32:33], v[194:195], 0, s[96:97]
	s_add_u32 s16, s14, 0x40080
	ds_read_b128 v[48:51], v137 offset:49152
	ds_read_b128 v[52:55], v137 offset:50176
	ds_read_b128 v[86:89], v137 offset:51200
	ds_read_b128 v[170:173], v137 offset:52224
	ds_read_b128 v[174:177], v137 offset:53248
	ds_read_b128 v[178:181], v137 offset:54272
	ds_read_b128 v[228:231], v137 offset:55296
	ds_read_b128 v[242:245], v137 offset:56320
	global_load_lds_dwordx4 v[32:33], off
	v_lshl_add_u64 v[32:33], v[196:197], 0, s[96:97]
	s_mov_b32 m0, s51
	s_addc_u32 s17, s15, 0
	global_load_lds_dwordx4 v[32:33], off
	v_lshl_add_u64 v[32:33], s[16:17], 0, v[64:65]
	s_mov_b32 m0, s18
	s_nop 0
	global_load_lds_dwordx4 v[32:33], off
	v_lshl_add_u64 v[32:33], s[16:17], 0, v[130:131]
	s_mov_b32 m0, s19
	s_nop 0
	global_load_lds_dwordx4 v[32:33], off
	v_lshl_add_u64 v[32:33], v[238:239], 0, s[96:97]
	s_mov_b32 m0, s35
	s_nop 0
	global_load_lds_dwordx4 v[32:33], off
	v_lshl_add_u64 v[32:33], v[240:241], 0, s[96:97]
	s_mov_b32 m0, s36
	s_nop 0
	global_load_lds_dwordx4 v[32:33], off
	s_waitcnt vmcnt(8)
	s_waitcnt lgkmcnt(0)
	s_barrier
	s_setprio 1
	s_waitcnt lgkmcnt(0)
	v_mfma_f32_16x16x32_bf16 v[32:35], v[0:3], v[48:51], v[138:141]
	v_mfma_f32_16x16x32_bf16 v[98:101], v[118:121], v[52:55], v[32:35]
	v_mfma_f32_16x16x32_bf16 v[32:35], v[166:169], v[48:51], v[142:145]
	v_mfma_f32_16x16x32_bf16 v[102:105], v[198:201], v[52:55], v[32:35]
	v_mfma_f32_16x16x32_bf16 v[32:35], v[0:3], v[86:89], v[146:149]
	v_mfma_f32_16x16x32_bf16 v[66:69], v[118:121], v[170:173], v[32:35]
	v_mfma_f32_16x16x32_bf16 v[32:35], v[166:169], v[86:89], v[150:153]
	v_mfma_f32_16x16x32_bf16 v[70:73], v[198:201], v[170:173], v[32:35]
	v_mfma_f32_16x16x32_bf16 v[32:35], v[0:3], v[174:177], v[154:157]
	v_mfma_f32_16x16x32_bf16 v[36:39], v[166:169], v[174:177], v[158:161]
	v_mfma_f32_16x16x32_bf16 v[0:3], v[0:3], v[228:231], v[4:7]
	v_mfma_f32_16x16x32_bf16 v[4:7], v[166:169], v[228:231], v[114:117]
	v_mfma_f32_16x16x32_bf16 v[32:35], v[118:121], v[178:181], v[32:35]
	v_mfma_f32_16x16x32_bf16 v[36:39], v[198:201], v[178:181], v[36:39]
	v_mfma_f32_16x16x32_bf16 v[0:3], v[118:121], v[242:245], v[0:3]
	v_mfma_f32_16x16x32_bf16 v[4:7], v[198:201], v[242:245], v[4:7]
	v_mfma_f32_16x16x32_bf16 v[16:19], v[202:205], v[48:51], v[16:19]
	v_mfma_f32_16x16x32_bf16 v[114:117], v[214:217], v[52:55], v[16:19]
	v_mfma_f32_16x16x32_bf16 v[16:19], v[218:221], v[48:51], v[20:23]
	v_mfma_f32_16x16x32_bf16 v[118:121], v[222:225], v[52:55], v[16:19]
	v_mfma_f32_16x16x32_bf16 v[16:19], v[202:205], v[86:89], v[206:209]
	v_mfma_f32_16x16x32_bf16 v[82:85], v[214:217], v[170:173], v[16:19]
	v_mfma_f32_16x16x32_bf16 v[16:19], v[218:221], v[86:89], v[182:185]
	v_mfma_f32_16x16x32_bf16 v[86:89], v[222:225], v[170:173], v[16:19]
	v_mfma_f32_16x16x32_bf16 v[16:19], v[202:205], v[174:177], v[210:213]
	v_mfma_f32_16x16x32_bf16 v[48:51], v[214:217], v[178:181], v[16:19]
	v_mfma_f32_16x16x32_bf16 v[16:19], v[218:221], v[174:177], v[186:189]
	v_mfma_f32_16x16x32_bf16 v[52:55], v[222:225], v[178:181], v[16:19]
	v_mfma_f32_16x16x32_bf16 v[16:19], v[202:205], v[228:231], v[190:193]
	v_mfma_f32_16x16x32_bf16 v[20:23], v[218:221], v[228:231], v[162:165]
	v_mfma_f32_16x16x32_bf16 v[16:19], v[214:217], v[242:245], v[16:19]
	v_mfma_f32_16x16x32_bf16 v[20:23], v[222:225], v[242:245], v[20:23]
	s_setprio 0
	s_barrier
	s_andn2_b64 vcc, exec, s[8:9]
	s_cbranch_vccnz .LBB0_1608
	s_barrier

.LBB0_1628:
	s_add_u32 s24, s22, 0xfff80080
	s_addc_u32 s25, s23, -1
	s_cmp_eq_u32 s62, 28
	s_cselect_b32 s29, s17, s25
	s_cselect_b32 s28, s55, s24
	s_cselect_b32 s25, s15, s59
	s_cselect_b32 s24, s57, s58
	s_add_i32 s63, 0, 0x10000
	s_add_i32 s66, 0, 0x14000
	v_add_u32_e32 v142, s63, v172
	v_add_u32_e32 v168, s66, v172
	ds_read_b128 v[130:133], v142
	ds_read_b128 v[134:137], v142 offset:1024
	ds_read_b128 v[138:141], v142 offset:2048
	ds_read_b128 v[142:145], v142 offset:3072
	ds_read_b128 v[146:149], v168
	ds_read_b128 v[160:163], v168 offset:1024
	ds_read_b128 v[164:167], v168 offset:2048
	ds_read_b128 v[168:171], v168 offset:3072
	v_lshl_add_u64 v[194:195], s[22:23], 0, v[156:157]
	s_add_i32 m0, s37, 0xc000
	ds_read_b128 v[174:177], v173
	ds_read_b128 v[178:181], v173 offset:1024
	ds_read_b128 v[182:185], v173 offset:2048
	ds_read_b128 v[186:189], v173 offset:3072
	ds_read_b128 v[190:193], v173 offset:4096
	ds_read_b128 v[198:201], v173 offset:5120
	ds_read_b128 v[202:205], v173 offset:6144
	ds_read_b128 v[206:209], v173 offset:7168
	global_load_lds_dwordx4 v[194:195], off
	v_lshl_add_u64 v[194:195], s[22:23], 0, v[158:159]
	s_add_i32 m0, s37, 0xe000
	s_nop 0
	global_load_lds_dwordx4 v[194:195], off
	s_waitcnt vmcnt(8)
	s_waitcnt lgkmcnt(0)
	s_barrier
	s_setprio 1
	s_waitcnt lgkmcnt(0)
	v_mfma_f32_16x16x32_bf16 v[126:129], v[130:133], v[174:177], v[126:129]
	v_mfma_f32_16x16x32_bf16 v[122:125], v[138:141], v[174:177], v[122:125]
	v_mfma_f32_16x16x32_bf16 v[118:121], v[130:133], v[182:185], v[118:121]
	v_mfma_f32_16x16x32_bf16 v[110:113], v[138:141], v[182:185], v[110:113]
	v_mfma_f32_16x16x32_bf16 v[98:101], v[130:133], v[190:193], v[98:101]
	v_mfma_f32_16x16x32_bf16 v[90:93], v[138:141], v[190:193], v[90:93]
	v_mfma_f32_16x16x32_bf16 v[82:85], v[130:133], v[202:205], v[82:85]
	v_mfma_f32_16x16x32_bf16 v[74:77], v[138:141], v[202:205], v[74:77]
	v_mfma_f32_16x16x32_bf16 v[126:129], v[134:137], v[178:181], v[126:129]
	v_mfma_f32_16x16x32_bf16 v[122:125], v[142:145], v[178:181], v[122:125]
	v_mfma_f32_16x16x32_bf16 v[118:121], v[134:137], v[186:189], v[118:121]
	v_mfma_f32_16x16x32_bf16 v[110:113], v[142:145], v[186:189], v[110:113]
	v_mfma_f32_16x16x32_bf16 v[98:101], v[134:137], v[198:201], v[98:101]
	v_mfma_f32_16x16x32_bf16 v[90:93], v[142:145], v[198:201], v[90:93]
	v_mfma_f32_16x16x32_bf16 v[82:85], v[134:137], v[206:209], v[82:85]
	v_mfma_f32_16x16x32_bf16 v[74:77], v[142:145], v[206:209], v[74:77]
	v_mfma_f32_16x16x32_bf16 v[114:117], v[146:149], v[174:177], v[114:117]
	v_mfma_f32_16x16x32_bf16 v[106:109], v[164:167], v[174:177], v[106:109]
	v_mfma_f32_16x16x32_bf16 v[102:105], v[146:149], v[182:185], v[102:105]
	v_mfma_f32_16x16x32_bf16 v[94:97], v[164:167], v[182:185], v[94:97]
	v_mfma_f32_16x16x32_bf16 v[86:89], v[146:149], v[190:193], v[86:89]
	v_mfma_f32_16x16x32_bf16 v[78:81], v[164:167], v[190:193], v[78:81]
	v_mfma_f32_16x16x32_bf16 v[70:73], v[146:149], v[202:205], v[70:73]
	v_mfma_f32_16x16x32_bf16 v[66:69], v[164:167], v[202:205], v[66:69]
	v_mfma_f32_16x16x32_bf16 v[114:117], v[160:163], v[178:181], v[114:117]
	v_mfma_f32_16x16x32_bf16 v[106:109], v[168:171], v[178:181], v[106:109]
	v_mfma_f32_16x16x32_bf16 v[102:105], v[160:163], v[186:189], v[102:105]
	v_mfma_f32_16x16x32_bf16 v[94:97], v[168:171], v[186:189], v[94:97]
	v_mfma_f32_16x16x32_bf16 v[86:89], v[160:163], v[198:201], v[86:89]
	v_mfma_f32_16x16x32_bf16 v[78:81], v[168:171], v[198:201], v[78:81]
	v_mfma_f32_16x16x32_bf16 v[70:73], v[160:163], v[206:209], v[70:73]
	v_mfma_f32_16x16x32_bf16 v[66:69], v[168:171], v[206:209], v[66:69]
	s_setprio 0
	s_barrier
	s_add_i32 s63, s63, s36
	v_lshl_add_u64 v[194:195], s[24:25], 0, v[64:65]
	s_mov_b32 m0, s63
	ds_read_b128 v[174:177], v173 offset:16384
	ds_read_b128 v[178:181], v173 offset:17408
	ds_read_b128 v[182:185], v173 offset:18432
	ds_read_b128 v[186:189], v173 offset:19456
	ds_read_b128 v[190:193], v173 offset:20480
	ds_read_b128 v[198:201], v173 offset:21504
	ds_read_b128 v[202:205], v173 offset:22528
	ds_read_b128 v[206:209], v173 offset:23552
	global_load_lds_dwordx4 v[194:195], off
	s_add_i32 m0, s63, 0x2000
	s_add_u32 s70, s24, 0x80000
	v_lshl_add_u64 v[196:197], s[24:25], 0, v[150:151]
	s_addc_u32 s71, s25, 0
	s_add_i32 s63, s66, s36
	global_load_lds_dwordx4 v[196:197], off
	v_lshl_add_u64 v[210:211], s[70:71], 0, v[64:65]
	s_mov_b32 m0, s63
	v_lshl_add_u64 v[212:213], s[28:29], 0, v[152:153]
	global_load_lds_dwordx4 v[210:211], off
	v_lshl_add_u64 v[210:211], s[70:71], 0, v[150:151]
	s_add_i32 m0, s63, 0x2000
	s_nop 0
	global_load_lds_dwordx4 v[210:211], off
	v_lshl_add_u64 v[210:211], s[28:29], 0, v[154:155]
	s_mov_b32 m0, s37
	s_nop 0
	global_load_lds_dwordx4 v[210:211], off
	s_mov_b32 m0, s38
	s_nop 0
	global_load_lds_dwordx4 v[212:213], off
	s_waitcnt vmcnt(8)
	s_waitcnt lgkmcnt(0)
	s_barrier
	s_setprio 1
	s_waitcnt lgkmcnt(0)
	v_mfma_f32_16x16x32_bf16 v[60:63], v[130:133], v[174:177], v[60:63]
	v_mfma_f32_16x16x32_bf16 v[56:59], v[138:141], v[174:177], v[56:59]
	v_mfma_f32_16x16x32_bf16 v[48:51], v[130:133], v[182:185], v[48:51]
	v_mfma_f32_16x16x32_bf16 v[40:43], v[138:141], v[182:185], v[40:43]
	v_mfma_f32_16x16x32_bf16 v[32:35], v[130:133], v[190:193], v[32:35]
	v_mfma_f32_16x16x32_bf16 v[24:27], v[138:141], v[190:193], v[24:27]
	v_mfma_f32_16x16x32_bf16 v[16:19], v[130:133], v[202:205], v[16:19]
	v_mfma_f32_16x16x32_bf16 v[8:11], v[138:141], v[202:205], v[8:11]
	v_mfma_f32_16x16x32_bf16 v[60:63], v[134:137], v[178:181], v[60:63]
	v_mfma_f32_16x16x32_bf16 v[56:59], v[142:145], v[178:181], v[56:59]
	v_mfma_f32_16x16x32_bf16 v[48:51], v[134:137], v[186:189], v[48:51]
	v_mfma_f32_16x16x32_bf16 v[40:43], v[142:145], v[186:189], v[40:43]
	v_mfma_f32_16x16x32_bf16 v[32:35], v[134:137], v[198:201], v[32:35]
	v_mfma_f32_16x16x32_bf16 v[24:27], v[142:145], v[198:201], v[24:27]
	v_mfma_f32_16x16x32_bf16 v[16:19], v[134:137], v[206:209], v[16:19]
	v_mfma_f32_16x16x32_bf16 v[8:11], v[142:145], v[206:209], v[8:11]
	v_mfma_f32_16x16x32_bf16 v[52:55], v[146:149], v[174:177], v[52:55]
	v_mfma_f32_16x16x32_bf16 v[44:47], v[164:167], v[174:177], v[44:47]
	v_mfma_f32_16x16x32_bf16 v[36:39], v[146:149], v[182:185], v[36:39]
	v_mfma_f32_16x16x32_bf16 v[28:31], v[164:167], v[182:185], v[28:31]
	v_mfma_f32_16x16x32_bf16 v[20:23], v[146:149], v[190:193], v[20:23]
	v_mfma_f32_16x16x32_bf16 v[12:15], v[164:167], v[190:193], v[12:15]
	v_mfma_f32_16x16x32_bf16 v[4:7], v[146:149], v[202:205], v[4:7]
	v_mfma_f32_16x16x32_bf16 v[0:3], v[164:167], v[202:205], v[0:3]
	v_mfma_f32_16x16x32_bf16 v[52:55], v[160:163], v[178:181], v[52:55]
	v_mfma_f32_16x16x32_bf16 v[44:47], v[168:171], v[178:181], v[44:47]
	v_mfma_f32_16x16x32_bf16 v[36:39], v[160:163], v[186:189], v[36:39]
	v_mfma_f32_16x16x32_bf16 v[28:31], v[168:171], v[186:189], v[28:31]
	v_mfma_f32_16x16x32_bf16 v[20:23], v[160:163], v[198:201], v[20:23]
	v_mfma_f32_16x16x32_bf16 v[12:15], v[168:171], v[198:201], v[12:15]
	v_mfma_f32_16x16x32_bf16 v[4:7], v[160:163], v[206:209], v[4:7]
	v_mfma_f32_16x16x32_bf16 v[0:3], v[168:171], v[206:209], v[0:3]
	s_setprio 0
	s_barrier
	s_add_i32 s63, 0, 0x18000
	s_add_i32 s66, 0, 0x1c000
	v_add_u32_e32 v142, s63, v172
	v_add_u32_e32 v168, s66, v172
	ds_read_b128 v[130:133], v142
	ds_read_b128 v[134:137], v142 offset:1024
	ds_read_b128 v[138:141], v142 offset:2048
	ds_read_b128 v[142:145], v142 offset:3072
	ds_read_b128 v[146:149], v168
	ds_read_b128 v[160:163], v168 offset:1024
	ds_read_b128 v[164:167], v168 offset:2048
	ds_read_b128 v[168:171], v168 offset:3072
	s_add_u32 s28, s28, 0x80000
	s_addc_u32 s29, s29, 0
	s_mov_b32 m0, s39
	v_lshl_add_u64 v[214:215], s[28:29], 0, v[154:155]
	ds_read_b128 v[174:177], v173 offset:32768
	ds_read_b128 v[178:181], v173 offset:33792
	ds_read_b128 v[182:185], v173 offset:34816
	ds_read_b128 v[186:189], v173 offset:35840
	ds_read_b128 v[190:193], v173 offset:36864
	ds_read_b128 v[198:201], v173 offset:37888
	ds_read_b128 v[202:205], v173 offset:38912
	ds_read_b128 v[206:209], v173 offset:39936
	global_load_lds_dwordx4 v[214:215], off
	v_lshl_add_u64 v[214:215], s[28:29], 0, v[152:153]
	s_mov_b32 m0, s44
	s_nop 0
	global_load_lds_dwordx4 v[214:215], off
	s_waitcnt vmcnt(8)
	s_waitcnt lgkmcnt(0)
	s_barrier
	s_setprio 1
	s_waitcnt lgkmcnt(0)
	v_mfma_f32_16x16x32_bf16 v[126:129], v[130:133], v[174:177], v[126:129]
	v_mfma_f32_16x16x32_bf16 v[122:125], v[138:141], v[174:177], v[122:125]
	v_mfma_f32_16x16x32_bf16 v[118:121], v[130:133], v[182:185], v[118:121]
	v_mfma_f32_16x16x32_bf16 v[110:113], v[138:141], v[182:185], v[110:113]
	v_mfma_f32_16x16x32_bf16 v[98:101], v[130:133], v[190:193], v[98:101]
	v_mfma_f32_16x16x32_bf16 v[90:93], v[138:141], v[190:193], v[90:93]
	v_mfma_f32_16x16x32_bf16 v[82:85], v[130:133], v[202:205], v[82:85]
	v_mfma_f32_16x16x32_bf16 v[74:77], v[138:141], v[202:205], v[74:77]
	v_mfma_f32_16x16x32_bf16 v[126:129], v[134:137], v[178:181], v[126:129]
	v_mfma_f32_16x16x32_bf16 v[122:125], v[142:145], v[178:181], v[122:125]
	v_mfma_f32_16x16x32_bf16 v[118:121], v[134:137], v[186:189], v[118:121]
	v_mfma_f32_16x16x32_bf16 v[110:113], v[142:145], v[186:189], v[110:113]
	v_mfma_f32_16x16x32_bf16 v[98:101], v[134:137], v[198:201], v[98:101]
	v_mfma_f32_16x16x32_bf16 v[90:93], v[142:145], v[198:201], v[90:93]
	v_mfma_f32_16x16x32_bf16 v[82:85], v[134:137], v[206:209], v[82:85]
	v_mfma_f32_16x16x32_bf16 v[74:77], v[142:145], v[206:209], v[74:77]
	v_mfma_f32_16x16x32_bf16 v[114:117], v[146:149], v[174:177], v[114:117]
	v_mfma_f32_16x16x32_bf16 v[106:109], v[164:167], v[174:177], v[106:109]
	v_mfma_f32_16x16x32_bf16 v[102:105], v[146:149], v[182:185], v[102:105]
	v_mfma_f32_16x16x32_bf16 v[94:97], v[164:167], v[182:185], v[94:97]
	v_mfma_f32_16x16x32_bf16 v[86:89], v[146:149], v[190:193], v[86:89]
	v_mfma_f32_16x16x32_bf16 v[78:81], v[164:167], v[190:193], v[78:81]
	v_mfma_f32_16x16x32_bf16 v[70:73], v[146:149], v[202:205], v[70:73]
	v_mfma_f32_16x16x32_bf16 v[66:69], v[164:167], v[202:205], v[66:69]
	v_mfma_f32_16x16x32_bf16 v[114:117], v[160:163], v[178:181], v[114:117]
	v_mfma_f32_16x16x32_bf16 v[106:109], v[168:171], v[178:181], v[106:109]
	v_mfma_f32_16x16x32_bf16 v[102:105], v[160:163], v[186:189], v[102:105]
	v_mfma_f32_16x16x32_bf16 v[94:97], v[168:171], v[186:189], v[94:97]
	v_mfma_f32_16x16x32_bf16 v[86:89], v[160:163], v[198:201], v[86:89]
	v_mfma_f32_16x16x32_bf16 v[78:81], v[168:171], v[198:201], v[78:81]
	v_mfma_f32_16x16x32_bf16 v[70:73], v[160:163], v[206:209], v[70:73]
	v_mfma_f32_16x16x32_bf16 v[66:69], v[168:171], v[206:209], v[66:69]
	s_setprio 0
	s_barrier
	s_add_i32 s28, s63, s36
	v_lshl_add_u64 v[194:195], v[194:195], 0, s[96:97]
	s_mov_b32 m0, s28
	ds_read_b128 v[174:177], v173 offset:49152
	ds_read_b128 v[178:181], v173 offset:50176
	ds_read_b128 v[182:185], v173 offset:51200
	ds_read_b128 v[186:189], v173 offset:52224
	ds_read_b128 v[190:193], v173 offset:53248
	ds_read_b128 v[198:201], v173 offset:54272
	ds_read_b128 v[202:205], v173 offset:55296
	ds_read_b128 v[206:209], v173 offset:56320
	global_load_lds_dwordx4 v[194:195], off
	s_add_i32 m0, s28, 0x2000
	s_add_u32 s24, s24, 0x80080
	v_lshl_add_u64 v[194:195], v[196:197], 0, s[96:97]
	s_addc_u32 s25, s25, 0
	s_add_i32 s28, s66, s36
	global_load_lds_dwordx4 v[194:195], off
	v_lshl_add_u64 v[194:195], s[24:25], 0, v[64:65]
	s_mov_b32 m0, s28
	s_nop 0
	global_load_lds_dwordx4 v[194:195], off
	v_lshl_add_u64 v[194:195], s[24:25], 0, v[150:151]
	s_add_i32 m0, s28, 0x2000
	s_nop 0
	global_load_lds_dwordx4 v[194:195], off
	v_lshl_add_u64 v[194:195], v[210:211], 0, s[96:97]
	s_mov_b32 m0, s48
	s_nop 0
	global_load_lds_dwordx4 v[194:195], off
	v_lshl_add_u64 v[194:195], v[212:213], 0, s[96:97]
	s_mov_b32 m0, s49
	s_nop 0
	global_load_lds_dwordx4 v[194:195], off
	s_waitcnt vmcnt(8)
	s_waitcnt lgkmcnt(0)
	s_barrier
	s_setprio 1
	s_waitcnt lgkmcnt(0)
	v_mfma_f32_16x16x32_bf16 v[60:63], v[130:133], v[174:177], v[60:63]
	v_mfma_f32_16x16x32_bf16 v[56:59], v[138:141], v[174:177], v[56:59]
	v_mfma_f32_16x16x32_bf16 v[48:51], v[130:133], v[182:185], v[48:51]
	v_mfma_f32_16x16x32_bf16 v[40:43], v[138:141], v[182:185], v[40:43]
	v_mfma_f32_16x16x32_bf16 v[32:35], v[130:133], v[190:193], v[32:35]
	v_mfma_f32_16x16x32_bf16 v[24:27], v[138:141], v[190:193], v[24:27]
	v_mfma_f32_16x16x32_bf16 v[16:19], v[130:133], v[202:205], v[16:19]
	v_mfma_f32_16x16x32_bf16 v[8:11], v[138:141], v[202:205], v[8:11]
	v_mfma_f32_16x16x32_bf16 v[60:63], v[134:137], v[178:181], v[60:63]
	v_mfma_f32_16x16x32_bf16 v[56:59], v[142:145], v[178:181], v[56:59]
	v_mfma_f32_16x16x32_bf16 v[48:51], v[134:137], v[186:189], v[48:51]
	v_mfma_f32_16x16x32_bf16 v[40:43], v[142:145], v[186:189], v[40:43]
	v_mfma_f32_16x16x32_bf16 v[32:35], v[134:137], v[198:201], v[32:35]
	v_mfma_f32_16x16x32_bf16 v[24:27], v[142:145], v[198:201], v[24:27]
	v_mfma_f32_16x16x32_bf16 v[16:19], v[134:137], v[206:209], v[16:19]
	v_mfma_f32_16x16x32_bf16 v[8:11], v[142:145], v[206:209], v[8:11]
	v_mfma_f32_16x16x32_bf16 v[52:55], v[146:149], v[174:177], v[52:55]
	v_mfma_f32_16x16x32_bf16 v[44:47], v[164:167], v[174:177], v[44:47]
	v_mfma_f32_16x16x32_bf16 v[36:39], v[146:149], v[182:185], v[36:39]
	v_mfma_f32_16x16x32_bf16 v[28:31], v[164:167], v[182:185], v[28:31]
	v_mfma_f32_16x16x32_bf16 v[20:23], v[146:149], v[190:193], v[20:23]
	v_mfma_f32_16x16x32_bf16 v[12:15], v[164:167], v[190:193], v[12:15]
	v_mfma_f32_16x16x32_bf16 v[4:7], v[146:149], v[202:205], v[4:7]
	v_mfma_f32_16x16x32_bf16 v[0:3], v[164:167], v[202:205], v[0:3]
	v_mfma_f32_16x16x32_bf16 v[52:55], v[160:163], v[178:181], v[52:55]
	v_mfma_f32_16x16x32_bf16 v[44:47], v[168:171], v[178:181], v[44:47]
	v_mfma_f32_16x16x32_bf16 v[36:39], v[160:163], v[186:189], v[36:39]
	v_mfma_f32_16x16x32_bf16 v[28:31], v[168:171], v[186:189], v[28:31]
	v_mfma_f32_16x16x32_bf16 v[20:23], v[160:163], v[198:201], v[20:23]
	v_mfma_f32_16x16x32_bf16 v[12:15], v[168:171], v[198:201], v[12:15]
	v_mfma_f32_16x16x32_bf16 v[4:7], v[160:163], v[206:209], v[4:7]
	v_mfma_f32_16x16x32_bf16 v[0:3], v[168:171], v[206:209], v[0:3]
	s_setprio 0
	s_barrier
	s_add_i32 s62, s62, 2
	s_add_u32 s22, s22, 0x100
	s_addc_u32 s23, s23, 0
	s_add_u32 s58, s58, 0x100
	s_addc_u32 s59, s59, 0
	s_cmp_gt_u32 s62, 29
	s_cbranch_scc0 .LBB0_1628
	s_and_b64 vcc, exec, s[12:13]
	s_cbranch_vccz .LBB0_1631
	s_barrier

.LBB0_1695:
	s_lshl_b32 s26, s35, 7
	s_add_u32 s27, s36, s26
	s_addc_u32 s86, s37, 0
	s_add_i32 s26, s35, 2
	s_lshl_b32 s87, s26, 7
	s_add_u32 s54, s36, s87
	s_addc_u32 s55, s37, 0
	s_and_b64 s[38:39], s[52:53], exec
	s_cselect_b32 s55, s23, s55
	s_cselect_b32 s54, s82, s54
	s_add_u32 s87, s44, s87
	s_addc_u32 s88, s45, 0
	s_and_b64 s[38:39], s[52:53], exec
	s_cselect_b32 s53, s21, s88
	s_cselect_b32 s52, s83, s87
	s_add_i32 s87, 0, 0x10000
	s_add_i32 s88, 0, 0x14000
	v_add_u32_e32 v142, s87, v210
	v_add_u32_e32 v158, s88, v210
	ds_read_b128 v[130:133], v142
	ds_read_b128 v[134:137], v142 offset:1024
	ds_read_b128 v[138:141], v142 offset:2048
	ds_read_b128 v[142:145], v142 offset:3072
	ds_read_b128 v[146:149], v158
	ds_read_b128 v[150:153], v158 offset:1024
	ds_read_b128 v[154:157], v158 offset:2048
	ds_read_b128 v[158:161], v158 offset:3072
	s_add_u32 s38, s27, 0x40080
	s_addc_u32 s39, s86, 0
	v_lshl_add_u64 v[192:193], s[38:39], 0, v[186:187]
	s_add_i32 m0, s63, 0xc000
	ds_read_b128 v[162:165], v211
	ds_read_b128 v[166:169], v211 offset:1024
	ds_read_b128 v[170:173], v211 offset:2048
	ds_read_b128 v[174:177], v211 offset:3072
	ds_read_b128 v[178:181], v211 offset:4096
	ds_read_b128 v[182:185], v211 offset:5120
	ds_read_b128 v[198:201], v211 offset:6144
	ds_read_b128 v[202:205], v211 offset:7168
	global_load_lds_dwordx4 v[192:193], off
	v_lshl_add_u64 v[192:193], s[38:39], 0, v[188:189]
	s_add_i32 m0, s63, 0xe000
	s_nop 0
	global_load_lds_dwordx4 v[192:193], off
	s_waitcnt vmcnt(8)
	s_waitcnt lgkmcnt(0)
	s_barrier
	s_setprio 1
	s_waitcnt lgkmcnt(0)
	v_mfma_f32_16x16x32_bf16 v[126:129], v[130:133], v[162:165], v[126:129]
	v_mfma_f32_16x16x32_bf16 v[122:125], v[138:141], v[162:165], v[122:125]
	v_mfma_f32_16x16x32_bf16 v[110:113], v[130:133], v[170:173], v[110:113]
	v_mfma_f32_16x16x32_bf16 v[106:109], v[138:141], v[170:173], v[106:109]
	v_mfma_f32_16x16x32_bf16 v[94:97], v[130:133], v[178:181], v[94:97]
	v_mfma_f32_16x16x32_bf16 v[90:93], v[138:141], v[178:181], v[90:93]
	v_mfma_f32_16x16x32_bf16 v[78:81], v[130:133], v[198:201], v[78:81]
	v_mfma_f32_16x16x32_bf16 v[74:77], v[138:141], v[198:201], v[74:77]
	v_mfma_f32_16x16x32_bf16 v[126:129], v[134:137], v[166:169], v[126:129]
	v_mfma_f32_16x16x32_bf16 v[122:125], v[142:145], v[166:169], v[122:125]
	v_mfma_f32_16x16x32_bf16 v[110:113], v[134:137], v[174:177], v[110:113]
	v_mfma_f32_16x16x32_bf16 v[106:109], v[142:145], v[174:177], v[106:109]
	v_mfma_f32_16x16x32_bf16 v[94:97], v[134:137], v[182:185], v[94:97]
	v_mfma_f32_16x16x32_bf16 v[90:93], v[142:145], v[182:185], v[90:93]
	v_mfma_f32_16x16x32_bf16 v[78:81], v[134:137], v[202:205], v[78:81]
	v_mfma_f32_16x16x32_bf16 v[74:77], v[142:145], v[202:205], v[74:77]
	v_mfma_f32_16x16x32_bf16 v[118:121], v[146:149], v[162:165], v[118:121]
	v_mfma_f32_16x16x32_bf16 v[114:117], v[154:157], v[162:165], v[114:117]
	v_mfma_f32_16x16x32_bf16 v[102:105], v[146:149], v[170:173], v[102:105]
	v_mfma_f32_16x16x32_bf16 v[98:101], v[154:157], v[170:173], v[98:101]
	v_mfma_f32_16x16x32_bf16 v[86:89], v[146:149], v[178:181], v[86:89]
	v_mfma_f32_16x16x32_bf16 v[82:85], v[154:157], v[178:181], v[82:85]
	v_mfma_f32_16x16x32_bf16 v[70:73], v[146:149], v[198:201], v[70:73]
	v_mfma_f32_16x16x32_bf16 v[66:69], v[154:157], v[198:201], v[66:69]
	v_mfma_f32_16x16x32_bf16 v[118:121], v[150:153], v[166:169], v[118:121]
	v_mfma_f32_16x16x32_bf16 v[114:117], v[158:161], v[166:169], v[114:117]
	v_mfma_f32_16x16x32_bf16 v[102:105], v[150:153], v[174:177], v[102:105]
	v_mfma_f32_16x16x32_bf16 v[98:101], v[158:161], v[174:177], v[98:101]
	v_mfma_f32_16x16x32_bf16 v[86:89], v[150:153], v[182:185], v[86:89]
	v_mfma_f32_16x16x32_bf16 v[82:85], v[158:161], v[182:185], v[82:85]
	v_mfma_f32_16x16x32_bf16 v[70:73], v[150:153], v[202:205], v[70:73]
	v_mfma_f32_16x16x32_bf16 v[66:69], v[158:161], v[202:205], v[66:69]
	s_setprio 0
	s_barrier
	s_add_i32 s27, s87, s9
	v_lshl_add_u64 v[192:193], s[52:53], 0, v[64:65]
	s_mov_b32 m0, s27
	ds_read_b128 v[162:165], v211 offset:16384
	ds_read_b128 v[166:169], v211 offset:17408
	ds_read_b128 v[170:173], v211 offset:18432
	ds_read_b128 v[174:177], v211 offset:19456
	ds_read_b128 v[178:181], v211 offset:20480
	ds_read_b128 v[182:185], v211 offset:21504
	ds_read_b128 v[198:201], v211 offset:22528
	ds_read_b128 v[202:205], v211 offset:23552
	global_load_lds_dwordx4 v[192:193], off
	s_add_i32 m0, s27, 0x2000
	s_add_u32 s38, s52, 0x40000
	v_lshl_add_u64 v[194:195], s[52:53], 0, v[190:191]
	s_addc_u32 s39, s53, 0
	s_add_i32 s27, s88, s9
	global_load_lds_dwordx4 v[194:195], off
	v_lshl_add_u64 v[196:197], s[38:39], 0, v[64:65]
	s_mov_b32 m0, s27
	v_lshl_add_u64 v[206:207], s[54:55], 0, v[188:189]
	global_load_lds_dwordx4 v[196:197], off
	v_lshl_add_u64 v[196:197], s[38:39], 0, v[190:191]
	s_add_i32 m0, s27, 0x2000
	s_nop 0
	global_load_lds_dwordx4 v[196:197], off
	v_lshl_add_u64 v[196:197], s[54:55], 0, v[186:187]
	s_mov_b32 m0, s63
	s_nop 0
	global_load_lds_dwordx4 v[196:197], off
	s_mov_b32 m0, s66
	s_nop 0
	global_load_lds_dwordx4 v[206:207], off
	s_waitcnt vmcnt(8)
	s_waitcnt lgkmcnt(0)
	s_barrier
	s_setprio 1
	s_waitcnt lgkmcnt(0)
	v_mfma_f32_16x16x32_bf16 v[60:63], v[130:133], v[162:165], v[60:63]
	v_mfma_f32_16x16x32_bf16 v[56:59], v[138:141], v[162:165], v[56:59]
	v_mfma_f32_16x16x32_bf16 v[44:47], v[130:133], v[170:173], v[44:47]
	v_mfma_f32_16x16x32_bf16 v[40:43], v[138:141], v[170:173], v[40:43]
	v_mfma_f32_16x16x32_bf16 v[28:31], v[130:133], v[178:181], v[28:31]
	v_mfma_f32_16x16x32_bf16 v[24:27], v[138:141], v[178:181], v[24:27]
	v_mfma_f32_16x16x32_bf16 v[12:15], v[130:133], v[198:201], v[12:15]
	v_mfma_f32_16x16x32_bf16 v[8:11], v[138:141], v[198:201], v[8:11]
	v_mfma_f32_16x16x32_bf16 v[60:63], v[134:137], v[166:169], v[60:63]
	v_mfma_f32_16x16x32_bf16 v[56:59], v[142:145], v[166:169], v[56:59]
	v_mfma_f32_16x16x32_bf16 v[44:47], v[134:137], v[174:177], v[44:47]
	v_mfma_f32_16x16x32_bf16 v[40:43], v[142:145], v[174:177], v[40:43]
	v_mfma_f32_16x16x32_bf16 v[28:31], v[134:137], v[182:185], v[28:31]
	v_mfma_f32_16x16x32_bf16 v[24:27], v[142:145], v[182:185], v[24:27]
	v_mfma_f32_16x16x32_bf16 v[12:15], v[134:137], v[202:205], v[12:15]
	v_mfma_f32_16x16x32_bf16 v[8:11], v[142:145], v[202:205], v[8:11]
	v_mfma_f32_16x16x32_bf16 v[52:55], v[146:149], v[162:165], v[52:55]
	v_mfma_f32_16x16x32_bf16 v[48:51], v[154:157], v[162:165], v[48:51]
	v_mfma_f32_16x16x32_bf16 v[36:39], v[146:149], v[170:173], v[36:39]
	v_mfma_f32_16x16x32_bf16 v[32:35], v[154:157], v[170:173], v[32:35]
	v_mfma_f32_16x16x32_bf16 v[20:23], v[146:149], v[178:181], v[20:23]
	v_mfma_f32_16x16x32_bf16 v[16:19], v[154:157], v[178:181], v[16:19]
	v_mfma_f32_16x16x32_bf16 v[4:7], v[146:149], v[198:201], v[4:7]
	v_mfma_f32_16x16x32_bf16 v[0:3], v[154:157], v[198:201], v[0:3]
	v_mfma_f32_16x16x32_bf16 v[52:55], v[150:153], v[166:169], v[52:55]
	v_mfma_f32_16x16x32_bf16 v[48:51], v[158:161], v[166:169], v[48:51]
	v_mfma_f32_16x16x32_bf16 v[36:39], v[150:153], v[174:177], v[36:39]
	v_mfma_f32_16x16x32_bf16 v[32:35], v[158:161], v[174:177], v[32:35]
	v_mfma_f32_16x16x32_bf16 v[20:23], v[150:153], v[182:185], v[20:23]
	v_mfma_f32_16x16x32_bf16 v[16:19], v[158:161], v[182:185], v[16:19]
	v_mfma_f32_16x16x32_bf16 v[4:7], v[150:153], v[202:205], v[4:7]
	v_mfma_f32_16x16x32_bf16 v[0:3], v[158:161], v[202:205], v[0:3]
	s_setprio 0
	s_barrier
	s_add_i32 s27, 0, 0x18000
	s_add_i32 s86, 0, 0x1c000
	v_add_u32_e32 v142, s27, v210
	v_add_u32_e32 v158, s86, v210
	ds_read_b128 v[130:133], v142
	ds_read_b128 v[134:137], v142 offset:1024
	ds_read_b128 v[138:141], v142 offset:2048
	ds_read_b128 v[142:145], v142 offset:3072
	ds_read_b128 v[146:149], v158
	ds_read_b128 v[150:153], v158 offset:1024
	ds_read_b128 v[154:157], v158 offset:2048
	ds_read_b128 v[158:161], v158 offset:3072
	s_add_u32 s38, s54, 0x40000
	s_addc_u32 s39, s55, 0
	s_mov_b32 m0, s69
	v_lshl_add_u64 v[208:209], s[38:39], 0, v[186:187]
	ds_read_b128 v[162:165], v211 offset:32768
	ds_read_b128 v[166:169], v211 offset:33792
	ds_read_b128 v[170:173], v211 offset:34816
	ds_read_b128 v[174:177], v211 offset:35840
	ds_read_b128 v[178:181], v211 offset:36864
	ds_read_b128 v[182:185], v211 offset:37888
	ds_read_b128 v[198:201], v211 offset:38912
	ds_read_b128 v[202:205], v211 offset:39936
	global_load_lds_dwordx4 v[208:209], off
	v_lshl_add_u64 v[208:209], s[38:39], 0, v[188:189]
	s_mov_b32 m0, s70
	s_nop 0
	global_load_lds_dwordx4 v[208:209], off
	s_waitcnt vmcnt(8)
	s_waitcnt lgkmcnt(0)
	s_barrier
	s_setprio 1
	s_waitcnt lgkmcnt(0)
	v_mfma_f32_16x16x32_bf16 v[126:129], v[130:133], v[162:165], v[126:129]
	v_mfma_f32_16x16x32_bf16 v[122:125], v[138:141], v[162:165], v[122:125]
	v_mfma_f32_16x16x32_bf16 v[110:113], v[130:133], v[170:173], v[110:113]
	v_mfma_f32_16x16x32_bf16 v[106:109], v[138:141], v[170:173], v[106:109]
	v_mfma_f32_16x16x32_bf16 v[94:97], v[130:133], v[178:181], v[94:97]
	v_mfma_f32_16x16x32_bf16 v[90:93], v[138:141], v[178:181], v[90:93]
	v_mfma_f32_16x16x32_bf16 v[78:81], v[130:133], v[198:201], v[78:81]
	v_mfma_f32_16x16x32_bf16 v[74:77], v[138:141], v[198:201], v[74:77]
	v_mfma_f32_16x16x32_bf16 v[126:129], v[134:137], v[166:169], v[126:129]
	v_mfma_f32_16x16x32_bf16 v[122:125], v[142:145], v[166:169], v[122:125]
	v_mfma_f32_16x16x32_bf16 v[110:113], v[134:137], v[174:177], v[110:113]
	v_mfma_f32_16x16x32_bf16 v[106:109], v[142:145], v[174:177], v[106:109]
	v_mfma_f32_16x16x32_bf16 v[94:97], v[134:137], v[182:185], v[94:97]
	v_mfma_f32_16x16x32_bf16 v[90:93], v[142:145], v[182:185], v[90:93]
	v_mfma_f32_16x16x32_bf16 v[78:81], v[134:137], v[202:205], v[78:81]
	v_mfma_f32_16x16x32_bf16 v[74:77], v[142:145], v[202:205], v[74:77]
	v_mfma_f32_16x16x32_bf16 v[118:121], v[146:149], v[162:165], v[118:121]
	v_mfma_f32_16x16x32_bf16 v[114:117], v[154:157], v[162:165], v[114:117]
	v_mfma_f32_16x16x32_bf16 v[102:105], v[146:149], v[170:173], v[102:105]
	v_mfma_f32_16x16x32_bf16 v[98:101], v[154:157], v[170:173], v[98:101]
	v_mfma_f32_16x16x32_bf16 v[86:89], v[146:149], v[178:181], v[86:89]
	v_mfma_f32_16x16x32_bf16 v[82:85], v[154:157], v[178:181], v[82:85]
	v_mfma_f32_16x16x32_bf16 v[70:73], v[146:149], v[198:201], v[70:73]
	v_mfma_f32_16x16x32_bf16 v[66:69], v[154:157], v[198:201], v[66:69]
	v_mfma_f32_16x16x32_bf16 v[118:121], v[150:153], v[166:169], v[118:121]
	v_mfma_f32_16x16x32_bf16 v[114:117], v[158:161], v[166:169], v[114:117]
	v_mfma_f32_16x16x32_bf16 v[102:105], v[150:153], v[174:177], v[102:105]
	v_mfma_f32_16x16x32_bf16 v[98:101], v[158:161], v[174:177], v[98:101]
	v_mfma_f32_16x16x32_bf16 v[86:89], v[150:153], v[182:185], v[86:89]
	v_mfma_f32_16x16x32_bf16 v[82:85], v[158:161], v[182:185], v[82:85]
	v_mfma_f32_16x16x32_bf16 v[70:73], v[150:153], v[202:205], v[70:73]
	v_mfma_f32_16x16x32_bf16 v[66:69], v[158:161], v[202:205], v[66:69]
	s_setprio 0
	s_barrier
	s_add_i32 s27, s27, s9
	v_lshl_add_u64 v[192:193], v[192:193], 0, s[96:97]
	s_mov_b32 m0, s27
	ds_read_b128 v[162:165], v211 offset:49152
	ds_read_b128 v[166:169], v211 offset:50176
	ds_read_b128 v[170:173], v211 offset:51200
	ds_read_b128 v[174:177], v211 offset:52224
	ds_read_b128 v[178:181], v211 offset:53248
	ds_read_b128 v[182:185], v211 offset:54272
	ds_read_b128 v[198:201], v211 offset:55296
	ds_read_b128 v[202:205], v211 offset:56320
	global_load_lds_dwordx4 v[192:193], off
	s_add_i32 m0, s27, 0x2000
	s_add_u32 s38, s52, 0x40080
	v_lshl_add_u64 v[192:193], v[194:195], 0, s[96:97]
	s_addc_u32 s39, s53, 0
	s_add_i32 s27, s86, s9
	global_load_lds_dwordx4 v[192:193], off
	v_lshl_add_u64 v[192:193], s[38:39], 0, v[64:65]
	s_mov_b32 m0, s27
	s_nop 0
	global_load_lds_dwordx4 v[192:193], off
	v_lshl_add_u64 v[192:193], s[38:39], 0, v[190:191]
	s_add_i32 m0, s27, 0x2000
	s_nop 0
	global_load_lds_dwordx4 v[192:193], off
	v_lshl_add_u64 v[192:193], v[196:197], 0, s[96:97]
	s_mov_b32 m0, s77
	s_nop 0
	global_load_lds_dwordx4 v[192:193], off
	v_lshl_add_u64 v[192:193], v[206:207], 0, s[96:97]
	s_mov_b32 m0, s78
	s_nop 0
	global_load_lds_dwordx4 v[192:193], off
	s_waitcnt vmcnt(8)
	s_waitcnt lgkmcnt(0)
	s_barrier
	s_setprio 1
	s_waitcnt lgkmcnt(0)
	v_mfma_f32_16x16x32_bf16 v[60:63], v[130:133], v[162:165], v[60:63]
	v_mfma_f32_16x16x32_bf16 v[56:59], v[138:141], v[162:165], v[56:59]
	v_mfma_f32_16x16x32_bf16 v[44:47], v[130:133], v[170:173], v[44:47]
	v_mfma_f32_16x16x32_bf16 v[40:43], v[138:141], v[170:173], v[40:43]
	v_mfma_f32_16x16x32_bf16 v[28:31], v[130:133], v[178:181], v[28:31]
	v_mfma_f32_16x16x32_bf16 v[24:27], v[138:141], v[178:181], v[24:27]
	v_mfma_f32_16x16x32_bf16 v[12:15], v[130:133], v[198:201], v[12:15]
	v_mfma_f32_16x16x32_bf16 v[8:11], v[138:141], v[198:201], v[8:11]
	v_mfma_f32_16x16x32_bf16 v[60:63], v[134:137], v[166:169], v[60:63]
	v_mfma_f32_16x16x32_bf16 v[56:59], v[142:145], v[166:169], v[56:59]
	v_mfma_f32_16x16x32_bf16 v[44:47], v[134:137], v[174:177], v[44:47]
	v_mfma_f32_16x16x32_bf16 v[40:43], v[142:145], v[174:177], v[40:43]
	v_mfma_f32_16x16x32_bf16 v[28:31], v[134:137], v[182:185], v[28:31]
	v_mfma_f32_16x16x32_bf16 v[24:27], v[142:145], v[182:185], v[24:27]
	v_mfma_f32_16x16x32_bf16 v[12:15], v[134:137], v[202:205], v[12:15]
	v_mfma_f32_16x16x32_bf16 v[8:11], v[142:145], v[202:205], v[8:11]
	v_mfma_f32_16x16x32_bf16 v[52:55], v[146:149], v[162:165], v[52:55]
	v_mfma_f32_16x16x32_bf16 v[48:51], v[154:157], v[162:165], v[48:51]
	v_mfma_f32_16x16x32_bf16 v[36:39], v[146:149], v[170:173], v[36:39]
	v_mfma_f32_16x16x32_bf16 v[32:35], v[154:157], v[170:173], v[32:35]
	v_mfma_f32_16x16x32_bf16 v[20:23], v[146:149], v[178:181], v[20:23]
	v_mfma_f32_16x16x32_bf16 v[16:19], v[154:157], v[178:181], v[16:19]
	v_mfma_f32_16x16x32_bf16 v[4:7], v[146:149], v[198:201], v[4:7]
	v_mfma_f32_16x16x32_bf16 v[0:3], v[154:157], v[198:201], v[0:3]
	v_mfma_f32_16x16x32_bf16 v[52:55], v[150:153], v[166:169], v[52:55]
	v_mfma_f32_16x16x32_bf16 v[48:51], v[158:161], v[166:169], v[48:51]
	v_mfma_f32_16x16x32_bf16 v[36:39], v[150:153], v[174:177], v[36:39]
	v_mfma_f32_16x16x32_bf16 v[32:35], v[158:161], v[174:177], v[32:35]
	v_mfma_f32_16x16x32_bf16 v[20:23], v[150:153], v[182:185], v[20:23]
	v_mfma_f32_16x16x32_bf16 v[16:19], v[158:161], v[182:185], v[16:19]
	v_mfma_f32_16x16x32_bf16 v[4:7], v[150:153], v[202:205], v[4:7]
	v_mfma_f32_16x16x32_bf16 v[0:3], v[158:161], v[202:205], v[0:3]
	s_setprio 0
	s_barrier
	s_cmp_gt_u32 s35, 13
	s_mov_b32 s35, s26
	s_cbranch_scc1 .LBB0_1711

.LBB0_1757:
	s_lshl_b32 s26, s87, 7
	s_add_u32 s27, s36, s26
	s_addc_u32 s88, s37, 0
	s_add_i32 s26, s87, 2
	s_lshl_b32 s89, s26, 7
	s_add_u32 s54, s36, s89
	s_addc_u32 s55, s37, 0
	s_and_b64 s[38:39], s[52:53], exec
	s_cselect_b32 s55, s23, s55
	s_cselect_b32 s54, s35, s54
	s_add_u32 s89, s40, s89
	s_addc_u32 s90, s41, 0
	s_and_b64 s[38:39], s[52:53], exec
	s_cselect_b32 s53, s21, s90
	s_cselect_b32 s52, s86, s89
	s_add_i32 s89, 0, 0x10000
	s_add_i32 s90, 0, 0x14000
	v_add_u32_e32 v142, s89, v154
	v_add_u32_e32 v152, s90, v154
	ds_read_b128 v[130:133], v142
	ds_read_b128 v[134:137], v142 offset:1024
	ds_read_b128 v[138:141], v142 offset:2048
	ds_read_b128 v[142:145], v142 offset:3072
	ds_read_b128 v[156:159], v152
	ds_read_b128 v[160:163], v152 offset:1024
	ds_read_b128 v[164:167], v152 offset:2048
	ds_read_b128 v[168:171], v152 offset:3072
	s_add_u32 s38, s27, 0x40080
	s_addc_u32 s39, s88, 0
	v_lshl_add_u64 v[152:153], s[38:39], 0, v[146:147]
	s_add_i32 m0, s63, 0xc000
	ds_read_b128 v[172:175], v155
	ds_read_b128 v[176:179], v155 offset:1024
	ds_read_b128 v[180:183], v155 offset:2048
	ds_read_b128 v[184:187], v155 offset:3072
	ds_read_b128 v[188:191], v155 offset:4096
	ds_read_b128 v[198:201], v155 offset:5120
	ds_read_b128 v[202:205], v155 offset:6144
	ds_read_b128 v[206:209], v155 offset:7168
	global_load_lds_dwordx4 v[152:153], off
	v_lshl_add_u64 v[152:153], s[38:39], 0, v[148:149]
	s_add_i32 m0, s63, 0xe000
	s_nop 0
	global_load_lds_dwordx4 v[152:153], off
	s_waitcnt vmcnt(8)
	s_waitcnt lgkmcnt(0)
	s_barrier
	s_setprio 1
	s_waitcnt lgkmcnt(0)
	v_mfma_f32_16x16x32_bf16 v[126:129], v[130:133], v[172:175], v[126:129]
	v_mfma_f32_16x16x32_bf16 v[122:125], v[138:141], v[172:175], v[122:125]
	v_mfma_f32_16x16x32_bf16 v[118:121], v[130:133], v[180:183], v[118:121]
	v_mfma_f32_16x16x32_bf16 v[110:113], v[138:141], v[180:183], v[110:113]
	v_mfma_f32_16x16x32_bf16 v[98:101], v[130:133], v[188:191], v[98:101]
	v_mfma_f32_16x16x32_bf16 v[90:93], v[138:141], v[188:191], v[90:93]
	v_mfma_f32_16x16x32_bf16 v[82:85], v[130:133], v[202:205], v[82:85]
	v_mfma_f32_16x16x32_bf16 v[74:77], v[138:141], v[202:205], v[74:77]
	v_mfma_f32_16x16x32_bf16 v[126:129], v[134:137], v[176:179], v[126:129]
	v_mfma_f32_16x16x32_bf16 v[122:125], v[142:145], v[176:179], v[122:125]
	v_mfma_f32_16x16x32_bf16 v[118:121], v[134:137], v[184:187], v[118:121]
	v_mfma_f32_16x16x32_bf16 v[110:113], v[142:145], v[184:187], v[110:113]
	v_mfma_f32_16x16x32_bf16 v[98:101], v[134:137], v[198:201], v[98:101]
	v_mfma_f32_16x16x32_bf16 v[90:93], v[142:145], v[198:201], v[90:93]
	v_mfma_f32_16x16x32_bf16 v[82:85], v[134:137], v[206:209], v[82:85]
	v_mfma_f32_16x16x32_bf16 v[74:77], v[142:145], v[206:209], v[74:77]
	v_mfma_f32_16x16x32_bf16 v[114:117], v[156:159], v[172:175], v[114:117]
	v_mfma_f32_16x16x32_bf16 v[106:109], v[164:167], v[172:175], v[106:109]
	v_mfma_f32_16x16x32_bf16 v[102:105], v[156:159], v[180:183], v[102:105]
	v_mfma_f32_16x16x32_bf16 v[94:97], v[164:167], v[180:183], v[94:97]
	v_mfma_f32_16x16x32_bf16 v[86:89], v[156:159], v[188:191], v[86:89]
	v_mfma_f32_16x16x32_bf16 v[78:81], v[164:167], v[188:191], v[78:81]
	v_mfma_f32_16x16x32_bf16 v[70:73], v[156:159], v[202:205], v[70:73]
	v_mfma_f32_16x16x32_bf16 v[66:69], v[164:167], v[202:205], v[66:69]
	v_mfma_f32_16x16x32_bf16 v[114:117], v[160:163], v[176:179], v[114:117]
	v_mfma_f32_16x16x32_bf16 v[106:109], v[168:171], v[176:179], v[106:109]
	v_mfma_f32_16x16x32_bf16 v[102:105], v[160:163], v[184:187], v[102:105]
	v_mfma_f32_16x16x32_bf16 v[94:97], v[168:171], v[184:187], v[94:97]
	v_mfma_f32_16x16x32_bf16 v[86:89], v[160:163], v[198:201], v[86:89]
	v_mfma_f32_16x16x32_bf16 v[78:81], v[168:171], v[198:201], v[78:81]
	v_mfma_f32_16x16x32_bf16 v[70:73], v[160:163], v[206:209], v[70:73]
	v_mfma_f32_16x16x32_bf16 v[66:69], v[168:171], v[206:209], v[66:69]
	s_setprio 0
	s_barrier
	s_add_i32 s27, s89, s13
	v_lshl_add_u64 v[152:153], s[52:53], 0, v[64:65]
	s_mov_b32 m0, s27
	ds_read_b128 v[172:175], v155 offset:16384
	ds_read_b128 v[176:179], v155 offset:17408
	ds_read_b128 v[180:183], v155 offset:18432
	ds_read_b128 v[184:187], v155 offset:19456
	ds_read_b128 v[188:191], v155 offset:20480
	ds_read_b128 v[198:201], v155 offset:21504
	ds_read_b128 v[202:205], v155 offset:22528
	ds_read_b128 v[206:209], v155 offset:23552
	global_load_lds_dwordx4 v[152:153], off
	s_add_i32 m0, s27, 0x2000
	s_add_u32 s38, s52, 0x40000
	v_lshl_add_u64 v[192:193], s[52:53], 0, v[150:151]
	s_addc_u32 s39, s53, 0
	s_add_i32 s27, s90, s13
	global_load_lds_dwordx4 v[192:193], off
	v_lshl_add_u64 v[194:195], s[38:39], 0, v[64:65]
	s_mov_b32 m0, s27
	v_lshl_add_u64 v[196:197], s[54:55], 0, v[148:149]
	global_load_lds_dwordx4 v[194:195], off
	v_lshl_add_u64 v[194:195], s[38:39], 0, v[150:151]
	s_add_i32 m0, s27, 0x2000
	s_nop 0
	global_load_lds_dwordx4 v[194:195], off
	v_lshl_add_u64 v[194:195], s[54:55], 0, v[146:147]
	s_mov_b32 m0, s63
	s_nop 0
	global_load_lds_dwordx4 v[194:195], off
	s_mov_b32 m0, s66
	s_nop 0
	global_load_lds_dwordx4 v[196:197], off
	s_waitcnt vmcnt(8)
	s_waitcnt lgkmcnt(0)
	s_barrier
	s_setprio 1
	s_waitcnt lgkmcnt(0)
	v_mfma_f32_16x16x32_bf16 v[60:63], v[130:133], v[172:175], v[60:63]
	v_mfma_f32_16x16x32_bf16 v[56:59], v[138:141], v[172:175], v[56:59]
	v_mfma_f32_16x16x32_bf16 v[48:51], v[130:133], v[180:183], v[48:51]
	v_mfma_f32_16x16x32_bf16 v[40:43], v[138:141], v[180:183], v[40:43]
	v_mfma_f32_16x16x32_bf16 v[32:35], v[130:133], v[188:191], v[32:35]
	v_mfma_f32_16x16x32_bf16 v[24:27], v[138:141], v[188:191], v[24:27]
	v_mfma_f32_16x16x32_bf16 v[16:19], v[130:133], v[202:205], v[16:19]
	v_mfma_f32_16x16x32_bf16 v[8:11], v[138:141], v[202:205], v[8:11]
	v_mfma_f32_16x16x32_bf16 v[60:63], v[134:137], v[176:179], v[60:63]
	v_mfma_f32_16x16x32_bf16 v[56:59], v[142:145], v[176:179], v[56:59]
	v_mfma_f32_16x16x32_bf16 v[48:51], v[134:137], v[184:187], v[48:51]
	v_mfma_f32_16x16x32_bf16 v[40:43], v[142:145], v[184:187], v[40:43]
	v_mfma_f32_16x16x32_bf16 v[32:35], v[134:137], v[198:201], v[32:35]
	v_mfma_f32_16x16x32_bf16 v[24:27], v[142:145], v[198:201], v[24:27]
	v_mfma_f32_16x16x32_bf16 v[16:19], v[134:137], v[206:209], v[16:19]
	v_mfma_f32_16x16x32_bf16 v[8:11], v[142:145], v[206:209], v[8:11]
	v_mfma_f32_16x16x32_bf16 v[52:55], v[156:159], v[172:175], v[52:55]
	v_mfma_f32_16x16x32_bf16 v[44:47], v[164:167], v[172:175], v[44:47]
	v_mfma_f32_16x16x32_bf16 v[36:39], v[156:159], v[180:183], v[36:39]
	v_mfma_f32_16x16x32_bf16 v[28:31], v[164:167], v[180:183], v[28:31]
	v_mfma_f32_16x16x32_bf16 v[20:23], v[156:159], v[188:191], v[20:23]
	v_mfma_f32_16x16x32_bf16 v[12:15], v[164:167], v[188:191], v[12:15]
	v_mfma_f32_16x16x32_bf16 v[4:7], v[156:159], v[202:205], v[4:7]
	v_mfma_f32_16x16x32_bf16 v[0:3], v[164:167], v[202:205], v[0:3]
	v_mfma_f32_16x16x32_bf16 v[52:55], v[160:163], v[176:179], v[52:55]
	v_mfma_f32_16x16x32_bf16 v[44:47], v[168:171], v[176:179], v[44:47]
	v_mfma_f32_16x16x32_bf16 v[36:39], v[160:163], v[184:187], v[36:39]
	v_mfma_f32_16x16x32_bf16 v[28:31], v[168:171], v[184:187], v[28:31]
	v_mfma_f32_16x16x32_bf16 v[20:23], v[160:163], v[198:201], v[20:23]
	v_mfma_f32_16x16x32_bf16 v[12:15], v[168:171], v[198:201], v[12:15]
	v_mfma_f32_16x16x32_bf16 v[4:7], v[160:163], v[206:209], v[4:7]
	v_mfma_f32_16x16x32_bf16 v[0:3], v[168:171], v[206:209], v[0:3]
	s_setprio 0
	s_barrier
	s_add_i32 s27, 0, 0x18000
	s_add_i32 s88, 0, 0x1c000
	v_add_u32_e32 v142, s27, v154
	v_add_u32_e32 v168, s88, v154
	ds_read_b128 v[130:133], v142
	ds_read_b128 v[134:137], v142 offset:1024
	ds_read_b128 v[138:141], v142 offset:2048
	ds_read_b128 v[142:145], v142 offset:3072
	ds_read_b128 v[156:159], v168
	ds_read_b128 v[160:163], v168 offset:1024
	ds_read_b128 v[164:167], v168 offset:2048
	ds_read_b128 v[168:171], v168 offset:3072
	s_add_u32 s38, s54, 0x40000
	s_addc_u32 s39, s55, 0
	s_mov_b32 m0, s69
	v_lshl_add_u64 v[210:211], s[38:39], 0, v[146:147]
	ds_read_b128 v[172:175], v155 offset:32768
	ds_read_b128 v[176:179], v155 offset:33792
	ds_read_b128 v[180:183], v155 offset:34816
	ds_read_b128 v[184:187], v155 offset:35840
	ds_read_b128 v[188:191], v155 offset:36864
	ds_read_b128 v[198:201], v155 offset:37888
	ds_read_b128 v[202:205], v155 offset:38912
	ds_read_b128 v[206:209], v155 offset:39936
	global_load_lds_dwordx4 v[210:211], off
	v_lshl_add_u64 v[210:211], s[38:39], 0, v[148:149]
	s_mov_b32 m0, s70
	s_nop 0
	global_load_lds_dwordx4 v[210:211], off
	s_waitcnt vmcnt(8)
	s_waitcnt lgkmcnt(0)
	s_barrier
	s_setprio 1
	s_waitcnt lgkmcnt(0)
	v_mfma_f32_16x16x32_bf16 v[126:129], v[130:133], v[172:175], v[126:129]
	v_mfma_f32_16x16x32_bf16 v[122:125], v[138:141], v[172:175], v[122:125]
	v_mfma_f32_16x16x32_bf16 v[118:121], v[130:133], v[180:183], v[118:121]
	v_mfma_f32_16x16x32_bf16 v[110:113], v[138:141], v[180:183], v[110:113]
	v_mfma_f32_16x16x32_bf16 v[98:101], v[130:133], v[188:191], v[98:101]
	v_mfma_f32_16x16x32_bf16 v[90:93], v[138:141], v[188:191], v[90:93]
	v_mfma_f32_16x16x32_bf16 v[82:85], v[130:133], v[202:205], v[82:85]
	v_mfma_f32_16x16x32_bf16 v[74:77], v[138:141], v[202:205], v[74:77]
	v_mfma_f32_16x16x32_bf16 v[126:129], v[134:137], v[176:179], v[126:129]
	v_mfma_f32_16x16x32_bf16 v[122:125], v[142:145], v[176:179], v[122:125]
	v_mfma_f32_16x16x32_bf16 v[118:121], v[134:137], v[184:187], v[118:121]
	v_mfma_f32_16x16x32_bf16 v[110:113], v[142:145], v[184:187], v[110:113]
	v_mfma_f32_16x16x32_bf16 v[98:101], v[134:137], v[198:201], v[98:101]
	v_mfma_f32_16x16x32_bf16 v[90:93], v[142:145], v[198:201], v[90:93]
	v_mfma_f32_16x16x32_bf16 v[82:85], v[134:137], v[206:209], v[82:85]
	v_mfma_f32_16x16x32_bf16 v[74:77], v[142:145], v[206:209], v[74:77]
	v_mfma_f32_16x16x32_bf16 v[114:117], v[156:159], v[172:175], v[114:117]
	v_mfma_f32_16x16x32_bf16 v[106:109], v[164:167], v[172:175], v[106:109]
	v_mfma_f32_16x16x32_bf16 v[102:105], v[156:159], v[180:183], v[102:105]
	v_mfma_f32_16x16x32_bf16 v[94:97], v[164:167], v[180:183], v[94:97]
	v_mfma_f32_16x16x32_bf16 v[86:89], v[156:159], v[188:191], v[86:89]
	v_mfma_f32_16x16x32_bf16 v[78:81], v[164:167], v[188:191], v[78:81]
	v_mfma_f32_16x16x32_bf16 v[70:73], v[156:159], v[202:205], v[70:73]
	v_mfma_f32_16x16x32_bf16 v[66:69], v[164:167], v[202:205], v[66:69]
	v_mfma_f32_16x16x32_bf16 v[114:117], v[160:163], v[176:179], v[114:117]
	v_mfma_f32_16x16x32_bf16 v[106:109], v[168:171], v[176:179], v[106:109]
	v_mfma_f32_16x16x32_bf16 v[102:105], v[160:163], v[184:187], v[102:105]
	v_mfma_f32_16x16x32_bf16 v[94:97], v[168:171], v[184:187], v[94:97]
	v_mfma_f32_16x16x32_bf16 v[86:89], v[160:163], v[198:201], v[86:89]
	v_mfma_f32_16x16x32_bf16 v[78:81], v[168:171], v[198:201], v[78:81]
	v_mfma_f32_16x16x32_bf16 v[70:73], v[160:163], v[206:209], v[70:73]
	v_mfma_f32_16x16x32_bf16 v[66:69], v[168:171], v[206:209], v[66:69]
	s_setprio 0
	s_barrier
	s_add_i32 s27, s27, s13
	v_lshl_add_u64 v[152:153], v[152:153], 0, s[96:97]
	s_mov_b32 m0, s27
	ds_read_b128 v[172:175], v155 offset:49152
	ds_read_b128 v[176:179], v155 offset:50176
	ds_read_b128 v[180:183], v155 offset:51200
	ds_read_b128 v[184:187], v155 offset:52224
	ds_read_b128 v[188:191], v155 offset:53248
	ds_read_b128 v[198:201], v155 offset:54272
	ds_read_b128 v[202:205], v155 offset:55296
	ds_read_b128 v[206:209], v155 offset:56320
	global_load_lds_dwordx4 v[152:153], off
	s_add_i32 m0, s27, 0x2000
	s_add_u32 s38, s52, 0x40080
	v_lshl_add_u64 v[152:153], v[192:193], 0, s[96:97]
	s_addc_u32 s39, s53, 0
	s_add_i32 s27, s88, s13
	global_load_lds_dwordx4 v[152:153], off
	v_lshl_add_u64 v[152:153], s[38:39], 0, v[64:65]
	s_mov_b32 m0, s27
	s_nop 0
	global_load_lds_dwordx4 v[152:153], off
	v_lshl_add_u64 v[152:153], s[38:39], 0, v[150:151]
	s_add_i32 m0, s27, 0x2000
	s_nop 0
	global_load_lds_dwordx4 v[152:153], off
	v_lshl_add_u64 v[152:153], v[194:195], 0, s[96:97]
	s_mov_b32 m0, s79
	s_nop 0
	global_load_lds_dwordx4 v[152:153], off
	v_lshl_add_u64 v[152:153], v[196:197], 0, s[96:97]
	s_mov_b32 m0, s82
	s_nop 0
	global_load_lds_dwordx4 v[152:153], off
	s_waitcnt vmcnt(8)
	s_waitcnt lgkmcnt(0)
	s_barrier
	s_setprio 1
	s_waitcnt lgkmcnt(0)
	v_mfma_f32_16x16x32_bf16 v[60:63], v[130:133], v[172:175], v[60:63]
	v_mfma_f32_16x16x32_bf16 v[56:59], v[138:141], v[172:175], v[56:59]
	v_mfma_f32_16x16x32_bf16 v[48:51], v[130:133], v[180:183], v[48:51]
	v_mfma_f32_16x16x32_bf16 v[40:43], v[138:141], v[180:183], v[40:43]
	v_mfma_f32_16x16x32_bf16 v[32:35], v[130:133], v[188:191], v[32:35]
	v_mfma_f32_16x16x32_bf16 v[24:27], v[138:141], v[188:191], v[24:27]
	v_mfma_f32_16x16x32_bf16 v[16:19], v[130:133], v[202:205], v[16:19]
	v_mfma_f32_16x16x32_bf16 v[8:11], v[138:141], v[202:205], v[8:11]
	v_mfma_f32_16x16x32_bf16 v[60:63], v[134:137], v[176:179], v[60:63]
	v_mfma_f32_16x16x32_bf16 v[56:59], v[142:145], v[176:179], v[56:59]
	v_mfma_f32_16x16x32_bf16 v[48:51], v[134:137], v[184:187], v[48:51]
	v_mfma_f32_16x16x32_bf16 v[40:43], v[142:145], v[184:187], v[40:43]
	v_mfma_f32_16x16x32_bf16 v[32:35], v[134:137], v[198:201], v[32:35]
	v_mfma_f32_16x16x32_bf16 v[24:27], v[142:145], v[198:201], v[24:27]
	v_mfma_f32_16x16x32_bf16 v[16:19], v[134:137], v[206:209], v[16:19]
	v_mfma_f32_16x16x32_bf16 v[8:11], v[142:145], v[206:209], v[8:11]
	v_mfma_f32_16x16x32_bf16 v[52:55], v[156:159], v[172:175], v[52:55]
	v_mfma_f32_16x16x32_bf16 v[44:47], v[164:167], v[172:175], v[44:47]
	v_mfma_f32_16x16x32_bf16 v[36:39], v[156:159], v[180:183], v[36:39]
	v_mfma_f32_16x16x32_bf16 v[28:31], v[164:167], v[180:183], v[28:31]
	v_mfma_f32_16x16x32_bf16 v[20:23], v[156:159], v[188:191], v[20:23]
	v_mfma_f32_16x16x32_bf16 v[12:15], v[164:167], v[188:191], v[12:15]
	v_mfma_f32_16x16x32_bf16 v[4:7], v[156:159], v[202:205], v[4:7]
	v_mfma_f32_16x16x32_bf16 v[0:3], v[164:167], v[202:205], v[0:3]
	v_mfma_f32_16x16x32_bf16 v[52:55], v[160:163], v[176:179], v[52:55]
	v_mfma_f32_16x16x32_bf16 v[44:47], v[168:171], v[176:179], v[44:47]
	v_mfma_f32_16x16x32_bf16 v[36:39], v[160:163], v[184:187], v[36:39]
	v_mfma_f32_16x16x32_bf16 v[28:31], v[168:171], v[184:187], v[28:31]
	v_mfma_f32_16x16x32_bf16 v[20:23], v[160:163], v[198:201], v[20:23]
	v_mfma_f32_16x16x32_bf16 v[12:15], v[168:171], v[198:201], v[12:15]
	v_mfma_f32_16x16x32_bf16 v[4:7], v[160:163], v[206:209], v[4:7]
	v_mfma_f32_16x16x32_bf16 v[0:3], v[168:171], v[206:209], v[0:3]
	s_setprio 0
	s_barrier
	s_cmp_gt_u32 s87, 13
	s_mov_b32 s87, s26
	s_cbranch_scc1 .LBB0_1773

.LBB0_1820:
	s_lshl_b32 s26, s83, 7
	s_add_u32 s27, s34, s26
	s_addc_u32 s86, s35, 0
	s_add_i32 s26, s83, 2
	s_lshl_b32 s87, s26, 7
	s_add_u32 s52, s34, s87
	s_addc_u32 s53, s35, 0
	s_and_b64 s[38:39], s[44:45], exec
	s_cselect_b32 s53, s1, s53
	s_cselect_b32 s52, s21, s52
	s_add_u32 s87, s36, s87
	s_addc_u32 s88, s37, 0
	s_and_b64 s[38:39], s[44:45], exec
	s_cselect_b32 s45, s19, s88
	s_cselect_b32 s44, s29, s87
	s_add_i32 s87, 0, 0x10000
	s_add_i32 s88, 0, 0x14000
	v_add_u32_e32 v142, s87, v154
	v_add_u32_e32 v152, s88, v154
	ds_read_b128 v[130:133], v142
	ds_read_b128 v[134:137], v142 offset:1024
	ds_read_b128 v[138:141], v142 offset:2048
	ds_read_b128 v[142:145], v142 offset:3072
	ds_read_b128 v[156:159], v152
	ds_read_b128 v[160:163], v152 offset:1024
	ds_read_b128 v[164:167], v152 offset:2048
	ds_read_b128 v[168:171], v152 offset:3072
	s_add_u32 s38, s27, 0x40080
	s_addc_u32 s39, s86, 0
	v_lshl_add_u64 v[152:153], s[38:39], 0, v[146:147]
	s_add_i32 m0, s55, 0xc000
	ds_read_b128 v[172:175], v155
	ds_read_b128 v[176:179], v155 offset:1024
	ds_read_b128 v[180:183], v155 offset:2048
	ds_read_b128 v[184:187], v155 offset:3072
	ds_read_b128 v[188:191], v155 offset:4096
	ds_read_b128 v[198:201], v155 offset:5120
	ds_read_b128 v[202:205], v155 offset:6144
	ds_read_b128 v[206:209], v155 offset:7168
	global_load_lds_dwordx4 v[152:153], off
	v_lshl_add_u64 v[152:153], s[38:39], 0, v[148:149]
	s_add_i32 m0, s55, 0xe000
	s_nop 0
	global_load_lds_dwordx4 v[152:153], off
	s_waitcnt vmcnt(8)
	s_waitcnt lgkmcnt(0)
	s_barrier
	s_setprio 1
	s_waitcnt lgkmcnt(0)
	v_mfma_f32_16x16x32_bf16 v[126:129], v[130:133], v[172:175], v[126:129]
	v_mfma_f32_16x16x32_bf16 v[122:125], v[138:141], v[172:175], v[122:125]
	v_mfma_f32_16x16x32_bf16 v[118:121], v[130:133], v[180:183], v[118:121]
	v_mfma_f32_16x16x32_bf16 v[114:117], v[138:141], v[180:183], v[114:117]
	v_mfma_f32_16x16x32_bf16 v[94:97], v[130:133], v[188:191], v[94:97]
	v_mfma_f32_16x16x32_bf16 v[90:93], v[138:141], v[188:191], v[90:93]
	v_mfma_f32_16x16x32_bf16 v[86:89], v[130:133], v[202:205], v[86:89]
	v_mfma_f32_16x16x32_bf16 v[78:81], v[138:141], v[202:205], v[78:81]
	v_mfma_f32_16x16x32_bf16 v[126:129], v[134:137], v[176:179], v[126:129]
	v_mfma_f32_16x16x32_bf16 v[122:125], v[142:145], v[176:179], v[122:125]
	v_mfma_f32_16x16x32_bf16 v[118:121], v[134:137], v[184:187], v[118:121]
	v_mfma_f32_16x16x32_bf16 v[114:117], v[142:145], v[184:187], v[114:117]
	v_mfma_f32_16x16x32_bf16 v[94:97], v[134:137], v[198:201], v[94:97]
	v_mfma_f32_16x16x32_bf16 v[90:93], v[142:145], v[198:201], v[90:93]
	v_mfma_f32_16x16x32_bf16 v[86:89], v[134:137], v[206:209], v[86:89]
	v_mfma_f32_16x16x32_bf16 v[78:81], v[142:145], v[206:209], v[78:81]
	v_mfma_f32_16x16x32_bf16 v[110:113], v[156:159], v[172:175], v[110:113]
	v_mfma_f32_16x16x32_bf16 v[106:109], v[164:167], v[172:175], v[106:109]
	v_mfma_f32_16x16x32_bf16 v[102:105], v[156:159], v[180:183], v[102:105]
	v_mfma_f32_16x16x32_bf16 v[98:101], v[164:167], v[180:183], v[98:101]
	v_mfma_f32_16x16x32_bf16 v[82:85], v[156:159], v[188:191], v[82:85]
	v_mfma_f32_16x16x32_bf16 v[74:77], v[164:167], v[188:191], v[74:77]
	v_mfma_f32_16x16x32_bf16 v[70:73], v[156:159], v[202:205], v[70:73]
	v_mfma_f32_16x16x32_bf16 v[66:69], v[164:167], v[202:205], v[66:69]
	v_mfma_f32_16x16x32_bf16 v[110:113], v[160:163], v[176:179], v[110:113]
	v_mfma_f32_16x16x32_bf16 v[106:109], v[168:171], v[176:179], v[106:109]
	v_mfma_f32_16x16x32_bf16 v[102:105], v[160:163], v[184:187], v[102:105]
	v_mfma_f32_16x16x32_bf16 v[98:101], v[168:171], v[184:187], v[98:101]
	v_mfma_f32_16x16x32_bf16 v[82:85], v[160:163], v[198:201], v[82:85]
	v_mfma_f32_16x16x32_bf16 v[74:77], v[168:171], v[198:201], v[74:77]
	v_mfma_f32_16x16x32_bf16 v[70:73], v[160:163], v[206:209], v[70:73]
	v_mfma_f32_16x16x32_bf16 v[66:69], v[168:171], v[206:209], v[66:69]
	s_setprio 0
	s_barrier
	s_add_i32 s27, s87, s54
	v_lshl_add_u64 v[152:153], s[44:45], 0, v[64:65]
	s_mov_b32 m0, s27
	ds_read_b128 v[172:175], v155 offset:16384
	ds_read_b128 v[176:179], v155 offset:17408
	ds_read_b128 v[180:183], v155 offset:18432
	ds_read_b128 v[184:187], v155 offset:19456
	ds_read_b128 v[188:191], v155 offset:20480
	ds_read_b128 v[198:201], v155 offset:21504
	ds_read_b128 v[202:205], v155 offset:22528
	ds_read_b128 v[206:209], v155 offset:23552
	global_load_lds_dwordx4 v[152:153], off
	s_add_i32 m0, s27, 0x2000
	s_add_u32 s38, s44, 0x40000
	v_lshl_add_u64 v[192:193], s[44:45], 0, v[150:151]
	s_addc_u32 s39, s45, 0
	s_add_i32 s27, s88, s54
	global_load_lds_dwordx4 v[192:193], off
	v_lshl_add_u64 v[194:195], s[38:39], 0, v[64:65]
	s_mov_b32 m0, s27
	v_lshl_add_u64 v[196:197], s[52:53], 0, v[148:149]
	global_load_lds_dwordx4 v[194:195], off
	v_lshl_add_u64 v[194:195], s[38:39], 0, v[150:151]
	s_add_i32 m0, s27, 0x2000
	s_nop 0
	global_load_lds_dwordx4 v[194:195], off
	v_lshl_add_u64 v[194:195], s[52:53], 0, v[146:147]
	s_mov_b32 m0, s55
	s_nop 0
	global_load_lds_dwordx4 v[194:195], off
	s_mov_b32 m0, s63
	s_nop 0
	global_load_lds_dwordx4 v[196:197], off
	s_waitcnt vmcnt(8)
	s_waitcnt lgkmcnt(0)
	s_barrier
	s_setprio 1
	s_waitcnt lgkmcnt(0)
	v_mfma_f32_16x16x32_bf16 v[60:63], v[130:133], v[172:175], v[60:63]
	v_mfma_f32_16x16x32_bf16 v[56:59], v[138:141], v[172:175], v[56:59]
	v_mfma_f32_16x16x32_bf16 v[52:55], v[130:133], v[180:183], v[52:55]
	v_mfma_f32_16x16x32_bf16 v[44:47], v[138:141], v[180:183], v[44:47]
	v_mfma_f32_16x16x32_bf16 v[36:39], v[130:133], v[188:191], v[36:39]
	v_mfma_f32_16x16x32_bf16 v[28:31], v[138:141], v[188:191], v[28:31]
	v_mfma_f32_16x16x32_bf16 v[20:23], v[130:133], v[202:205], v[20:23]
	v_mfma_f32_16x16x32_bf16 v[12:15], v[138:141], v[202:205], v[12:15]
	v_mfma_f32_16x16x32_bf16 v[60:63], v[134:137], v[176:179], v[60:63]
	v_mfma_f32_16x16x32_bf16 v[56:59], v[142:145], v[176:179], v[56:59]
	v_mfma_f32_16x16x32_bf16 v[52:55], v[134:137], v[184:187], v[52:55]
	v_mfma_f32_16x16x32_bf16 v[44:47], v[142:145], v[184:187], v[44:47]
	v_mfma_f32_16x16x32_bf16 v[36:39], v[134:137], v[198:201], v[36:39]
	v_mfma_f32_16x16x32_bf16 v[28:31], v[142:145], v[198:201], v[28:31]
	v_mfma_f32_16x16x32_bf16 v[20:23], v[134:137], v[206:209], v[20:23]
	v_mfma_f32_16x16x32_bf16 v[12:15], v[142:145], v[206:209], v[12:15]
	v_mfma_f32_16x16x32_bf16 v[48:51], v[156:159], v[172:175], v[48:51]
	v_mfma_f32_16x16x32_bf16 v[40:43], v[164:167], v[172:175], v[40:43]
	v_mfma_f32_16x16x32_bf16 v[32:35], v[156:159], v[180:183], v[32:35]
	v_mfma_f32_16x16x32_bf16 v[24:27], v[164:167], v[180:183], v[24:27]
	v_mfma_f32_16x16x32_bf16 v[16:19], v[156:159], v[188:191], v[16:19]
	v_mfma_f32_16x16x32_bf16 v[8:11], v[164:167], v[188:191], v[8:11]
	v_mfma_f32_16x16x32_bf16 v[4:7], v[156:159], v[202:205], v[4:7]
	v_mfma_f32_16x16x32_bf16 v[0:3], v[164:167], v[202:205], v[0:3]
	v_mfma_f32_16x16x32_bf16 v[48:51], v[160:163], v[176:179], v[48:51]
	v_mfma_f32_16x16x32_bf16 v[40:43], v[168:171], v[176:179], v[40:43]
	v_mfma_f32_16x16x32_bf16 v[32:35], v[160:163], v[184:187], v[32:35]
	v_mfma_f32_16x16x32_bf16 v[24:27], v[168:171], v[184:187], v[24:27]
	v_mfma_f32_16x16x32_bf16 v[16:19], v[160:163], v[198:201], v[16:19]
	v_mfma_f32_16x16x32_bf16 v[8:11], v[168:171], v[198:201], v[8:11]
	v_mfma_f32_16x16x32_bf16 v[4:7], v[160:163], v[206:209], v[4:7]
	v_mfma_f32_16x16x32_bf16 v[0:3], v[168:171], v[206:209], v[0:3]
	s_setprio 0
	s_barrier
	s_add_i32 s27, 0, 0x18000
	s_add_i32 s86, 0, 0x1c000
	v_add_u32_e32 v142, s27, v154
	v_add_u32_e32 v168, s86, v154
	ds_read_b128 v[130:133], v142
	ds_read_b128 v[134:137], v142 offset:1024
	ds_read_b128 v[138:141], v142 offset:2048
	ds_read_b128 v[142:145], v142 offset:3072
	ds_read_b128 v[156:159], v168
	ds_read_b128 v[160:163], v168 offset:1024
	ds_read_b128 v[164:167], v168 offset:2048
	ds_read_b128 v[168:171], v168 offset:3072
	s_add_u32 s38, s52, 0x40000
	s_addc_u32 s39, s53, 0
	s_mov_b32 m0, s66
	v_lshl_add_u64 v[210:211], s[38:39], 0, v[146:147]
	ds_read_b128 v[172:175], v155 offset:32768
	ds_read_b128 v[176:179], v155 offset:33792
	ds_read_b128 v[180:183], v155 offset:34816
	ds_read_b128 v[184:187], v155 offset:35840
	ds_read_b128 v[188:191], v155 offset:36864
	ds_read_b128 v[198:201], v155 offset:37888
	ds_read_b128 v[202:205], v155 offset:38912
	ds_read_b128 v[206:209], v155 offset:39936
	global_load_lds_dwordx4 v[210:211], off
	v_lshl_add_u64 v[210:211], s[38:39], 0, v[148:149]
	s_mov_b32 m0, s69
	s_nop 0
	global_load_lds_dwordx4 v[210:211], off
	s_waitcnt vmcnt(8)
	s_waitcnt lgkmcnt(0)
	s_barrier
	s_setprio 1
	s_waitcnt lgkmcnt(0)
	v_mfma_f32_16x16x32_bf16 v[126:129], v[130:133], v[172:175], v[126:129]
	v_mfma_f32_16x16x32_bf16 v[122:125], v[138:141], v[172:175], v[122:125]
	v_mfma_f32_16x16x32_bf16 v[118:121], v[130:133], v[180:183], v[118:121]
	v_mfma_f32_16x16x32_bf16 v[114:117], v[138:141], v[180:183], v[114:117]
	v_mfma_f32_16x16x32_bf16 v[94:97], v[130:133], v[188:191], v[94:97]
	v_mfma_f32_16x16x32_bf16 v[90:93], v[138:141], v[188:191], v[90:93]
	v_mfma_f32_16x16x32_bf16 v[86:89], v[130:133], v[202:205], v[86:89]
	v_mfma_f32_16x16x32_bf16 v[78:81], v[138:141], v[202:205], v[78:81]
	v_mfma_f32_16x16x32_bf16 v[126:129], v[134:137], v[176:179], v[126:129]
	v_mfma_f32_16x16x32_bf16 v[122:125], v[142:145], v[176:179], v[122:125]
	v_mfma_f32_16x16x32_bf16 v[118:121], v[134:137], v[184:187], v[118:121]
	v_mfma_f32_16x16x32_bf16 v[114:117], v[142:145], v[184:187], v[114:117]
	v_mfma_f32_16x16x32_bf16 v[94:97], v[134:137], v[198:201], v[94:97]
	v_mfma_f32_16x16x32_bf16 v[90:93], v[142:145], v[198:201], v[90:93]
	v_mfma_f32_16x16x32_bf16 v[86:89], v[134:137], v[206:209], v[86:89]
	v_mfma_f32_16x16x32_bf16 v[78:81], v[142:145], v[206:209], v[78:81]
	v_mfma_f32_16x16x32_bf16 v[110:113], v[156:159], v[172:175], v[110:113]
	v_mfma_f32_16x16x32_bf16 v[106:109], v[164:167], v[172:175], v[106:109]
	v_mfma_f32_16x16x32_bf16 v[102:105], v[156:159], v[180:183], v[102:105]
	v_mfma_f32_16x16x32_bf16 v[98:101], v[164:167], v[180:183], v[98:101]
	v_mfma_f32_16x16x32_bf16 v[82:85], v[156:159], v[188:191], v[82:85]
	v_mfma_f32_16x16x32_bf16 v[74:77], v[164:167], v[188:191], v[74:77]
	v_mfma_f32_16x16x32_bf16 v[70:73], v[156:159], v[202:205], v[70:73]
	v_mfma_f32_16x16x32_bf16 v[66:69], v[164:167], v[202:205], v[66:69]
	v_mfma_f32_16x16x32_bf16 v[110:113], v[160:163], v[176:179], v[110:113]
	v_mfma_f32_16x16x32_bf16 v[106:109], v[168:171], v[176:179], v[106:109]
	v_mfma_f32_16x16x32_bf16 v[102:105], v[160:163], v[184:187], v[102:105]
	v_mfma_f32_16x16x32_bf16 v[98:101], v[168:171], v[184:187], v[98:101]
	v_mfma_f32_16x16x32_bf16 v[82:85], v[160:163], v[198:201], v[82:85]
	v_mfma_f32_16x16x32_bf16 v[74:77], v[168:171], v[198:201], v[74:77]
	v_mfma_f32_16x16x32_bf16 v[70:73], v[160:163], v[206:209], v[70:73]
	v_mfma_f32_16x16x32_bf16 v[66:69], v[168:171], v[206:209], v[66:69]
	s_setprio 0
	s_barrier
	s_add_i32 s27, s27, s54
	v_lshl_add_u64 v[152:153], v[152:153], 0, s[96:97]
	s_mov_b32 m0, s27
	ds_read_b128 v[172:175], v155 offset:49152
	ds_read_b128 v[176:179], v155 offset:50176
	ds_read_b128 v[180:183], v155 offset:51200
	ds_read_b128 v[184:187], v155 offset:52224
	ds_read_b128 v[188:191], v155 offset:53248
	ds_read_b128 v[198:201], v155 offset:54272
	ds_read_b128 v[202:205], v155 offset:55296
	ds_read_b128 v[206:209], v155 offset:56320
	global_load_lds_dwordx4 v[152:153], off
	s_add_i32 m0, s27, 0x2000
	s_add_u32 s38, s44, 0x40080
	v_lshl_add_u64 v[152:153], v[192:193], 0, s[96:97]
	s_addc_u32 s39, s45, 0
	s_add_i32 s27, s86, s54
	global_load_lds_dwordx4 v[152:153], off
	v_lshl_add_u64 v[152:153], s[38:39], 0, v[64:65]
	s_mov_b32 m0, s27
	s_nop 0
	global_load_lds_dwordx4 v[152:153], off
	v_lshl_add_u64 v[152:153], s[38:39], 0, v[150:151]
	s_add_i32 m0, s27, 0x2000
	s_nop 0
	global_load_lds_dwordx4 v[152:153], off
	v_lshl_add_u64 v[152:153], v[194:195], 0, s[96:97]
	s_mov_b32 m0, s78
	s_nop 0
	global_load_lds_dwordx4 v[152:153], off
	v_lshl_add_u64 v[152:153], v[196:197], 0, s[96:97]
	s_mov_b32 m0, s79
	s_nop 0
	global_load_lds_dwordx4 v[152:153], off
	s_waitcnt vmcnt(8)
	s_waitcnt lgkmcnt(0)
	s_barrier
	s_setprio 1
	s_waitcnt lgkmcnt(0)
	v_mfma_f32_16x16x32_bf16 v[60:63], v[130:133], v[172:175], v[60:63]
	v_mfma_f32_16x16x32_bf16 v[56:59], v[138:141], v[172:175], v[56:59]
	v_mfma_f32_16x16x32_bf16 v[52:55], v[130:133], v[180:183], v[52:55]
	v_mfma_f32_16x16x32_bf16 v[44:47], v[138:141], v[180:183], v[44:47]
	v_mfma_f32_16x16x32_bf16 v[36:39], v[130:133], v[188:191], v[36:39]
	v_mfma_f32_16x16x32_bf16 v[28:31], v[138:141], v[188:191], v[28:31]
	v_mfma_f32_16x16x32_bf16 v[20:23], v[130:133], v[202:205], v[20:23]
	v_mfma_f32_16x16x32_bf16 v[12:15], v[138:141], v[202:205], v[12:15]
	v_mfma_f32_16x16x32_bf16 v[60:63], v[134:137], v[176:179], v[60:63]
	v_mfma_f32_16x16x32_bf16 v[56:59], v[142:145], v[176:179], v[56:59]
	v_mfma_f32_16x16x32_bf16 v[52:55], v[134:137], v[184:187], v[52:55]
	v_mfma_f32_16x16x32_bf16 v[44:47], v[142:145], v[184:187], v[44:47]
	v_mfma_f32_16x16x32_bf16 v[36:39], v[134:137], v[198:201], v[36:39]
	v_mfma_f32_16x16x32_bf16 v[28:31], v[142:145], v[198:201], v[28:31]
	v_mfma_f32_16x16x32_bf16 v[20:23], v[134:137], v[206:209], v[20:23]
	v_mfma_f32_16x16x32_bf16 v[12:15], v[142:145], v[206:209], v[12:15]
	v_mfma_f32_16x16x32_bf16 v[48:51], v[156:159], v[172:175], v[48:51]
	v_mfma_f32_16x16x32_bf16 v[40:43], v[164:167], v[172:175], v[40:43]
	v_mfma_f32_16x16x32_bf16 v[32:35], v[156:159], v[180:183], v[32:35]
	v_mfma_f32_16x16x32_bf16 v[24:27], v[164:167], v[180:183], v[24:27]
	v_mfma_f32_16x16x32_bf16 v[16:19], v[156:159], v[188:191], v[16:19]
	v_mfma_f32_16x16x32_bf16 v[8:11], v[164:167], v[188:191], v[8:11]
	v_mfma_f32_16x16x32_bf16 v[4:7], v[156:159], v[202:205], v[4:7]
	v_mfma_f32_16x16x32_bf16 v[0:3], v[164:167], v[202:205], v[0:3]
	v_mfma_f32_16x16x32_bf16 v[48:51], v[160:163], v[176:179], v[48:51]
	v_mfma_f32_16x16x32_bf16 v[40:43], v[168:171], v[176:179], v[40:43]
	v_mfma_f32_16x16x32_bf16 v[32:35], v[160:163], v[184:187], v[32:35]
	v_mfma_f32_16x16x32_bf16 v[24:27], v[168:171], v[184:187], v[24:27]
	v_mfma_f32_16x16x32_bf16 v[16:19], v[160:163], v[198:201], v[16:19]
	v_mfma_f32_16x16x32_bf16 v[8:11], v[168:171], v[198:201], v[8:11]
	v_mfma_f32_16x16x32_bf16 v[4:7], v[160:163], v[206:209], v[4:7]
	v_mfma_f32_16x16x32_bf16 v[0:3], v[168:171], v[206:209], v[0:3]
	s_setprio 0
	s_barrier
	s_cmp_gt_u32 s83, 13
	s_mov_b32 s83, s26
	s_cbranch_scc1 .LBB0_1836

.LBB0_1874:
	s_add_i32 s59, 0, 0x14000
	s_add_i32 s63, 0, 0x10000
	v_add_u32_e32 v138, s59, v136
	v_add_u32_e32 v139, s63, v136
	ds_read_b128 v[0:3], v138 offset:3072
	ds_read_b128 v[4:7], v138 offset:2048
	ds_read_b128 v[8:11], v138 offset:1024
	ds_read_b128 v[12:15], v138
	ds_read_b128 v[16:19], v139 offset:3072
	ds_read_b128 v[20:23], v139 offset:2048
	ds_read_b128 v[24:27], v139 offset:1024
	ds_read_b128 v[28:31], v139
	s_add_u32 s24, s20, 0x40080
	s_addc_u32 s25, s21, 0
	s_add_i32 s69, s39, 0xc000
	v_lshl_add_u64 v[66:67], s[24:25], 0, v[130:131]
	s_mov_b32 m0, s69
	s_add_i32 s15, s39, 0xe000
	ds_read_b128 v[32:35], v137
	ds_read_b128 v[36:39], v137 offset:1024
	ds_read_b128 v[40:43], v137 offset:2048
	ds_read_b128 v[44:47], v137 offset:3072
	ds_read_b128 v[48:51], v137 offset:4096
	ds_read_b128 v[52:55], v137 offset:5120
	ds_read_b128 v[56:59], v137 offset:6144
	ds_read_b128 v[60:63], v137 offset:7168
	global_load_lds_dwordx4 v[66:67], off
	v_lshl_add_u64 v[66:67], s[24:25], 0, v[132:133]
	s_mov_b32 m0, s15
	s_nop 0
	global_load_lds_dwordx4 v[66:67], off
	s_waitcnt vmcnt(8)
	s_waitcnt lgkmcnt(0)
	s_barrier
	s_setprio 1
	s_waitcnt lgkmcnt(0)
	v_mfma_f32_16x16x32_bf16 v[66:69], v[28:31], v[32:35], 0
	v_mfma_f32_16x16x32_bf16 v[70:73], v[20:23], v[32:35], 0
	v_mfma_f32_16x16x32_bf16 v[74:77], v[28:31], v[40:43], 0
	v_mfma_f32_16x16x32_bf16 v[78:81], v[20:23], v[40:43], 0
	v_mfma_f32_16x16x32_bf16 v[82:85], v[28:31], v[48:51], 0
	v_mfma_f32_16x16x32_bf16 v[86:89], v[20:23], v[48:51], 0
	v_mfma_f32_16x16x32_bf16 v[90:93], v[28:31], v[56:59], 0
	v_mfma_f32_16x16x32_bf16 v[94:97], v[20:23], v[56:59], 0
	v_mfma_f32_16x16x32_bf16 v[66:69], v[24:27], v[36:39], v[66:69]
	v_mfma_f32_16x16x32_bf16 v[70:73], v[16:19], v[36:39], v[70:73]
	v_mfma_f32_16x16x32_bf16 v[74:77], v[24:27], v[44:47], v[74:77]
	v_mfma_f32_16x16x32_bf16 v[78:81], v[16:19], v[44:47], v[78:81]
	v_mfma_f32_16x16x32_bf16 v[82:85], v[24:27], v[52:55], v[82:85]
	v_mfma_f32_16x16x32_bf16 v[86:89], v[16:19], v[52:55], v[86:89]
	v_mfma_f32_16x16x32_bf16 v[90:93], v[24:27], v[60:63], v[90:93]
	v_mfma_f32_16x16x32_bf16 v[94:97], v[16:19], v[60:63], v[94:97]
	v_mfma_f32_16x16x32_bf16 v[98:101], v[12:15], v[32:35], 0
	v_mfma_f32_16x16x32_bf16 v[32:35], v[4:7], v[32:35], 0
	v_mfma_f32_16x16x32_bf16 v[98:101], v[8:11], v[36:39], v[98:101]
	v_mfma_f32_16x16x32_bf16 v[36:39], v[0:3], v[36:39], v[32:35]
	v_mfma_f32_16x16x32_bf16 v[32:35], v[12:15], v[40:43], 0
	v_mfma_f32_16x16x32_bf16 v[102:105], v[8:11], v[44:47], v[32:35]
	v_mfma_f32_16x16x32_bf16 v[32:35], v[4:7], v[40:43], 0
	v_mfma_f32_16x16x32_bf16 v[44:47], v[0:3], v[44:47], v[32:35]
	v_mfma_f32_16x16x32_bf16 v[32:35], v[12:15], v[48:51], 0
	v_mfma_f32_16x16x32_bf16 v[106:109], v[8:11], v[52:55], v[32:35]
	v_mfma_f32_16x16x32_bf16 v[32:35], v[4:7], v[48:51], 0
	v_mfma_f32_16x16x32_bf16 v[52:55], v[0:3], v[52:55], v[32:35]
	v_mfma_f32_16x16x32_bf16 v[32:35], v[12:15], v[56:59], 0
	v_mfma_f32_16x16x32_bf16 v[110:113], v[8:11], v[60:63], v[32:35]
	v_mfma_f32_16x16x32_bf16 v[32:35], v[4:7], v[56:59], 0
	v_mfma_f32_16x16x32_bf16 v[60:63], v[0:3], v[60:63], v[32:35]
	s_setprio 0
	s_barrier
	s_add_i32 s63, s63, s38
	v_lshl_add_u64 v[232:233], s[22:23], 0, v[64:65]
	s_mov_b64 s[26:27], 0x100
	s_add_i32 s58, s63, 0x2000
	v_lshl_add_u64 v[140:141], v[232:233], 0, s[26:27]
	s_mov_b32 m0, s63
	v_lshl_add_u64 v[250:251], s[22:23], 0, v[134:135]
	s_add_u32 s24, s22, 0x40100
	ds_read_b128 v[32:35], v137 offset:16384
	ds_read_b128 v[40:43], v137 offset:17408
	ds_read_b128 v[48:51], v137 offset:18432
	ds_read_b128 v[56:59], v137 offset:19456
	ds_read_b128 v[114:117], v137 offset:20480
	ds_read_b128 v[118:121], v137 offset:21504
	ds_read_b128 v[122:125], v137 offset:22528
	ds_read_b128 v[126:129], v137 offset:23552
	global_load_lds_dwordx4 v[140:141], off
	v_lshl_add_u64 v[140:141], v[250:251], 0, s[26:27]
	s_mov_b32 m0, s58
	s_addc_u32 s25, s23, 0
	s_add_i32 s59, s59, s38
	global_load_lds_dwordx4 v[140:141], off
	v_lshl_add_u64 v[140:141], s[24:25], 0, v[64:65]
	s_mov_b32 m0, s59
	s_add_i32 s62, s59, 0x2000
	global_load_lds_dwordx4 v[140:141], off
	v_lshl_add_u64 v[140:141], s[24:25], 0, v[134:135]
	s_mov_b32 m0, s62
	v_lshl_add_u64 v[226:227], s[20:21], 0, v[130:131]
	global_load_lds_dwordx4 v[140:141], off
	v_lshl_add_u64 v[140:141], v[226:227], 0, s[26:27]
	s_mov_b32 m0, s39
	v_lshl_add_u64 v[236:237], s[20:21], 0, v[132:133]
	global_load_lds_dwordx4 v[140:141], off
	v_lshl_add_u64 v[140:141], v[236:237], 0, s[26:27]
	s_mov_b32 m0, s40
	s_nop 0
	global_load_lds_dwordx4 v[140:141], off
	s_waitcnt vmcnt(8)
	s_waitcnt lgkmcnt(0)
	s_barrier
	s_setprio 1
	s_waitcnt lgkmcnt(0)
	v_mfma_f32_16x16x32_bf16 v[140:143], v[28:31], v[32:35], 0
	v_mfma_f32_16x16x32_bf16 v[146:149], v[20:23], v[32:35], 0
	v_mfma_f32_16x16x32_bf16 v[150:153], v[28:31], v[48:51], 0
	v_mfma_f32_16x16x32_bf16 v[154:157], v[20:23], v[48:51], 0
	v_mfma_f32_16x16x32_bf16 v[158:161], v[28:31], v[114:117], 0
	v_mfma_f32_16x16x32_bf16 v[162:165], v[20:23], v[114:117], 0
	v_mfma_f32_16x16x32_bf16 v[28:31], v[28:31], v[122:125], 0
	v_mfma_f32_16x16x32_bf16 v[20:23], v[20:23], v[122:125], 0
	v_mfma_f32_16x16x32_bf16 v[142:145], v[24:27], v[40:43], v[140:143]
	v_mfma_f32_16x16x32_bf16 v[146:149], v[16:19], v[40:43], v[146:149]
	v_mfma_f32_16x16x32_bf16 v[150:153], v[24:27], v[56:59], v[150:153]
	v_mfma_f32_16x16x32_bf16 v[154:157], v[16:19], v[56:59], v[154:157]
	v_mfma_f32_16x16x32_bf16 v[158:161], v[24:27], v[118:121], v[158:161]
	v_mfma_f32_16x16x32_bf16 v[162:165], v[16:19], v[118:121], v[162:165]
	v_mfma_f32_16x16x32_bf16 v[166:169], v[24:27], v[126:129], v[28:31]
	v_mfma_f32_16x16x32_bf16 v[170:173], v[16:19], v[126:129], v[20:23]
	v_mfma_f32_16x16x32_bf16 v[16:19], v[12:15], v[32:35], 0
	v_mfma_f32_16x16x32_bf16 v[174:177], v[8:11], v[40:43], v[16:19]
	v_mfma_f32_16x16x32_bf16 v[16:19], v[4:7], v[32:35], 0
	v_mfma_f32_16x16x32_bf16 v[178:181], v[0:3], v[40:43], v[16:19]
	v_mfma_f32_16x16x32_bf16 v[16:19], v[12:15], v[48:51], 0
	v_mfma_f32_16x16x32_bf16 v[182:185], v[8:11], v[56:59], v[16:19]
	v_mfma_f32_16x16x32_bf16 v[16:19], v[4:7], v[48:51], 0
	v_mfma_f32_16x16x32_bf16 v[186:189], v[0:3], v[56:59], v[16:19]
	v_mfma_f32_16x16x32_bf16 v[16:19], v[12:15], v[114:117], 0
	v_mfma_f32_16x16x32_bf16 v[190:193], v[8:11], v[118:121], v[16:19]
	v_mfma_f32_16x16x32_bf16 v[16:19], v[4:7], v[114:117], 0
	v_mfma_f32_16x16x32_bf16 v[12:15], v[12:15], v[122:125], 0
	v_mfma_f32_16x16x32_bf16 v[4:7], v[4:7], v[122:125], 0
	v_mfma_f32_16x16x32_bf16 v[118:121], v[0:3], v[118:121], v[16:19]
	v_mfma_f32_16x16x32_bf16 v[198:201], v[8:11], v[126:129], v[12:15]
	v_mfma_f32_16x16x32_bf16 v[126:129], v[0:3], v[126:129], v[4:7]
	s_setprio 0
	s_barrier
	s_add_i32 s76, 0, 0x18000
	s_add_i32 s70, 0, 0x1c000
	v_add_u32_e32 v140, s76, v136
	v_add_u32_e32 v141, s70, v136
	ds_read_b128 v[114:117], v140
	ds_read_b128 v[122:125], v140 offset:1024
	ds_read_b128 v[202:205], v140 offset:2048
	ds_read_b128 v[206:209], v140 offset:3072
	ds_read_b128 v[210:213], v141
	ds_read_b128 v[214:217], v141 offset:1024
	ds_read_b128 v[218:221], v141 offset:2048
	ds_read_b128 v[222:225], v141 offset:3072
	s_add_u32 s24, s20, 0x40100
	s_addc_u32 s25, s21, 0
	s_mov_b32 m0, s41
	v_lshl_add_u64 v[0:1], s[24:25], 0, v[130:131]
	ds_read_b128 v[40:43], v137 offset:32768
	ds_read_b128 v[48:51], v137 offset:33792
	ds_read_b128 v[56:59], v137 offset:34816
	ds_read_b128 v[228:231], v137 offset:35840
	ds_read_b128 v[242:245], v137 offset:36864
	ds_read_b128 v[246:249], v137 offset:37888
	ds_read_b128 v[194:197], v137 offset:38912
	ds_read_b128 v[238:241], v137 offset:39936
	global_load_lds_dwordx4 v[0:1], off
	v_lshl_add_u64 v[0:1], s[24:25], 0, v[132:133]
	s_mov_b32 m0, s43
	s_nop 0
	global_load_lds_dwordx4 v[0:1], off
	s_waitcnt vmcnt(8)
	s_waitcnt lgkmcnt(0)
	s_barrier
	s_setprio 1
	s_waitcnt lgkmcnt(0)
	v_mfma_f32_16x16x32_bf16 v[0:3], v[114:117], v[40:43], v[66:69]
	v_mfma_f32_16x16x32_bf16 v[4:7], v[202:205], v[40:43], v[70:73]
	v_mfma_f32_16x16x32_bf16 v[8:11], v[114:117], v[56:59], v[74:77]
	v_mfma_f32_16x16x32_bf16 v[12:15], v[202:205], v[56:59], v[78:81]
	v_mfma_f32_16x16x32_bf16 v[16:19], v[114:117], v[242:245], v[82:85]
	v_mfma_f32_16x16x32_bf16 v[20:23], v[202:205], v[242:245], v[86:89]
	v_mfma_f32_16x16x32_bf16 v[24:27], v[114:117], v[194:197], v[90:93]
	v_mfma_f32_16x16x32_bf16 v[28:31], v[202:205], v[194:197], v[94:97]
	v_mfma_f32_16x16x32_bf16 v[0:3], v[122:125], v[48:51], v[0:3]
	v_mfma_f32_16x16x32_bf16 v[4:7], v[206:209], v[48:51], v[4:7]
	v_mfma_f32_16x16x32_bf16 v[8:11], v[122:125], v[228:231], v[8:11]
	v_mfma_f32_16x16x32_bf16 v[12:15], v[206:209], v[228:231], v[12:15]
	v_mfma_f32_16x16x32_bf16 v[16:19], v[122:125], v[246:249], v[16:19]
	v_mfma_f32_16x16x32_bf16 v[20:23], v[206:209], v[246:249], v[20:23]
	v_mfma_f32_16x16x32_bf16 v[24:27], v[122:125], v[238:241], v[24:27]
	v_mfma_f32_16x16x32_bf16 v[28:31], v[206:209], v[238:241], v[28:31]
	v_mfma_f32_16x16x32_bf16 v[32:35], v[210:213], v[40:43], v[98:101]
	v_mfma_f32_16x16x32_bf16 v[36:39], v[218:221], v[40:43], v[36:39]
	v_mfma_f32_16x16x32_bf16 v[32:35], v[214:217], v[48:51], v[32:35]
	v_mfma_f32_16x16x32_bf16 v[36:39], v[222:225], v[48:51], v[36:39]
	v_mfma_f32_16x16x32_bf16 v[40:43], v[210:213], v[56:59], v[102:105]
	v_mfma_f32_16x16x32_bf16 v[44:47], v[218:221], v[56:59], v[44:47]
	v_mfma_f32_16x16x32_bf16 v[48:51], v[210:213], v[242:245], v[106:109]
	v_mfma_f32_16x16x32_bf16 v[52:55], v[218:221], v[242:245], v[52:55]
	v_mfma_f32_16x16x32_bf16 v[56:59], v[210:213], v[194:197], v[110:113]
	v_mfma_f32_16x16x32_bf16 v[60:63], v[218:221], v[194:197], v[60:63]
	v_mfma_f32_16x16x32_bf16 v[40:43], v[214:217], v[228:231], v[40:43]
	v_mfma_f32_16x16x32_bf16 v[44:47], v[222:225], v[228:231], v[44:47]
	v_mfma_f32_16x16x32_bf16 v[48:51], v[214:217], v[246:249], v[48:51]
	v_mfma_f32_16x16x32_bf16 v[52:55], v[222:225], v[246:249], v[52:55]
	v_mfma_f32_16x16x32_bf16 v[56:59], v[214:217], v[238:241], v[56:59]
	v_mfma_f32_16x16x32_bf16 v[60:63], v[222:225], v[238:241], v[60:63]
	s_setprio 0
	s_barrier
	s_add_i32 s76, s76, s38
	s_mov_b64 s[24:25], 0x180
	s_add_i32 s66, s76, 0x2000
	v_lshl_add_u64 v[66:67], v[232:233], 0, s[24:25]
	s_mov_b32 m0, s76
	s_add_u32 s22, s22, 0x40180
	ds_read_b128 v[102:105], v137 offset:49152
	ds_read_b128 v[106:109], v137 offset:50176
	ds_read_b128 v[110:113], v137 offset:51200
	ds_read_b128 v[194:197], v137 offset:52224
	ds_read_b128 v[228:231], v137 offset:53248
	ds_read_b128 v[238:241], v137 offset:54272
	ds_read_b128 v[242:245], v137 offset:55296
	ds_read_b128 v[246:249], v137 offset:56320
	global_load_lds_dwordx4 v[66:67], off
	v_lshl_add_u64 v[66:67], v[250:251], 0, s[24:25]
	s_mov_b32 m0, s66
	s_addc_u32 s23, s23, 0
	s_add_i32 s70, s70, s38
	global_load_lds_dwordx4 v[66:67], off
	v_lshl_add_u64 v[66:67], s[22:23], 0, v[64:65]
	s_mov_b32 m0, s70
	s_add_i32 s71, s70, 0x2000
	global_load_lds_dwordx4 v[66:67], off
	v_lshl_add_u64 v[66:67], s[22:23], 0, v[134:135]
	s_mov_b32 m0, s71
	s_nop 0
	global_load_lds_dwordx4 v[66:67], off
	v_lshl_add_u64 v[66:67], v[226:227], 0, s[24:25]
	s_mov_b32 m0, s49
	s_nop 0
	global_load_lds_dwordx4 v[66:67], off
	v_lshl_add_u64 v[66:67], v[236:237], 0, s[24:25]
	s_mov_b32 m0, s51
	s_nop 0
	global_load_lds_dwordx4 v[66:67], off
	s_waitcnt vmcnt(8)
	s_waitcnt lgkmcnt(0)
	s_barrier
	s_setprio 1
	s_waitcnt lgkmcnt(0)
	v_mfma_f32_16x16x32_bf16 v[66:69], v[114:117], v[102:105], v[142:145]
	v_mfma_f32_16x16x32_bf16 v[70:73], v[202:205], v[102:105], v[146:149]
	v_mfma_f32_16x16x32_bf16 v[74:77], v[114:117], v[110:113], v[150:153]
	v_mfma_f32_16x16x32_bf16 v[78:81], v[202:205], v[110:113], v[154:157]
	v_mfma_f32_16x16x32_bf16 v[82:85], v[114:117], v[228:231], v[158:161]
	v_mfma_f32_16x16x32_bf16 v[86:89], v[202:205], v[228:231], v[162:165]
	v_mfma_f32_16x16x32_bf16 v[90:93], v[114:117], v[242:245], v[166:169]
	v_mfma_f32_16x16x32_bf16 v[94:97], v[202:205], v[242:245], v[170:173]
	v_mfma_f32_16x16x32_bf16 v[66:69], v[122:125], v[106:109], v[66:69]
	v_mfma_f32_16x16x32_bf16 v[70:73], v[206:209], v[106:109], v[70:73]
	v_mfma_f32_16x16x32_bf16 v[74:77], v[122:125], v[194:197], v[74:77]
	v_mfma_f32_16x16x32_bf16 v[78:81], v[206:209], v[194:197], v[78:81]
	v_mfma_f32_16x16x32_bf16 v[82:85], v[122:125], v[238:241], v[82:85]
	v_mfma_f32_16x16x32_bf16 v[86:89], v[206:209], v[238:241], v[86:89]
	v_mfma_f32_16x16x32_bf16 v[90:93], v[122:125], v[246:249], v[90:93]
	v_mfma_f32_16x16x32_bf16 v[94:97], v[206:209], v[246:249], v[94:97]
	v_mfma_f32_16x16x32_bf16 v[98:101], v[210:213], v[102:105], v[174:177]
	v_mfma_f32_16x16x32_bf16 v[102:105], v[218:221], v[102:105], v[178:181]
	v_mfma_f32_16x16x32_bf16 v[98:101], v[214:217], v[106:109], v[98:101]
	v_mfma_f32_16x16x32_bf16 v[102:105], v[222:225], v[106:109], v[102:105]
	v_mfma_f32_16x16x32_bf16 v[106:109], v[210:213], v[110:113], v[182:185]
	v_mfma_f32_16x16x32_bf16 v[110:113], v[218:221], v[110:113], v[186:189]
	v_mfma_f32_16x16x32_bf16 v[114:117], v[210:213], v[228:231], v[190:193]
	v_mfma_f32_16x16x32_bf16 v[118:121], v[218:221], v[228:231], v[118:121]
	v_mfma_f32_16x16x32_bf16 v[122:125], v[210:213], v[242:245], v[198:201]
	v_mfma_f32_16x16x32_bf16 v[126:129], v[218:221], v[242:245], v[126:129]
	v_mfma_f32_16x16x32_bf16 v[106:109], v[214:217], v[194:197], v[106:109]
	v_mfma_f32_16x16x32_bf16 v[110:113], v[222:225], v[194:197], v[110:113]
	v_mfma_f32_16x16x32_bf16 v[114:117], v[214:217], v[238:241], v[114:117]
	v_mfma_f32_16x16x32_bf16 v[118:121], v[222:225], v[238:241], v[118:121]
	v_mfma_f32_16x16x32_bf16 v[122:125], v[214:217], v[246:249], v[122:125]
	v_mfma_f32_16x16x32_bf16 v[126:129], v[222:225], v[246:249], v[126:129]
	s_setprio 0
	s_barrier
	s_and_b64 vcc, exec, s[6:7]
	s_cbranch_vccnz .LBB0_1892
	s_getreg_b32 s22, hwreg(HW_REG_HW_ID, 0, 6)
	s_and_b32 s22, s22, 63
	s_lshl_b32 s22, s22, 2
	s_add_i32 s22, s22, 0
	s_add_i32 s22, s22, 0x27400
	v_mov_b32_e32 v142, s22
	ds_read_b32 v142, v142
	s_waitcnt lgkmcnt(0)
	v_readfirstlane_b32 s22, v142
	s_cmp_lg_u32 s22, 0
	s_cbranch_scc1 .LBB0_1891
	s_lshl_b32 s22, s14, 6
	s_ashr_i32 s23, s22, 31
	s_lshl_b64 s[22:23], s[22:23], 2
	s_add_u32 s22, s0, s22
	s_addc_u32 s23, s1, s23
	s_add_u32 s22, s22, 0x29800
	s_addc_u32 s23, s23, 0
	s_mov_b32 s77, 1
	s_branch .LBB0_1878

.LBB0_1892:
	ds_read_b128 v[142:145], v139
	ds_read_b128 v[146:149], v139 offset:1024
	ds_read_b128 v[150:153], v139 offset:2048
	ds_read_b128 v[154:157], v139 offset:3072
	ds_read_b128 v[158:161], v138
	ds_read_b128 v[162:165], v138 offset:1024
	ds_read_b128 v[166:169], v138 offset:2048
	ds_read_b128 v[170:173], v138 offset:3072
	s_add_u32 s20, s20, 0x40180
	s_addc_u32 s21, s21, 0
	s_mov_b32 m0, s69
	v_lshl_add_u64 v[138:139], s[20:21], 0, v[130:131]
	ds_read_b128 v[174:177], v137
	ds_read_b128 v[178:181], v137 offset:1024
	ds_read_b128 v[182:185], v137 offset:2048
	ds_read_b128 v[186:189], v137 offset:3072
	ds_read_b128 v[190:193], v137 offset:4096
	ds_read_b128 v[194:197], v137 offset:5120
	ds_read_b128 v[198:201], v137 offset:6144
	ds_read_b128 v[202:205], v137 offset:7168
	global_load_lds_dwordx4 v[138:139], off
	v_lshl_add_u64 v[138:139], s[20:21], 0, v[132:133]
	s_mov_b32 m0, s15
	s_nop 0
	global_load_lds_dwordx4 v[138:139], off
	s_waitcnt vmcnt(8)
	s_waitcnt lgkmcnt(0)
	s_barrier
	s_setprio 1
	s_waitcnt lgkmcnt(0)
	v_mfma_f32_16x16x32_bf16 v[0:3], v[142:145], v[174:177], v[0:3]
	v_mfma_f32_16x16x32_bf16 v[4:7], v[150:153], v[174:177], v[4:7]
	v_mfma_f32_16x16x32_bf16 v[8:11], v[142:145], v[182:185], v[8:11]
	v_mfma_f32_16x16x32_bf16 v[12:15], v[150:153], v[182:185], v[12:15]
	v_mfma_f32_16x16x32_bf16 v[16:19], v[142:145], v[190:193], v[16:19]
	v_mfma_f32_16x16x32_bf16 v[20:23], v[150:153], v[190:193], v[20:23]
	v_mfma_f32_16x16x32_bf16 v[24:27], v[142:145], v[198:201], v[24:27]
	v_mfma_f32_16x16x32_bf16 v[28:31], v[150:153], v[198:201], v[28:31]
	v_mfma_f32_16x16x32_bf16 v[0:3], v[146:149], v[178:181], v[0:3]
	v_mfma_f32_16x16x32_bf16 v[4:7], v[154:157], v[178:181], v[4:7]
	v_mfma_f32_16x16x32_bf16 v[8:11], v[146:149], v[186:189], v[8:11]
	v_mfma_f32_16x16x32_bf16 v[12:15], v[154:157], v[186:189], v[12:15]
	v_mfma_f32_16x16x32_bf16 v[16:19], v[146:149], v[194:197], v[16:19]
	v_mfma_f32_16x16x32_bf16 v[20:23], v[154:157], v[194:197], v[20:23]
	v_mfma_f32_16x16x32_bf16 v[24:27], v[146:149], v[202:205], v[24:27]
	v_mfma_f32_16x16x32_bf16 v[28:31], v[154:157], v[202:205], v[28:31]
	v_mfma_f32_16x16x32_bf16 v[40:43], v[158:161], v[182:185], v[40:43]
	v_mfma_f32_16x16x32_bf16 v[32:35], v[158:161], v[174:177], v[32:35]
	v_mfma_f32_16x16x32_bf16 v[36:39], v[166:169], v[174:177], v[36:39]
	v_mfma_f32_16x16x32_bf16 v[174:177], v[162:165], v[186:189], v[40:43]
	v_mfma_f32_16x16x32_bf16 v[40:43], v[166:169], v[182:185], v[44:47]
	v_mfma_f32_16x16x32_bf16 v[32:35], v[162:165], v[178:181], v[32:35]
	v_mfma_f32_16x16x32_bf16 v[36:39], v[170:173], v[178:181], v[36:39]
	v_mfma_f32_16x16x32_bf16 v[178:181], v[170:173], v[186:189], v[40:43]
	v_mfma_f32_16x16x32_bf16 v[40:43], v[158:161], v[190:193], v[48:51]
	v_mfma_f32_16x16x32_bf16 v[48:51], v[162:165], v[194:197], v[40:43]
	v_mfma_f32_16x16x32_bf16 v[40:43], v[166:169], v[190:193], v[52:55]
	v_mfma_f32_16x16x32_bf16 v[52:55], v[170:173], v[194:197], v[40:43]
	v_mfma_f32_16x16x32_bf16 v[40:43], v[158:161], v[198:201], v[56:59]
	v_mfma_f32_16x16x32_bf16 v[182:185], v[162:165], v[202:205], v[40:43]
	v_mfma_f32_16x16x32_bf16 v[40:43], v[166:169], v[198:201], v[60:63]
	v_mfma_f32_16x16x32_bf16 v[186:189], v[170:173], v[202:205], v[40:43]
	s_setprio 0
	s_barrier
	s_mov_b32 m0, s63
	v_lshl_add_u64 v[226:227], s[18:19], 0, v[64:65]
	s_add_u32 s20, s18, 0x40000
	s_nop 1
	ds_read_b128 v[40:43], v137 offset:16384
	ds_read_b128 v[44:47], v137 offset:17408
	ds_read_b128 v[56:59], v137 offset:18432
	ds_read_b128 v[60:63], v137 offset:19456
	ds_read_b128 v[190:193], v137 offset:20480
	ds_read_b128 v[194:197], v137 offset:21504
	ds_read_b128 v[198:201], v137 offset:22528
	ds_read_b128 v[202:205], v137 offset:23552
	global_load_lds_dwordx4 v[226:227], off
	v_lshl_add_u64 v[232:233], s[18:19], 0, v[134:135]
	s_mov_b32 m0, s58
	s_addc_u32 s21, s19, 0
	global_load_lds_dwordx4 v[232:233], off
	v_lshl_add_u64 v[138:139], s[20:21], 0, v[64:65]
	s_mov_b32 m0, s59
	v_lshl_add_u64 v[236:237], s[16:17], 0, v[130:131]
	global_load_lds_dwordx4 v[138:139], off
	v_lshl_add_u64 v[138:139], s[20:21], 0, v[134:135]
	s_mov_b32 m0, s62
	v_lshl_add_u64 v[246:247], s[16:17], 0, v[132:133]
	global_load_lds_dwordx4 v[138:139], off
	s_mov_b32 m0, s39
	s_nop 0
	global_load_lds_dwordx4 v[236:237], off
	s_mov_b32 m0, s40
	s_nop 0
	global_load_lds_dwordx4 v[246:247], off
	s_waitcnt vmcnt(8)
	s_waitcnt lgkmcnt(0)
	s_barrier
	s_setprio 1
	s_waitcnt lgkmcnt(0)
	v_mfma_f32_16x16x32_bf16 v[74:77], v[142:145], v[56:59], v[74:77]
	v_mfma_f32_16x16x32_bf16 v[206:209], v[146:149], v[60:63], v[74:77]
	v_mfma_f32_16x16x32_bf16 v[74:77], v[150:153], v[56:59], v[78:81]
	v_mfma_f32_16x16x32_bf16 v[210:213], v[154:157], v[60:63], v[74:77]
	v_mfma_f32_16x16x32_bf16 v[74:77], v[142:145], v[190:193], v[82:85]
	v_mfma_f32_16x16x32_bf16 v[82:85], v[146:149], v[194:197], v[74:77]
	v_mfma_f32_16x16x32_bf16 v[74:77], v[150:153], v[190:193], v[86:89]
	v_mfma_f32_16x16x32_bf16 v[66:69], v[142:145], v[40:43], v[66:69]
	v_mfma_f32_16x16x32_bf16 v[70:73], v[150:153], v[40:43], v[70:73]
	v_mfma_f32_16x16x32_bf16 v[86:89], v[154:157], v[194:197], v[74:77]
	v_mfma_f32_16x16x32_bf16 v[74:77], v[142:145], v[198:201], v[90:93]
	v_mfma_f32_16x16x32_bf16 v[66:69], v[146:149], v[44:47], v[66:69]
	v_mfma_f32_16x16x32_bf16 v[70:73], v[154:157], v[44:47], v[70:73]
	v_mfma_f32_16x16x32_bf16 v[142:145], v[146:149], v[202:205], v[74:77]
	v_mfma_f32_16x16x32_bf16 v[74:77], v[150:153], v[198:201], v[94:97]
	v_mfma_f32_16x16x32_bf16 v[146:149], v[154:157], v[202:205], v[74:77]
	v_mfma_f32_16x16x32_bf16 v[74:77], v[158:161], v[40:43], v[98:101]
	v_mfma_f32_16x16x32_bf16 v[40:43], v[166:169], v[40:43], v[102:105]
	v_mfma_f32_16x16x32_bf16 v[154:157], v[170:173], v[44:47], v[40:43]
	v_mfma_f32_16x16x32_bf16 v[40:43], v[158:161], v[56:59], v[106:109]
	v_mfma_f32_16x16x32_bf16 v[214:217], v[162:165], v[60:63], v[40:43]
	v_mfma_f32_16x16x32_bf16 v[40:43], v[166:169], v[56:59], v[110:113]
	v_mfma_f32_16x16x32_bf16 v[218:221], v[170:173], v[60:63], v[40:43]
	v_mfma_f32_16x16x32_bf16 v[40:43], v[158:161], v[190:193], v[114:117]
	v_mfma_f32_16x16x32_bf16 v[222:225], v[162:165], v[194:197], v[40:43]
	v_mfma_f32_16x16x32_bf16 v[40:43], v[166:169], v[190:193], v[118:121]
	v_mfma_f32_16x16x32_bf16 v[190:193], v[170:173], v[194:197], v[40:43]
	v_mfma_f32_16x16x32_bf16 v[40:43], v[158:161], v[198:201], v[122:125]
	v_mfma_f32_16x16x32_bf16 v[158:161], v[162:165], v[202:205], v[40:43]
	v_mfma_f32_16x16x32_bf16 v[40:43], v[166:169], v[198:201], v[126:129]
	v_mfma_f32_16x16x32_bf16 v[150:153], v[162:165], v[44:47], v[74:77]
	v_mfma_f32_16x16x32_bf16 v[162:165], v[170:173], v[202:205], v[40:43]
	s_setprio 0
	s_barrier
	ds_read_b128 v[114:117], v140
	ds_read_b128 v[118:121], v140 offset:1024
	ds_read_b128 v[166:169], v140 offset:2048
	ds_read_b128 v[170:173], v140 offset:3072
	ds_read_b128 v[194:197], v141
	ds_read_b128 v[198:201], v141 offset:1024
	ds_read_b128 v[202:205], v141 offset:2048
	ds_read_b128 v[138:141], v141 offset:3072
	s_add_u32 s20, s16, 0x40000
	s_addc_u32 s21, s17, 0
	s_mov_b32 m0, s41
	v_lshl_add_u64 v[40:41], s[20:21], 0, v[130:131]
	ds_read_b128 v[56:59], v137 offset:32768
	ds_read_b128 v[60:63], v137 offset:33792
	ds_read_b128 v[94:97], v137 offset:34816
	ds_read_b128 v[98:101], v137 offset:35840
	ds_read_b128 v[102:105], v137 offset:36864
	ds_read_b128 v[228:231], v137 offset:37888
	ds_read_b128 v[238:241], v137 offset:38912
	ds_read_b128 v[242:245], v137 offset:39936
	global_load_lds_dwordx4 v[40:41], off
	v_lshl_add_u64 v[40:41], s[20:21], 0, v[132:133]
	s_mov_b32 m0, s43
	s_nop 0
	global_load_lds_dwordx4 v[40:41], off
	s_waitcnt vmcnt(8)
	s_waitcnt lgkmcnt(0)
	s_barrier
	s_setprio 1
	s_waitcnt lgkmcnt(0)
	v_mfma_f32_16x16x32_bf16 v[0:3], v[114:117], v[56:59], v[0:3]
	v_mfma_f32_16x16x32_bf16 v[106:109], v[118:121], v[60:63], v[0:3]
	v_mfma_f32_16x16x32_bf16 v[0:3], v[166:169], v[56:59], v[4:7]
	v_mfma_f32_16x16x32_bf16 v[110:113], v[170:173], v[60:63], v[0:3]
	v_mfma_f32_16x16x32_bf16 v[0:3], v[114:117], v[94:97], v[8:11]
	v_mfma_f32_16x16x32_bf16 v[74:77], v[118:121], v[98:101], v[0:3]
	v_mfma_f32_16x16x32_bf16 v[0:3], v[166:169], v[94:97], v[12:15]
	v_mfma_f32_16x16x32_bf16 v[78:81], v[170:173], v[98:101], v[0:3]
	v_mfma_f32_16x16x32_bf16 v[0:3], v[114:117], v[102:105], v[16:19]
	v_mfma_f32_16x16x32_bf16 v[40:43], v[118:121], v[228:231], v[0:3]
	v_mfma_f32_16x16x32_bf16 v[0:3], v[166:169], v[102:105], v[20:23]
	v_mfma_f32_16x16x32_bf16 v[44:47], v[170:173], v[228:231], v[0:3]
	v_mfma_f32_16x16x32_bf16 v[0:3], v[114:117], v[238:241], v[24:27]
	v_mfma_f32_16x16x32_bf16 v[8:11], v[118:121], v[242:245], v[0:3]
	v_mfma_f32_16x16x32_bf16 v[0:3], v[166:169], v[238:241], v[28:31]
	v_mfma_f32_16x16x32_bf16 v[12:15], v[170:173], v[242:245], v[0:3]
	v_mfma_f32_16x16x32_bf16 v[0:3], v[194:197], v[56:59], v[32:35]
	v_mfma_f32_16x16x32_bf16 v[122:125], v[198:201], v[60:63], v[0:3]
	v_mfma_f32_16x16x32_bf16 v[0:3], v[202:205], v[56:59], v[36:39]
	v_mfma_f32_16x16x32_bf16 v[126:129], v[138:141], v[60:63], v[0:3]
	v_mfma_f32_16x16x32_bf16 v[0:3], v[194:197], v[94:97], v[174:177]
	v_mfma_f32_16x16x32_bf16 v[90:93], v[198:201], v[98:101], v[0:3]
	v_mfma_f32_16x16x32_bf16 v[0:3], v[202:205], v[94:97], v[178:181]
	v_mfma_f32_16x16x32_bf16 v[94:97], v[138:141], v[98:101], v[0:3]
	v_mfma_f32_16x16x32_bf16 v[0:3], v[194:197], v[102:105], v[48:51]
	v_mfma_f32_16x16x32_bf16 v[56:59], v[198:201], v[228:231], v[0:3]
	v_mfma_f32_16x16x32_bf16 v[0:3], v[202:205], v[102:105], v[52:55]
	v_mfma_f32_16x16x32_bf16 v[60:63], v[138:141], v[228:231], v[0:3]
	v_mfma_f32_16x16x32_bf16 v[0:3], v[194:197], v[238:241], v[182:185]
	v_mfma_f32_16x16x32_bf16 v[24:27], v[198:201], v[242:245], v[0:3]
	v_mfma_f32_16x16x32_bf16 v[0:3], v[202:205], v[238:241], v[186:189]
	v_mfma_f32_16x16x32_bf16 v[28:31], v[138:141], v[242:245], v[0:3]
	s_setprio 0
	s_barrier
	s_mov_b32 m0, s76
	s_nop 3
	v_lshl_add_u64 v[0:1], v[226:227], 0, s[96:97]
	s_add_u32 s20, s18, 0x40080
	ds_read_b128 v[16:19], v137 offset:49152
	ds_read_b128 v[20:23], v137 offset:50176
	ds_read_b128 v[48:51], v137 offset:51200
	ds_read_b128 v[52:55], v137 offset:52224
	ds_read_b128 v[174:177], v137 offset:53248
	ds_read_b128 v[178:181], v137 offset:54272
	ds_read_b128 v[182:185], v137 offset:55296
	ds_read_b128 v[186:189], v137 offset:56320
	global_load_lds_dwordx4 v[0:1], off
	v_lshl_add_u64 v[0:1], v[232:233], 0, s[96:97]
	s_mov_b32 m0, s66
	s_addc_u32 s21, s19, 0
	global_load_lds_dwordx4 v[0:1], off
	v_lshl_add_u64 v[0:1], s[20:21], 0, v[64:65]
	s_mov_b32 m0, s70
	s_nop 0
	global_load_lds_dwordx4 v[0:1], off
	v_lshl_add_u64 v[0:1], s[20:21], 0, v[134:135]
	s_mov_b32 m0, s71
	s_nop 0
	global_load_lds_dwordx4 v[0:1], off
	v_lshl_add_u64 v[0:1], v[236:237], 0, s[96:97]
	s_mov_b32 m0, s49
	s_nop 0
	global_load_lds_dwordx4 v[0:1], off
	v_lshl_add_u64 v[0:1], v[246:247], 0, s[96:97]
	s_mov_b32 m0, s51
	s_nop 0
	global_load_lds_dwordx4 v[0:1], off
	s_waitcnt vmcnt(8)
	s_waitcnt lgkmcnt(0)
	s_barrier
	s_setprio 1
	s_waitcnt lgkmcnt(0)
	v_mfma_f32_16x16x32_bf16 v[0:3], v[114:117], v[16:19], v[66:69]
	v_mfma_f32_16x16x32_bf16 v[98:101], v[118:121], v[20:23], v[0:3]
	v_mfma_f32_16x16x32_bf16 v[0:3], v[166:169], v[16:19], v[70:73]
	v_mfma_f32_16x16x32_bf16 v[102:105], v[170:173], v[20:23], v[0:3]
	v_mfma_f32_16x16x32_bf16 v[0:3], v[114:117], v[48:51], v[206:209]
	v_mfma_f32_16x16x32_bf16 v[66:69], v[118:121], v[52:55], v[0:3]
	v_mfma_f32_16x16x32_bf16 v[0:3], v[166:169], v[48:51], v[210:213]
	v_mfma_f32_16x16x32_bf16 v[70:73], v[170:173], v[52:55], v[0:3]
	v_mfma_f32_16x16x32_bf16 v[0:3], v[114:117], v[174:177], v[82:85]
	v_mfma_f32_16x16x32_bf16 v[32:35], v[118:121], v[178:181], v[0:3]
	v_mfma_f32_16x16x32_bf16 v[0:3], v[166:169], v[174:177], v[86:89]
	v_mfma_f32_16x16x32_bf16 v[36:39], v[170:173], v[178:181], v[0:3]
	v_mfma_f32_16x16x32_bf16 v[0:3], v[114:117], v[182:185], v[142:145]
	v_mfma_f32_16x16x32_bf16 v[4:7], v[166:169], v[182:185], v[146:149]
	v_mfma_f32_16x16x32_bf16 v[0:3], v[118:121], v[186:189], v[0:3]
	v_mfma_f32_16x16x32_bf16 v[4:7], v[170:173], v[186:189], v[4:7]
	v_mfma_f32_16x16x32_bf16 v[82:85], v[194:197], v[16:19], v[150:153]
	v_mfma_f32_16x16x32_bf16 v[16:19], v[202:205], v[16:19], v[154:157]
	v_mfma_f32_16x16x32_bf16 v[118:121], v[138:141], v[20:23], v[16:19]
	v_mfma_f32_16x16x32_bf16 v[16:19], v[194:197], v[48:51], v[214:217]
	v_mfma_f32_16x16x32_bf16 v[114:117], v[198:201], v[20:23], v[82:85]
	v_mfma_f32_16x16x32_bf16 v[82:85], v[198:201], v[52:55], v[16:19]
	v_mfma_f32_16x16x32_bf16 v[16:19], v[202:205], v[48:51], v[218:221]
	v_mfma_f32_16x16x32_bf16 v[86:89], v[138:141], v[52:55], v[16:19]
	v_mfma_f32_16x16x32_bf16 v[16:19], v[194:197], v[174:177], v[222:225]
	v_mfma_f32_16x16x32_bf16 v[48:51], v[198:201], v[178:181], v[16:19]
	v_mfma_f32_16x16x32_bf16 v[16:19], v[202:205], v[174:177], v[190:193]
	v_mfma_f32_16x16x32_bf16 v[52:55], v[138:141], v[178:181], v[16:19]
	v_mfma_f32_16x16x32_bf16 v[16:19], v[194:197], v[182:185], v[158:161]
	v_mfma_f32_16x16x32_bf16 v[20:23], v[202:205], v[182:185], v[162:165]
	v_mfma_f32_16x16x32_bf16 v[16:19], v[198:201], v[186:189], v[16:19]
	v_mfma_f32_16x16x32_bf16 v[20:23], v[138:141], v[186:189], v[20:23]
	s_setprio 0
	s_barrier
	s_andn2_b64 vcc, exec, s[10:11]
	v_mov_b64_e32 v[250:251], 0xff
	s_cbranch_vccnz .LBB0_1894
	s_barrier

.LBB0_2425:
	s_add_u32 s28, s24, 0xfffc0080
	s_addc_u32 s29, s25, -1
	s_add_i32 s56, 0, 0x10000
	s_cmp_eq_u32 s55, 12
	s_cselect_b32 s35, s15, s29
	s_cselect_b32 s34, s21, s28
	s_cselect_b32 s29, s13, s54
	s_cselect_b32 s28, s52, s53
	s_add_i32 s58, 0, 0x14000
	v_add_u32_e32 v154, s56, v144
	v_add_u32_e32 v170, s58, v144
	ds_read_b128 v[140:143], v154
	ds_read_b128 v[146:149], v154 offset:1024
	ds_read_b128 v[150:153], v154 offset:2048
	ds_read_b128 v[154:157], v154 offset:3072
	ds_read_b128 v[158:161], v170
	ds_read_b128 v[162:165], v170 offset:1024
	ds_read_b128 v[166:169], v170 offset:2048
	ds_read_b128 v[170:173], v170 offset:3072
	v_lshl_add_u64 v[206:207], s[24:25], 0, v[136:137]
	s_add_i32 m0, s41, 0xc000
	ds_read_b128 v[174:177], v145
	ds_read_b128 v[178:181], v145 offset:1024
	ds_read_b128 v[182:185], v145 offset:2048
	ds_read_b128 v[186:189], v145 offset:3072
	ds_read_b128 v[190:193], v145 offset:4096
	ds_read_b128 v[194:197], v145 offset:5120
	ds_read_b128 v[198:201], v145 offset:6144
	ds_read_b128 v[202:205], v145 offset:7168
	global_load_lds_dwordx4 v[206:207], off
	v_lshl_add_u64 v[206:207], s[24:25], 0, v[138:139]
	s_add_i32 m0, s41, 0xe000
	s_nop 0
	global_load_lds_dwordx4 v[206:207], off
	s_waitcnt vmcnt(8)
	s_waitcnt lgkmcnt(0)
	s_barrier
	s_setprio 1
	s_waitcnt lgkmcnt(0)
	v_mfma_f32_16x16x32_bf16 v[126:129], v[140:143], v[174:177], v[126:129]
	v_mfma_f32_16x16x32_bf16 v[122:125], v[150:153], v[174:177], v[122:125]
	v_mfma_f32_16x16x32_bf16 v[110:113], v[140:143], v[182:185], v[110:113]
	v_mfma_f32_16x16x32_bf16 v[106:109], v[150:153], v[182:185], v[106:109]
	v_mfma_f32_16x16x32_bf16 v[94:97], v[140:143], v[190:193], v[94:97]
	v_mfma_f32_16x16x32_bf16 v[90:93], v[150:153], v[190:193], v[90:93]
	v_mfma_f32_16x16x32_bf16 v[78:81], v[140:143], v[198:201], v[78:81]
	v_mfma_f32_16x16x32_bf16 v[74:77], v[150:153], v[198:201], v[74:77]
	v_mfma_f32_16x16x32_bf16 v[126:129], v[146:149], v[178:181], v[126:129]
	v_mfma_f32_16x16x32_bf16 v[122:125], v[154:157], v[178:181], v[122:125]
	v_mfma_f32_16x16x32_bf16 v[110:113], v[146:149], v[186:189], v[110:113]
	v_mfma_f32_16x16x32_bf16 v[106:109], v[154:157], v[186:189], v[106:109]
	v_mfma_f32_16x16x32_bf16 v[94:97], v[146:149], v[194:197], v[94:97]
	v_mfma_f32_16x16x32_bf16 v[90:93], v[154:157], v[194:197], v[90:93]
	v_mfma_f32_16x16x32_bf16 v[78:81], v[146:149], v[202:205], v[78:81]
	v_mfma_f32_16x16x32_bf16 v[74:77], v[154:157], v[202:205], v[74:77]
	v_mfma_f32_16x16x32_bf16 v[118:121], v[158:161], v[174:177], v[118:121]
	v_mfma_f32_16x16x32_bf16 v[114:117], v[166:169], v[174:177], v[114:117]
	v_mfma_f32_16x16x32_bf16 v[102:105], v[158:161], v[182:185], v[102:105]
	v_mfma_f32_16x16x32_bf16 v[98:101], v[166:169], v[182:185], v[98:101]
	v_mfma_f32_16x16x32_bf16 v[86:89], v[158:161], v[190:193], v[86:89]
	v_mfma_f32_16x16x32_bf16 v[82:85], v[166:169], v[190:193], v[82:85]
	v_mfma_f32_16x16x32_bf16 v[70:73], v[158:161], v[198:201], v[70:73]
	v_mfma_f32_16x16x32_bf16 v[66:69], v[166:169], v[198:201], v[66:69]
	v_mfma_f32_16x16x32_bf16 v[118:121], v[162:165], v[178:181], v[118:121]
	v_mfma_f32_16x16x32_bf16 v[114:117], v[170:173], v[178:181], v[114:117]
	v_mfma_f32_16x16x32_bf16 v[102:105], v[162:165], v[186:189], v[102:105]
	v_mfma_f32_16x16x32_bf16 v[98:101], v[170:173], v[186:189], v[98:101]
	v_mfma_f32_16x16x32_bf16 v[86:89], v[162:165], v[194:197], v[86:89]
	v_mfma_f32_16x16x32_bf16 v[82:85], v[170:173], v[194:197], v[82:85]
	v_mfma_f32_16x16x32_bf16 v[70:73], v[162:165], v[202:205], v[70:73]
	v_mfma_f32_16x16x32_bf16 v[66:69], v[170:173], v[202:205], v[66:69]
	s_setprio 0
	s_barrier
	s_add_i32 s56, s56, s38
	v_lshl_add_u64 v[206:207], s[28:29], 0, v[64:65]
	s_mov_b32 m0, s56
	ds_read_b128 v[174:177], v145 offset:16384
	ds_read_b128 v[178:181], v145 offset:17408
	ds_read_b128 v[182:185], v145 offset:18432
	ds_read_b128 v[186:189], v145 offset:19456
	ds_read_b128 v[190:193], v145 offset:20480
	ds_read_b128 v[194:197], v145 offset:21504
	ds_read_b128 v[198:201], v145 offset:22528
	ds_read_b128 v[202:205], v145 offset:23552
	global_load_lds_dwordx4 v[206:207], off
	s_add_i32 m0, s56, 0x2000
	s_add_u32 s56, s28, 0x40000
	v_lshl_add_u64 v[208:209], s[28:29], 0, v[130:131]
	s_addc_u32 s57, s29, 0
	s_add_i32 s58, s58, s38
	global_load_lds_dwordx4 v[208:209], off
	v_lshl_add_u64 v[210:211], s[56:57], 0, v[64:65]
	s_mov_b32 m0, s58
	v_lshl_add_u64 v[212:213], s[34:35], 0, v[132:133]
	global_load_lds_dwordx4 v[210:211], off
	v_lshl_add_u64 v[210:211], s[56:57], 0, v[130:131]
	s_add_i32 m0, s58, 0x2000
	s_nop 0
	global_load_lds_dwordx4 v[210:211], off
	v_lshl_add_u64 v[210:211], s[34:35], 0, v[134:135]
	s_mov_b32 m0, s41
	s_nop 0
	global_load_lds_dwordx4 v[210:211], off
	s_mov_b32 m0, s23
	s_nop 0
	global_load_lds_dwordx4 v[212:213], off
	s_waitcnt vmcnt(8)
	s_waitcnt lgkmcnt(0)
	s_barrier
	s_setprio 1
	s_waitcnt lgkmcnt(0)
	v_mfma_f32_16x16x32_bf16 v[60:63], v[140:143], v[174:177], v[60:63]
	v_mfma_f32_16x16x32_bf16 v[56:59], v[150:153], v[174:177], v[56:59]
	v_mfma_f32_16x16x32_bf16 v[44:47], v[140:143], v[182:185], v[44:47]
	v_mfma_f32_16x16x32_bf16 v[40:43], v[150:153], v[182:185], v[40:43]
	v_mfma_f32_16x16x32_bf16 v[28:31], v[140:143], v[190:193], v[28:31]
	v_mfma_f32_16x16x32_bf16 v[24:27], v[150:153], v[190:193], v[24:27]
	v_mfma_f32_16x16x32_bf16 v[12:15], v[140:143], v[198:201], v[12:15]
	v_mfma_f32_16x16x32_bf16 v[8:11], v[150:153], v[198:201], v[8:11]
	v_mfma_f32_16x16x32_bf16 v[60:63], v[146:149], v[178:181], v[60:63]
	v_mfma_f32_16x16x32_bf16 v[56:59], v[154:157], v[178:181], v[56:59]
	v_mfma_f32_16x16x32_bf16 v[44:47], v[146:149], v[186:189], v[44:47]
	v_mfma_f32_16x16x32_bf16 v[40:43], v[154:157], v[186:189], v[40:43]
	v_mfma_f32_16x16x32_bf16 v[28:31], v[146:149], v[194:197], v[28:31]
	v_mfma_f32_16x16x32_bf16 v[24:27], v[154:157], v[194:197], v[24:27]
	v_mfma_f32_16x16x32_bf16 v[12:15], v[146:149], v[202:205], v[12:15]
	v_mfma_f32_16x16x32_bf16 v[8:11], v[154:157], v[202:205], v[8:11]
	v_mfma_f32_16x16x32_bf16 v[52:55], v[158:161], v[174:177], v[52:55]
	v_mfma_f32_16x16x32_bf16 v[48:51], v[166:169], v[174:177], v[48:51]
	v_mfma_f32_16x16x32_bf16 v[36:39], v[158:161], v[182:185], v[36:39]
	v_mfma_f32_16x16x32_bf16 v[32:35], v[166:169], v[182:185], v[32:35]
	v_mfma_f32_16x16x32_bf16 v[20:23], v[158:161], v[190:193], v[20:23]
	v_mfma_f32_16x16x32_bf16 v[16:19], v[166:169], v[190:193], v[16:19]
	v_mfma_f32_16x16x32_bf16 v[4:7], v[158:161], v[198:201], v[4:7]
	v_mfma_f32_16x16x32_bf16 v[0:3], v[166:169], v[198:201], v[0:3]
	v_mfma_f32_16x16x32_bf16 v[52:55], v[162:165], v[178:181], v[52:55]
	v_mfma_f32_16x16x32_bf16 v[48:51], v[170:173], v[178:181], v[48:51]
	v_mfma_f32_16x16x32_bf16 v[36:39], v[162:165], v[186:189], v[36:39]
	v_mfma_f32_16x16x32_bf16 v[32:35], v[170:173], v[186:189], v[32:35]
	v_mfma_f32_16x16x32_bf16 v[20:23], v[162:165], v[194:197], v[20:23]
	v_mfma_f32_16x16x32_bf16 v[16:19], v[170:173], v[194:197], v[16:19]
	v_mfma_f32_16x16x32_bf16 v[4:7], v[162:165], v[202:205], v[4:7]
	v_mfma_f32_16x16x32_bf16 v[0:3], v[170:173], v[202:205], v[0:3]
	s_setprio 0
	s_barrier
	s_add_i32 s56, 0, 0x18000
	s_add_i32 s57, 0, 0x1c000
	v_add_u32_e32 v154, s56, v144
	v_add_u32_e32 v170, s57, v144
	ds_read_b128 v[140:143], v154
	ds_read_b128 v[146:149], v154 offset:1024
	ds_read_b128 v[150:153], v154 offset:2048
	ds_read_b128 v[154:157], v154 offset:3072
	ds_read_b128 v[158:161], v170
	ds_read_b128 v[162:165], v170 offset:1024
	ds_read_b128 v[166:169], v170 offset:2048
	ds_read_b128 v[170:173], v170 offset:3072
	s_add_u32 s34, s34, 0x40000
	s_addc_u32 s35, s35, 0
	s_mov_b32 m0, s43
	v_lshl_add_u64 v[214:215], s[34:35], 0, v[134:135]
	ds_read_b128 v[174:177], v145 offset:32768
	ds_read_b128 v[178:181], v145 offset:33792
	ds_read_b128 v[182:185], v145 offset:34816
	ds_read_b128 v[186:189], v145 offset:35840
	ds_read_b128 v[190:193], v145 offset:36864
	ds_read_b128 v[194:197], v145 offset:37888
	ds_read_b128 v[198:201], v145 offset:38912
	ds_read_b128 v[202:205], v145 offset:39936
	global_load_lds_dwordx4 v[214:215], off
	v_lshl_add_u64 v[214:215], s[34:35], 0, v[132:133]
	s_mov_b32 m0, s44
	s_nop 0
	global_load_lds_dwordx4 v[214:215], off
	s_waitcnt vmcnt(8)
	s_waitcnt lgkmcnt(0)
	s_barrier
	s_setprio 1
	s_waitcnt lgkmcnt(0)
	v_mfma_f32_16x16x32_bf16 v[126:129], v[140:143], v[174:177], v[126:129]
	v_mfma_f32_16x16x32_bf16 v[122:125], v[150:153], v[174:177], v[122:125]
	v_mfma_f32_16x16x32_bf16 v[110:113], v[140:143], v[182:185], v[110:113]
	v_mfma_f32_16x16x32_bf16 v[106:109], v[150:153], v[182:185], v[106:109]
	v_mfma_f32_16x16x32_bf16 v[94:97], v[140:143], v[190:193], v[94:97]
	v_mfma_f32_16x16x32_bf16 v[90:93], v[150:153], v[190:193], v[90:93]
	v_mfma_f32_16x16x32_bf16 v[78:81], v[140:143], v[198:201], v[78:81]
	v_mfma_f32_16x16x32_bf16 v[74:77], v[150:153], v[198:201], v[74:77]
	v_mfma_f32_16x16x32_bf16 v[126:129], v[146:149], v[178:181], v[126:129]
	v_mfma_f32_16x16x32_bf16 v[122:125], v[154:157], v[178:181], v[122:125]
	v_mfma_f32_16x16x32_bf16 v[110:113], v[146:149], v[186:189], v[110:113]
	v_mfma_f32_16x16x32_bf16 v[106:109], v[154:157], v[186:189], v[106:109]
	v_mfma_f32_16x16x32_bf16 v[94:97], v[146:149], v[194:197], v[94:97]
	v_mfma_f32_16x16x32_bf16 v[90:93], v[154:157], v[194:197], v[90:93]
	v_mfma_f32_16x16x32_bf16 v[78:81], v[146:149], v[202:205], v[78:81]
	v_mfma_f32_16x16x32_bf16 v[74:77], v[154:157], v[202:205], v[74:77]
	v_mfma_f32_16x16x32_bf16 v[118:121], v[158:161], v[174:177], v[118:121]
	v_mfma_f32_16x16x32_bf16 v[114:117], v[166:169], v[174:177], v[114:117]
	v_mfma_f32_16x16x32_bf16 v[102:105], v[158:161], v[182:185], v[102:105]
	v_mfma_f32_16x16x32_bf16 v[98:101], v[166:169], v[182:185], v[98:101]
	v_mfma_f32_16x16x32_bf16 v[86:89], v[158:161], v[190:193], v[86:89]
	v_mfma_f32_16x16x32_bf16 v[82:85], v[166:169], v[190:193], v[82:85]
	v_mfma_f32_16x16x32_bf16 v[70:73], v[158:161], v[198:201], v[70:73]
	v_mfma_f32_16x16x32_bf16 v[66:69], v[166:169], v[198:201], v[66:69]
	v_mfma_f32_16x16x32_bf16 v[118:121], v[162:165], v[178:181], v[118:121]
	v_mfma_f32_16x16x32_bf16 v[114:117], v[170:173], v[178:181], v[114:117]
	v_mfma_f32_16x16x32_bf16 v[102:105], v[162:165], v[186:189], v[102:105]
	v_mfma_f32_16x16x32_bf16 v[98:101], v[170:173], v[186:189], v[98:101]
	v_mfma_f32_16x16x32_bf16 v[86:89], v[162:165], v[194:197], v[86:89]
	v_mfma_f32_16x16x32_bf16 v[82:85], v[170:173], v[194:197], v[82:85]
	v_mfma_f32_16x16x32_bf16 v[70:73], v[162:165], v[202:205], v[70:73]
	v_mfma_f32_16x16x32_bf16 v[66:69], v[170:173], v[202:205], v[66:69]
	s_setprio 0
	s_barrier
	s_add_i32 s34, s56, s38
	v_lshl_add_u64 v[206:207], v[206:207], 0, s[96:97]
	s_mov_b32 m0, s34
	ds_read_b128 v[174:177], v145 offset:49152
	ds_read_b128 v[178:181], v145 offset:50176
	ds_read_b128 v[182:185], v145 offset:51200
	ds_read_b128 v[186:189], v145 offset:52224
	ds_read_b128 v[190:193], v145 offset:53248
	ds_read_b128 v[194:197], v145 offset:54272
	ds_read_b128 v[198:201], v145 offset:55296
	ds_read_b128 v[202:205], v145 offset:56320
	global_load_lds_dwordx4 v[206:207], off
	s_add_i32 m0, s34, 0x2000
	s_add_u32 s28, s28, 0x40080
	v_lshl_add_u64 v[206:207], v[208:209], 0, s[96:97]
	s_addc_u32 s29, s29, 0
	s_add_i32 s34, s57, s38
	global_load_lds_dwordx4 v[206:207], off
	v_lshl_add_u64 v[206:207], s[28:29], 0, v[64:65]
	s_mov_b32 m0, s34
	s_nop 0
	global_load_lds_dwordx4 v[206:207], off
	v_lshl_add_u64 v[206:207], s[28:29], 0, v[130:131]
	s_add_i32 m0, s34, 0x2000
	s_nop 0
	global_load_lds_dwordx4 v[206:207], off
	v_lshl_add_u64 v[206:207], v[210:211], 0, s[96:97]
	s_mov_b32 m0, s48
	s_nop 0
	global_load_lds_dwordx4 v[206:207], off
	v_lshl_add_u64 v[206:207], v[212:213], 0, s[96:97]
	s_mov_b32 m0, s49
	s_nop 0
	global_load_lds_dwordx4 v[206:207], off
	s_waitcnt vmcnt(8)
	s_waitcnt lgkmcnt(0)
	s_barrier
	s_setprio 1
	s_waitcnt lgkmcnt(0)
	v_mfma_f32_16x16x32_bf16 v[60:63], v[140:143], v[174:177], v[60:63]
	v_mfma_f32_16x16x32_bf16 v[56:59], v[150:153], v[174:177], v[56:59]
	v_mfma_f32_16x16x32_bf16 v[44:47], v[140:143], v[182:185], v[44:47]
	v_mfma_f32_16x16x32_bf16 v[40:43], v[150:153], v[182:185], v[40:43]
	v_mfma_f32_16x16x32_bf16 v[28:31], v[140:143], v[190:193], v[28:31]
	v_mfma_f32_16x16x32_bf16 v[24:27], v[150:153], v[190:193], v[24:27]
	v_mfma_f32_16x16x32_bf16 v[12:15], v[140:143], v[198:201], v[12:15]
	v_mfma_f32_16x16x32_bf16 v[8:11], v[150:153], v[198:201], v[8:11]
	v_mfma_f32_16x16x32_bf16 v[60:63], v[146:149], v[178:181], v[60:63]
	v_mfma_f32_16x16x32_bf16 v[56:59], v[154:157], v[178:181], v[56:59]
	v_mfma_f32_16x16x32_bf16 v[44:47], v[146:149], v[186:189], v[44:47]
	v_mfma_f32_16x16x32_bf16 v[40:43], v[154:157], v[186:189], v[40:43]
	v_mfma_f32_16x16x32_bf16 v[28:31], v[146:149], v[194:197], v[28:31]
	v_mfma_f32_16x16x32_bf16 v[24:27], v[154:157], v[194:197], v[24:27]
	v_mfma_f32_16x16x32_bf16 v[12:15], v[146:149], v[202:205], v[12:15]
	v_mfma_f32_16x16x32_bf16 v[8:11], v[154:157], v[202:205], v[8:11]
	v_mfma_f32_16x16x32_bf16 v[52:55], v[158:161], v[174:177], v[52:55]
	v_mfma_f32_16x16x32_bf16 v[48:51], v[166:169], v[174:177], v[48:51]
	v_mfma_f32_16x16x32_bf16 v[36:39], v[158:161], v[182:185], v[36:39]
	v_mfma_f32_16x16x32_bf16 v[32:35], v[166:169], v[182:185], v[32:35]
	v_mfma_f32_16x16x32_bf16 v[20:23], v[158:161], v[190:193], v[20:23]
	v_mfma_f32_16x16x32_bf16 v[16:19], v[166:169], v[190:193], v[16:19]
	v_mfma_f32_16x16x32_bf16 v[4:7], v[158:161], v[198:201], v[4:7]
	v_mfma_f32_16x16x32_bf16 v[0:3], v[166:169], v[198:201], v[0:3]
	v_mfma_f32_16x16x32_bf16 v[52:55], v[162:165], v[178:181], v[52:55]
	v_mfma_f32_16x16x32_bf16 v[48:51], v[170:173], v[178:181], v[48:51]
	v_mfma_f32_16x16x32_bf16 v[36:39], v[162:165], v[186:189], v[36:39]
	v_mfma_f32_16x16x32_bf16 v[32:35], v[170:173], v[186:189], v[32:35]
	v_mfma_f32_16x16x32_bf16 v[20:23], v[162:165], v[194:197], v[20:23]
	v_mfma_f32_16x16x32_bf16 v[16:19], v[170:173], v[194:197], v[16:19]
	v_mfma_f32_16x16x32_bf16 v[4:7], v[162:165], v[202:205], v[4:7]
	v_mfma_f32_16x16x32_bf16 v[0:3], v[170:173], v[202:205], v[0:3]
	s_setprio 0
	s_barrier
	s_add_i32 s55, s55, 2
	s_add_u32 s24, s24, 0x100
	s_addc_u32 s25, s25, 0
	s_add_u32 s53, s53, 0x100
	s_addc_u32 s54, s54, 0
	s_cmp_gt_u32 s55, 13
	s_cbranch_scc0 .LBB0_2425
	s_and_b64 vcc, exec, s[10:11]
	s_cbranch_vccz .LBB0_2428
	s_barrier

.LBB0_2501:
	s_add_u32 s16, s14, 0x100
	s_addc_u32 s17, s15, 0
	s_add_i32 s54, 0, 0x10000
	s_cmp_eq_u32 s53, 40
	s_cselect_b32 s21, s7, s17
	s_cselect_b32 s20, s6, s16
	s_cselect_b32 s19, s13, s52
	s_cselect_b32 s18, s12, s47
	s_add_i32 s55, 0, 0x14000
	v_add_u32_e32 v142, s54, v158
	v_add_u32_e32 v156, s55, v158
	ds_read_b128 v[130:133], v142
	ds_read_b128 v[134:137], v142 offset:1024
	ds_read_b128 v[138:141], v142 offset:2048
	ds_read_b128 v[142:145], v142 offset:3072
	ds_read_b128 v[160:163], v156
	ds_read_b128 v[164:167], v156 offset:1024
	ds_read_b128 v[168:171], v156 offset:2048
	ds_read_b128 v[172:175], v156 offset:3072
	v_lshl_add_u64 v[156:157], s[14:15], 0, v[152:153]
	s_add_i32 m0, s27, 0xc000
	ds_read_b128 v[176:179], v159
	ds_read_b128 v[180:183], v159 offset:1024
	ds_read_b128 v[184:187], v159 offset:2048
	ds_read_b128 v[188:191], v159 offset:3072
	ds_read_b128 v[192:195], v159 offset:4096
	ds_read_b128 v[196:199], v159 offset:5120
	ds_read_b128 v[200:203], v159 offset:6144
	ds_read_b128 v[204:207], v159 offset:7168
	global_load_lds_dwordx4 v[156:157], off
	v_lshl_add_u64 v[156:157], s[14:15], 0, v[154:155]
	s_add_i32 m0, s27, 0xe000
	s_nop 0
	global_load_lds_dwordx4 v[156:157], off
	s_waitcnt vmcnt(8)
	s_waitcnt lgkmcnt(0)
	s_barrier
	s_setprio 1
	s_waitcnt lgkmcnt(0)
	v_mfma_f32_16x16x32_bf16 v[126:129], v[130:133], v[176:179], v[126:129]
	v_mfma_f32_16x16x32_bf16 v[122:125], v[138:141], v[176:179], v[122:125]
	v_mfma_f32_16x16x32_bf16 v[118:121], v[130:133], v[184:187], v[118:121]
	v_mfma_f32_16x16x32_bf16 v[110:113], v[138:141], v[184:187], v[110:113]
	v_mfma_f32_16x16x32_bf16 v[98:101], v[130:133], v[192:195], v[98:101]
	v_mfma_f32_16x16x32_bf16 v[90:93], v[138:141], v[192:195], v[90:93]
	v_mfma_f32_16x16x32_bf16 v[82:85], v[130:133], v[200:203], v[82:85]
	v_mfma_f32_16x16x32_bf16 v[74:77], v[138:141], v[200:203], v[74:77]
	v_mfma_f32_16x16x32_bf16 v[126:129], v[134:137], v[180:183], v[126:129]
	v_mfma_f32_16x16x32_bf16 v[122:125], v[142:145], v[180:183], v[122:125]
	v_mfma_f32_16x16x32_bf16 v[118:121], v[134:137], v[188:191], v[118:121]
	v_mfma_f32_16x16x32_bf16 v[110:113], v[142:145], v[188:191], v[110:113]
	v_mfma_f32_16x16x32_bf16 v[98:101], v[134:137], v[196:199], v[98:101]
	v_mfma_f32_16x16x32_bf16 v[90:93], v[142:145], v[196:199], v[90:93]
	v_mfma_f32_16x16x32_bf16 v[82:85], v[134:137], v[204:207], v[82:85]
	v_mfma_f32_16x16x32_bf16 v[74:77], v[142:145], v[204:207], v[74:77]
	v_mfma_f32_16x16x32_bf16 v[114:117], v[160:163], v[176:179], v[114:117]
	v_mfma_f32_16x16x32_bf16 v[106:109], v[168:171], v[176:179], v[106:109]
	v_mfma_f32_16x16x32_bf16 v[102:105], v[160:163], v[184:187], v[102:105]
	v_mfma_f32_16x16x32_bf16 v[94:97], v[168:171], v[184:187], v[94:97]
	v_mfma_f32_16x16x32_bf16 v[86:89], v[160:163], v[192:195], v[86:89]
	v_mfma_f32_16x16x32_bf16 v[78:81], v[168:171], v[192:195], v[78:81]
	v_mfma_f32_16x16x32_bf16 v[70:73], v[160:163], v[200:203], v[70:73]
	v_mfma_f32_16x16x32_bf16 v[66:69], v[168:171], v[200:203], v[66:69]
	v_mfma_f32_16x16x32_bf16 v[114:117], v[164:167], v[180:183], v[114:117]
	v_mfma_f32_16x16x32_bf16 v[106:109], v[172:175], v[180:183], v[106:109]
	v_mfma_f32_16x16x32_bf16 v[102:105], v[164:167], v[188:191], v[102:105]
	v_mfma_f32_16x16x32_bf16 v[94:97], v[172:175], v[188:191], v[94:97]
	v_mfma_f32_16x16x32_bf16 v[86:89], v[164:167], v[196:199], v[86:89]
	v_mfma_f32_16x16x32_bf16 v[78:81], v[172:175], v[196:199], v[78:81]
	v_mfma_f32_16x16x32_bf16 v[70:73], v[164:167], v[204:207], v[70:73]
	v_mfma_f32_16x16x32_bf16 v[66:69], v[172:175], v[204:207], v[66:69]
	s_setprio 0
	s_barrier
	s_add_i32 s14, s54, s26
	v_lshl_add_u64 v[156:157], s[18:19], 0, v[64:65]
	s_mov_b32 m0, s14
	ds_read_b128 v[176:179], v159 offset:16384
	ds_read_b128 v[180:183], v159 offset:17408
	ds_read_b128 v[184:187], v159 offset:18432
	ds_read_b128 v[188:191], v159 offset:19456
	ds_read_b128 v[192:195], v159 offset:20480
	ds_read_b128 v[196:199], v159 offset:21504
	ds_read_b128 v[200:203], v159 offset:22528
	ds_read_b128 v[204:207], v159 offset:23552
	global_load_lds_dwordx4 v[156:157], off
	s_add_i32 m0, s14, 0x2000
	s_add_u32 s14, s18, 0xb0000
	v_lshl_add_u64 v[208:209], s[18:19], 0, v[146:147]
	s_addc_u32 s15, s19, 0
	s_add_i32 s54, s55, s26
	global_load_lds_dwordx4 v[208:209], off
	v_lshl_add_u64 v[210:211], s[14:15], 0, v[64:65]
	s_mov_b32 m0, s54
	v_lshl_add_u64 v[212:213], s[20:21], 0, v[148:149]
	global_load_lds_dwordx4 v[210:211], off
	v_lshl_add_u64 v[210:211], s[14:15], 0, v[146:147]
	s_add_i32 m0, s54, 0x2000
	s_nop 0
	global_load_lds_dwordx4 v[210:211], off
	v_lshl_add_u64 v[210:211], s[20:21], 0, v[150:151]
	s_mov_b32 m0, s27
	s_nop 0
	global_load_lds_dwordx4 v[210:211], off
	s_mov_b32 m0, s28
	s_nop 0
	global_load_lds_dwordx4 v[212:213], off
	s_waitcnt vmcnt(8)
	s_waitcnt lgkmcnt(0)
	s_barrier
	s_setprio 1
	s_waitcnt lgkmcnt(0)
	v_mfma_f32_16x16x32_bf16 v[60:63], v[130:133], v[176:179], v[60:63]
	v_mfma_f32_16x16x32_bf16 v[56:59], v[138:141], v[176:179], v[56:59]
	v_mfma_f32_16x16x32_bf16 v[48:51], v[130:133], v[184:187], v[48:51]
	v_mfma_f32_16x16x32_bf16 v[40:43], v[138:141], v[184:187], v[40:43]
	v_mfma_f32_16x16x32_bf16 v[32:35], v[130:133], v[192:195], v[32:35]
	v_mfma_f32_16x16x32_bf16 v[24:27], v[138:141], v[192:195], v[24:27]
	v_mfma_f32_16x16x32_bf16 v[16:19], v[130:133], v[200:203], v[16:19]
	v_mfma_f32_16x16x32_bf16 v[8:11], v[138:141], v[200:203], v[8:11]
	v_mfma_f32_16x16x32_bf16 v[60:63], v[134:137], v[180:183], v[60:63]
	v_mfma_f32_16x16x32_bf16 v[56:59], v[142:145], v[180:183], v[56:59]
	v_mfma_f32_16x16x32_bf16 v[48:51], v[134:137], v[188:191], v[48:51]
	v_mfma_f32_16x16x32_bf16 v[40:43], v[142:145], v[188:191], v[40:43]
	v_mfma_f32_16x16x32_bf16 v[32:35], v[134:137], v[196:199], v[32:35]
	v_mfma_f32_16x16x32_bf16 v[24:27], v[142:145], v[196:199], v[24:27]
	v_mfma_f32_16x16x32_bf16 v[16:19], v[134:137], v[204:207], v[16:19]
	v_mfma_f32_16x16x32_bf16 v[8:11], v[142:145], v[204:207], v[8:11]
	v_mfma_f32_16x16x32_bf16 v[52:55], v[160:163], v[176:179], v[52:55]
	v_mfma_f32_16x16x32_bf16 v[44:47], v[168:171], v[176:179], v[44:47]
	v_mfma_f32_16x16x32_bf16 v[36:39], v[160:163], v[184:187], v[36:39]
	v_mfma_f32_16x16x32_bf16 v[28:31], v[168:171], v[184:187], v[28:31]
	v_mfma_f32_16x16x32_bf16 v[20:23], v[160:163], v[192:195], v[20:23]
	v_mfma_f32_16x16x32_bf16 v[12:15], v[168:171], v[192:195], v[12:15]
	v_mfma_f32_16x16x32_bf16 v[4:7], v[160:163], v[200:203], v[4:7]
	v_mfma_f32_16x16x32_bf16 v[0:3], v[168:171], v[200:203], v[0:3]
	v_mfma_f32_16x16x32_bf16 v[52:55], v[164:167], v[180:183], v[52:55]
	v_mfma_f32_16x16x32_bf16 v[44:47], v[172:175], v[180:183], v[44:47]
	v_mfma_f32_16x16x32_bf16 v[36:39], v[164:167], v[188:191], v[36:39]
	v_mfma_f32_16x16x32_bf16 v[28:31], v[172:175], v[188:191], v[28:31]
	v_mfma_f32_16x16x32_bf16 v[20:23], v[164:167], v[196:199], v[20:23]
	v_mfma_f32_16x16x32_bf16 v[12:15], v[172:175], v[196:199], v[12:15]
	v_mfma_f32_16x16x32_bf16 v[4:7], v[164:167], v[204:207], v[4:7]
	v_mfma_f32_16x16x32_bf16 v[0:3], v[172:175], v[204:207], v[0:3]
	s_setprio 0
	s_barrier
	s_add_i32 s54, 0, 0x18000
	s_add_i32 s55, 0, 0x1c000
	v_add_u32_e32 v142, s54, v158
	v_add_u32_e32 v172, s55, v158
	ds_read_b128 v[130:133], v142
	ds_read_b128 v[134:137], v142 offset:1024
	ds_read_b128 v[138:141], v142 offset:2048
	ds_read_b128 v[142:145], v142 offset:3072
	ds_read_b128 v[160:163], v172
	ds_read_b128 v[164:167], v172 offset:1024
	ds_read_b128 v[168:171], v172 offset:2048
	ds_read_b128 v[172:175], v172 offset:3072
	s_add_u32 s14, s20, 0xb0000
	s_addc_u32 s15, s21, 0
	s_mov_b32 m0, s29
	v_lshl_add_u64 v[214:215], s[14:15], 0, v[150:151]
	ds_read_b128 v[176:179], v159 offset:32768
	ds_read_b128 v[180:183], v159 offset:33792
	ds_read_b128 v[184:187], v159 offset:34816
	ds_read_b128 v[188:191], v159 offset:35840
	ds_read_b128 v[192:195], v159 offset:36864
	ds_read_b128 v[196:199], v159 offset:37888
	ds_read_b128 v[200:203], v159 offset:38912
	ds_read_b128 v[204:207], v159 offset:39936
	global_load_lds_dwordx4 v[214:215], off
	v_lshl_add_u64 v[214:215], s[14:15], 0, v[148:149]
	s_mov_b32 m0, s31
	s_nop 0
	global_load_lds_dwordx4 v[214:215], off
	s_waitcnt vmcnt(8)
	s_waitcnt lgkmcnt(0)
	s_barrier
	s_setprio 1
	s_waitcnt lgkmcnt(0)
	v_mfma_f32_16x16x32_bf16 v[126:129], v[130:133], v[176:179], v[126:129]
	v_mfma_f32_16x16x32_bf16 v[122:125], v[138:141], v[176:179], v[122:125]
	v_mfma_f32_16x16x32_bf16 v[118:121], v[130:133], v[184:187], v[118:121]
	v_mfma_f32_16x16x32_bf16 v[110:113], v[138:141], v[184:187], v[110:113]
	v_mfma_f32_16x16x32_bf16 v[98:101], v[130:133], v[192:195], v[98:101]
	v_mfma_f32_16x16x32_bf16 v[90:93], v[138:141], v[192:195], v[90:93]
	v_mfma_f32_16x16x32_bf16 v[82:85], v[130:133], v[200:203], v[82:85]
	v_mfma_f32_16x16x32_bf16 v[74:77], v[138:141], v[200:203], v[74:77]
	v_mfma_f32_16x16x32_bf16 v[126:129], v[134:137], v[180:183], v[126:129]
	v_mfma_f32_16x16x32_bf16 v[122:125], v[142:145], v[180:183], v[122:125]
	v_mfma_f32_16x16x32_bf16 v[118:121], v[134:137], v[188:191], v[118:121]
	v_mfma_f32_16x16x32_bf16 v[110:113], v[142:145], v[188:191], v[110:113]
	v_mfma_f32_16x16x32_bf16 v[98:101], v[134:137], v[196:199], v[98:101]
	v_mfma_f32_16x16x32_bf16 v[90:93], v[142:145], v[196:199], v[90:93]
	v_mfma_f32_16x16x32_bf16 v[82:85], v[134:137], v[204:207], v[82:85]
	v_mfma_f32_16x16x32_bf16 v[74:77], v[142:145], v[204:207], v[74:77]
	v_mfma_f32_16x16x32_bf16 v[114:117], v[160:163], v[176:179], v[114:117]
	v_mfma_f32_16x16x32_bf16 v[106:109], v[168:171], v[176:179], v[106:109]
	v_mfma_f32_16x16x32_bf16 v[102:105], v[160:163], v[184:187], v[102:105]
	v_mfma_f32_16x16x32_bf16 v[94:97], v[168:171], v[184:187], v[94:97]
	v_mfma_f32_16x16x32_bf16 v[86:89], v[160:163], v[192:195], v[86:89]
	v_mfma_f32_16x16x32_bf16 v[78:81], v[168:171], v[192:195], v[78:81]
	v_mfma_f32_16x16x32_bf16 v[70:73], v[160:163], v[200:203], v[70:73]
	v_mfma_f32_16x16x32_bf16 v[66:69], v[168:171], v[200:203], v[66:69]
	v_mfma_f32_16x16x32_bf16 v[114:117], v[164:167], v[180:183], v[114:117]
	v_mfma_f32_16x16x32_bf16 v[106:109], v[172:175], v[180:183], v[106:109]
	v_mfma_f32_16x16x32_bf16 v[102:105], v[164:167], v[188:191], v[102:105]
	v_mfma_f32_16x16x32_bf16 v[94:97], v[172:175], v[188:191], v[94:97]
	v_mfma_f32_16x16x32_bf16 v[86:89], v[164:167], v[196:199], v[86:89]
	v_mfma_f32_16x16x32_bf16 v[78:81], v[172:175], v[196:199], v[78:81]
	v_mfma_f32_16x16x32_bf16 v[70:73], v[164:167], v[204:207], v[70:73]
	v_mfma_f32_16x16x32_bf16 v[66:69], v[172:175], v[204:207], v[66:69]
	s_setprio 0
	s_barrier
	s_add_i32 s14, s54, s26
	v_lshl_add_u64 v[156:157], v[156:157], 0, s[96:97]
	s_mov_b32 m0, s14
	ds_read_b128 v[176:179], v159 offset:49152
	ds_read_b128 v[180:183], v159 offset:50176
	ds_read_b128 v[184:187], v159 offset:51200
	ds_read_b128 v[188:191], v159 offset:52224
	ds_read_b128 v[192:195], v159 offset:53248
	ds_read_b128 v[196:199], v159 offset:54272
	ds_read_b128 v[200:203], v159 offset:55296
	ds_read_b128 v[204:207], v159 offset:56320
	global_load_lds_dwordx4 v[156:157], off
	s_add_i32 m0, s14, 0x2000
	s_add_u32 s14, s18, 0xb0080
	v_lshl_add_u64 v[156:157], v[208:209], 0, s[96:97]
	s_addc_u32 s15, s19, 0
	s_add_i32 s18, s55, s26
	global_load_lds_dwordx4 v[156:157], off
	v_lshl_add_u64 v[156:157], s[14:15], 0, v[64:65]
	s_mov_b32 m0, s18
	s_nop 0
	global_load_lds_dwordx4 v[156:157], off
	v_lshl_add_u64 v[156:157], s[14:15], 0, v[146:147]
	s_add_i32 m0, s18, 0x2000
	s_nop 0
	global_load_lds_dwordx4 v[156:157], off
	v_lshl_add_u64 v[156:157], v[210:211], 0, s[96:97]
	s_mov_b32 m0, s38
	s_nop 0
	global_load_lds_dwordx4 v[156:157], off
	v_lshl_add_u64 v[156:157], v[212:213], 0, s[96:97]
	s_mov_b32 m0, s39
	s_nop 0
	global_load_lds_dwordx4 v[156:157], off
	s_waitcnt vmcnt(8)
	s_waitcnt lgkmcnt(0)
	s_barrier
	s_setprio 1
	s_waitcnt lgkmcnt(0)
	v_mfma_f32_16x16x32_bf16 v[60:63], v[130:133], v[176:179], v[60:63]
	v_mfma_f32_16x16x32_bf16 v[56:59], v[138:141], v[176:179], v[56:59]
	v_mfma_f32_16x16x32_bf16 v[48:51], v[130:133], v[184:187], v[48:51]
	v_mfma_f32_16x16x32_bf16 v[40:43], v[138:141], v[184:187], v[40:43]
	v_mfma_f32_16x16x32_bf16 v[32:35], v[130:133], v[192:195], v[32:35]
	v_mfma_f32_16x16x32_bf16 v[24:27], v[138:141], v[192:195], v[24:27]
	v_mfma_f32_16x16x32_bf16 v[16:19], v[130:133], v[200:203], v[16:19]
	v_mfma_f32_16x16x32_bf16 v[8:11], v[138:141], v[200:203], v[8:11]
	v_mfma_f32_16x16x32_bf16 v[60:63], v[134:137], v[180:183], v[60:63]
	v_mfma_f32_16x16x32_bf16 v[56:59], v[142:145], v[180:183], v[56:59]
	v_mfma_f32_16x16x32_bf16 v[48:51], v[134:137], v[188:191], v[48:51]
	v_mfma_f32_16x16x32_bf16 v[40:43], v[142:145], v[188:191], v[40:43]
	v_mfma_f32_16x16x32_bf16 v[32:35], v[134:137], v[196:199], v[32:35]
	v_mfma_f32_16x16x32_bf16 v[24:27], v[142:145], v[196:199], v[24:27]
	v_mfma_f32_16x16x32_bf16 v[16:19], v[134:137], v[204:207], v[16:19]
	v_mfma_f32_16x16x32_bf16 v[8:11], v[142:145], v[204:207], v[8:11]
	v_mfma_f32_16x16x32_bf16 v[52:55], v[160:163], v[176:179], v[52:55]
	v_mfma_f32_16x16x32_bf16 v[44:47], v[168:171], v[176:179], v[44:47]
	v_mfma_f32_16x16x32_bf16 v[36:39], v[160:163], v[184:187], v[36:39]
	v_mfma_f32_16x16x32_bf16 v[28:31], v[168:171], v[184:187], v[28:31]
	v_mfma_f32_16x16x32_bf16 v[20:23], v[160:163], v[192:195], v[20:23]
	v_mfma_f32_16x16x32_bf16 v[12:15], v[168:171], v[192:195], v[12:15]
	v_mfma_f32_16x16x32_bf16 v[4:7], v[160:163], v[200:203], v[4:7]
	v_mfma_f32_16x16x32_bf16 v[0:3], v[168:171], v[200:203], v[0:3]
	v_mfma_f32_16x16x32_bf16 v[52:55], v[164:167], v[180:183], v[52:55]
	v_mfma_f32_16x16x32_bf16 v[44:47], v[172:175], v[180:183], v[44:47]
	v_mfma_f32_16x16x32_bf16 v[36:39], v[164:167], v[188:191], v[36:39]
	v_mfma_f32_16x16x32_bf16 v[28:31], v[172:175], v[188:191], v[28:31]
	v_mfma_f32_16x16x32_bf16 v[20:23], v[164:167], v[196:199], v[20:23]
	v_mfma_f32_16x16x32_bf16 v[12:15], v[172:175], v[196:199], v[12:15]
	v_mfma_f32_16x16x32_bf16 v[4:7], v[164:167], v[204:207], v[4:7]
	v_mfma_f32_16x16x32_bf16 v[0:3], v[172:175], v[204:207], v[0:3]
	s_setprio 0
	s_barrier
	s_add_i32 s53, s53, 2
	s_add_u32 s47, s47, 0x100
	s_addc_u32 s52, s52, 0
	s_cmp_gt_u32 s53, 41
	s_mov_b64 s[14:15], s[16:17]
	s_cbranch_scc0 .LBB0_2501
	s_and_b64 vcc, exec, s[10:11]
	s_cbranch_vccz .LBB0_2504
	s_barrier

.LBB0_2521:
	s_add_i32 s39, 0, 0x10000
	s_add_i32 s38, 0, 0x14000
	v_add_u32_e32 v212, s39, v136
	v_add_u32_e32 v213, s38, v136
	ds_read_b128 v[0:3], v212
	ds_read_b128 v[4:7], v212 offset:1024
	ds_read_b128 v[8:11], v212 offset:2048
	ds_read_b128 v[12:15], v212 offset:3072
	ds_read_b128 v[16:19], v213
	ds_read_b128 v[20:23], v213 offset:1024
	ds_read_b128 v[24:27], v213 offset:2048
	ds_read_b128 v[28:31], v213 offset:3072
	s_add_u32 s36, s10, 0xb0080
	s_addc_u32 s37, s11, 0
	s_add_i32 s41, s19, 0xc000
	v_lshl_add_u64 v[66:67], s[36:37], 0, v[134:135]
	s_mov_b32 m0, s41
	s_add_i32 s35, s19, 0xe000
	ds_read_b128 v[32:35], v137
	ds_read_b128 v[36:39], v137 offset:1024
	ds_read_b128 v[40:43], v137 offset:2048
	ds_read_b128 v[44:47], v137 offset:3072
	ds_read_b128 v[48:51], v137 offset:4096
	ds_read_b128 v[52:55], v137 offset:5120
	ds_read_b128 v[56:59], v137 offset:6144
	ds_read_b128 v[60:63], v137 offset:7168
	global_load_lds_dwordx4 v[66:67], off
	v_lshl_add_u64 v[66:67], s[36:37], 0, v[132:133]
	s_mov_b32 m0, s35
	s_nop 0
	global_load_lds_dwordx4 v[66:67], off
	s_waitcnt vmcnt(8)
	s_waitcnt lgkmcnt(0)
	s_barrier
	s_setprio 1
	s_waitcnt lgkmcnt(0)
	v_mfma_f32_16x16x32_bf16 v[66:69], v[0:3], v[32:35], 0
	v_mfma_f32_16x16x32_bf16 v[70:73], v[8:11], v[32:35], 0
	v_mfma_f32_16x16x32_bf16 v[74:77], v[0:3], v[40:43], 0
	v_mfma_f32_16x16x32_bf16 v[78:81], v[8:11], v[40:43], 0
	v_mfma_f32_16x16x32_bf16 v[82:85], v[0:3], v[48:51], 0
	v_mfma_f32_16x16x32_bf16 v[86:89], v[8:11], v[48:51], 0
	v_mfma_f32_16x16x32_bf16 v[90:93], v[0:3], v[56:59], 0
	v_mfma_f32_16x16x32_bf16 v[94:97], v[8:11], v[56:59], 0
	v_mfma_f32_16x16x32_bf16 v[66:69], v[4:7], v[36:39], v[66:69]
	v_mfma_f32_16x16x32_bf16 v[70:73], v[12:15], v[36:39], v[70:73]
	v_mfma_f32_16x16x32_bf16 v[74:77], v[4:7], v[44:47], v[74:77]
	v_mfma_f32_16x16x32_bf16 v[78:81], v[12:15], v[44:47], v[78:81]
	v_mfma_f32_16x16x32_bf16 v[82:85], v[4:7], v[52:55], v[82:85]
	v_mfma_f32_16x16x32_bf16 v[86:89], v[12:15], v[52:55], v[86:89]
	v_mfma_f32_16x16x32_bf16 v[90:93], v[4:7], v[60:63], v[90:93]
	v_mfma_f32_16x16x32_bf16 v[94:97], v[12:15], v[60:63], v[94:97]
	v_mfma_f32_16x16x32_bf16 v[98:101], v[16:19], v[32:35], 0
	v_mfma_f32_16x16x32_bf16 v[32:35], v[24:27], v[32:35], 0
	v_mfma_f32_16x16x32_bf16 v[98:101], v[20:23], v[36:39], v[98:101]
	v_mfma_f32_16x16x32_bf16 v[32:35], v[28:31], v[36:39], v[32:35]
	v_mfma_f32_16x16x32_bf16 v[36:39], v[16:19], v[40:43], 0
	v_mfma_f32_16x16x32_bf16 v[40:43], v[24:27], v[40:43], 0
	v_mfma_f32_16x16x32_bf16 v[36:39], v[20:23], v[44:47], v[36:39]
	v_mfma_f32_16x16x32_bf16 v[40:43], v[28:31], v[44:47], v[40:43]
	v_mfma_f32_16x16x32_bf16 v[44:47], v[16:19], v[48:51], 0
	v_mfma_f32_16x16x32_bf16 v[48:51], v[24:27], v[48:51], 0
	v_mfma_f32_16x16x32_bf16 v[44:47], v[20:23], v[52:55], v[44:47]
	v_mfma_f32_16x16x32_bf16 v[48:51], v[28:31], v[52:55], v[48:51]
	v_mfma_f32_16x16x32_bf16 v[52:55], v[16:19], v[56:59], 0
	v_mfma_f32_16x16x32_bf16 v[56:59], v[24:27], v[56:59], 0
	v_mfma_f32_16x16x32_bf16 v[52:55], v[20:23], v[60:63], v[52:55]
	v_mfma_f32_16x16x32_bf16 v[56:59], v[28:31], v[60:63], v[56:59]
	s_setprio 0
	s_barrier
	s_add_i32 s39, s39, s18
	v_lshl_add_u64 v[202:203], s[12:13], 0, v[64:65]
	s_mov_b64 s[52:53], 0x100
	s_add_i32 s36, s39, 0x2000
	v_lshl_add_u64 v[138:139], v[202:203], 0, s[52:53]
	s_mov_b32 m0, s39
	v_lshl_add_u64 v[204:205], s[12:13], 0, v[130:131]
	s_add_u32 s48, s12, 0xb0100
	ds_read_b128 v[60:63], v137 offset:16384
	ds_read_b128 v[102:105], v137 offset:17408
	ds_read_b128 v[106:109], v137 offset:18432
	ds_read_b128 v[110:113], v137 offset:19456
	ds_read_b128 v[114:117], v137 offset:20480
	ds_read_b128 v[118:121], v137 offset:21504
	ds_read_b128 v[122:125], v137 offset:22528
	ds_read_b128 v[126:129], v137 offset:23552
	global_load_lds_dwordx4 v[138:139], off
	v_lshl_add_u64 v[138:139], v[204:205], 0, s[52:53]
	s_mov_b32 m0, s36
	s_addc_u32 s49, s13, 0
	s_add_i32 s37, s38, s18
	global_load_lds_dwordx4 v[138:139], off
	v_lshl_add_u64 v[138:139], s[48:49], 0, v[64:65]
	s_mov_b32 m0, s37
	s_add_i32 s38, s37, 0x2000
	global_load_lds_dwordx4 v[138:139], off
	v_lshl_add_u64 v[138:139], s[48:49], 0, v[130:131]
	s_mov_b32 m0, s38
	v_lshl_add_u64 v[206:207], s[10:11], 0, v[134:135]
	global_load_lds_dwordx4 v[138:139], off
	v_lshl_add_u64 v[138:139], v[206:207], 0, s[52:53]
	s_mov_b32 m0, s19
	v_lshl_add_u64 v[208:209], s[10:11], 0, v[132:133]
	global_load_lds_dwordx4 v[138:139], off
	v_lshl_add_u64 v[138:139], v[208:209], 0, s[52:53]
	s_mov_b32 m0, s20
	s_nop 0
	global_load_lds_dwordx4 v[138:139], off
	s_waitcnt vmcnt(8)
	s_waitcnt lgkmcnt(0)
	s_barrier
	s_setprio 1
	s_waitcnt lgkmcnt(0)
	v_mfma_f32_16x16x32_bf16 v[138:141], v[0:3], v[60:63], 0
	v_mfma_f32_16x16x32_bf16 v[146:149], v[0:3], v[106:109], 0
	v_mfma_f32_16x16x32_bf16 v[154:157], v[0:3], v[114:117], 0
	v_mfma_f32_16x16x32_bf16 v[0:3], v[0:3], v[122:125], 0
	v_mfma_f32_16x16x32_bf16 v[138:141], v[4:7], v[102:105], v[138:141]
	v_mfma_f32_16x16x32_bf16 v[146:149], v[4:7], v[110:113], v[146:149]
	v_mfma_f32_16x16x32_bf16 v[154:157], v[4:7], v[118:121], v[154:157]
	v_mfma_f32_16x16x32_bf16 v[0:3], v[4:7], v[126:129], v[0:3]
	v_mfma_f32_16x16x32_bf16 v[4:7], v[8:11], v[122:125], 0
	v_mfma_f32_16x16x32_bf16 v[142:145], v[8:11], v[60:63], 0
	v_mfma_f32_16x16x32_bf16 v[150:153], v[8:11], v[106:109], 0
	v_mfma_f32_16x16x32_bf16 v[158:161], v[8:11], v[114:117], 0
	v_mfma_f32_16x16x32_bf16 v[4:7], v[12:15], v[126:129], v[4:7]
	v_mfma_f32_16x16x32_bf16 v[142:145], v[12:15], v[102:105], v[142:145]
	v_mfma_f32_16x16x32_bf16 v[150:153], v[12:15], v[110:113], v[150:153]
	v_mfma_f32_16x16x32_bf16 v[158:161], v[12:15], v[118:121], v[158:161]
	v_mfma_f32_16x16x32_bf16 v[8:11], v[16:19], v[60:63], 0
	v_mfma_f32_16x16x32_bf16 v[12:15], v[24:27], v[60:63], 0
	v_mfma_f32_16x16x32_bf16 v[8:11], v[20:23], v[102:105], v[8:11]
	v_mfma_f32_16x16x32_bf16 v[12:15], v[28:31], v[102:105], v[12:15]
	v_mfma_f32_16x16x32_bf16 v[60:63], v[16:19], v[106:109], 0
	v_mfma_f32_16x16x32_bf16 v[102:105], v[24:27], v[106:109], 0
	v_mfma_f32_16x16x32_bf16 v[106:109], v[16:19], v[114:117], 0
	v_mfma_f32_16x16x32_bf16 v[16:19], v[16:19], v[122:125], 0
	v_mfma_f32_16x16x32_bf16 v[60:63], v[20:23], v[110:113], v[60:63]
	v_mfma_f32_16x16x32_bf16 v[102:105], v[28:31], v[110:113], v[102:105]
	v_mfma_f32_16x16x32_bf16 v[106:109], v[20:23], v[118:121], v[106:109]
	v_mfma_f32_16x16x32_bf16 v[110:113], v[24:27], v[114:117], 0
	v_mfma_f32_16x16x32_bf16 v[16:19], v[20:23], v[126:129], v[16:19]
	v_mfma_f32_16x16x32_bf16 v[20:23], v[24:27], v[122:125], 0
	v_mfma_f32_16x16x32_bf16 v[110:113], v[28:31], v[118:121], v[110:113]
	v_mfma_f32_16x16x32_bf16 v[20:23], v[28:31], v[126:129], v[20:23]
	s_setprio 0
	s_barrier
	s_add_i32 s43, 0, 0x18000
	s_add_i32 s51, 0, 0x1c000
	v_add_u32_e32 v214, s43, v136
	v_add_u32_e32 v215, s51, v136
	ds_read_b128 v[24:27], v214
	ds_read_b128 v[28:31], v214 offset:1024
	ds_read_b128 v[114:117], v214 offset:2048
	ds_read_b128 v[118:121], v214 offset:3072
	ds_read_b128 v[122:125], v215
	ds_read_b128 v[126:129], v215 offset:1024
	ds_read_b128 v[162:165], v215 offset:2048
	ds_read_b128 v[166:169], v215 offset:3072
	s_add_u32 s48, s10, 0xb0100
	s_addc_u32 s49, s11, 0
	s_mov_b32 m0, s21
	v_lshl_add_u64 v[210:211], s[48:49], 0, v[134:135]
	ds_read_b128 v[170:173], v137 offset:32768
	ds_read_b128 v[174:177], v137 offset:33792
	ds_read_b128 v[178:181], v137 offset:34816
	ds_read_b128 v[182:185], v137 offset:35840
	ds_read_b128 v[186:189], v137 offset:36864
	ds_read_b128 v[190:193], v137 offset:37888
	ds_read_b128 v[194:197], v137 offset:38912
	ds_read_b128 v[198:201], v137 offset:39936
	global_load_lds_dwordx4 v[210:211], off
	v_lshl_add_u64 v[210:211], s[48:49], 0, v[132:133]
	s_mov_b32 m0, s22
	s_nop 0
	global_load_lds_dwordx4 v[210:211], off
	s_waitcnt vmcnt(8)
	s_waitcnt lgkmcnt(0)
	s_barrier
	s_setprio 1
	s_waitcnt lgkmcnt(0)
	v_mfma_f32_16x16x32_bf16 v[66:69], v[24:27], v[170:173], v[66:69]
	v_mfma_f32_16x16x32_bf16 v[70:73], v[114:117], v[170:173], v[70:73]
	v_mfma_f32_16x16x32_bf16 v[74:77], v[24:27], v[178:181], v[74:77]
	v_mfma_f32_16x16x32_bf16 v[78:81], v[114:117], v[178:181], v[78:81]
	v_mfma_f32_16x16x32_bf16 v[82:85], v[24:27], v[186:189], v[82:85]
	v_mfma_f32_16x16x32_bf16 v[86:89], v[114:117], v[186:189], v[86:89]
	v_mfma_f32_16x16x32_bf16 v[90:93], v[24:27], v[194:197], v[90:93]
	v_mfma_f32_16x16x32_bf16 v[94:97], v[114:117], v[194:197], v[94:97]
	v_mfma_f32_16x16x32_bf16 v[66:69], v[28:31], v[174:177], v[66:69]
	v_mfma_f32_16x16x32_bf16 v[70:73], v[118:121], v[174:177], v[70:73]
	v_mfma_f32_16x16x32_bf16 v[74:77], v[28:31], v[182:185], v[74:77]
	v_mfma_f32_16x16x32_bf16 v[78:81], v[118:121], v[182:185], v[78:81]
	v_mfma_f32_16x16x32_bf16 v[82:85], v[28:31], v[190:193], v[82:85]
	v_mfma_f32_16x16x32_bf16 v[86:89], v[118:121], v[190:193], v[86:89]
	v_mfma_f32_16x16x32_bf16 v[90:93], v[28:31], v[198:201], v[90:93]
	v_mfma_f32_16x16x32_bf16 v[94:97], v[118:121], v[198:201], v[94:97]
	v_mfma_f32_16x16x32_bf16 v[98:101], v[122:125], v[170:173], v[98:101]
	v_mfma_f32_16x16x32_bf16 v[32:35], v[162:165], v[170:173], v[32:35]
	v_mfma_f32_16x16x32_bf16 v[36:39], v[122:125], v[178:181], v[36:39]
	v_mfma_f32_16x16x32_bf16 v[40:43], v[162:165], v[178:181], v[40:43]
	v_mfma_f32_16x16x32_bf16 v[44:47], v[122:125], v[186:189], v[44:47]
	v_mfma_f32_16x16x32_bf16 v[48:51], v[162:165], v[186:189], v[48:51]
	v_mfma_f32_16x16x32_bf16 v[52:55], v[122:125], v[194:197], v[52:55]
	v_mfma_f32_16x16x32_bf16 v[56:59], v[162:165], v[194:197], v[56:59]
	v_mfma_f32_16x16x32_bf16 v[98:101], v[126:129], v[174:177], v[98:101]
	v_mfma_f32_16x16x32_bf16 v[32:35], v[166:169], v[174:177], v[32:35]
	v_mfma_f32_16x16x32_bf16 v[36:39], v[126:129], v[182:185], v[36:39]
	v_mfma_f32_16x16x32_bf16 v[40:43], v[166:169], v[182:185], v[40:43]
	v_mfma_f32_16x16x32_bf16 v[44:47], v[126:129], v[190:193], v[44:47]
	v_mfma_f32_16x16x32_bf16 v[48:51], v[166:169], v[190:193], v[48:51]
	v_mfma_f32_16x16x32_bf16 v[52:55], v[126:129], v[198:201], v[52:55]
	v_mfma_f32_16x16x32_bf16 v[56:59], v[166:169], v[198:201], v[56:59]
	s_setprio 0
	s_barrier
	s_add_i32 s43, s43, s18
	s_mov_b64 s[52:53], 0x180
	s_add_i32 s40, s43, 0x2000
	v_lshl_add_u64 v[202:203], v[202:203], 0, s[52:53]
	s_mov_b32 m0, s43
	s_add_u32 s48, s12, 0xb0180
	ds_read_b128 v[170:173], v137 offset:49152
	ds_read_b128 v[174:177], v137 offset:50176
	ds_read_b128 v[178:181], v137 offset:51200
	ds_read_b128 v[182:185], v137 offset:52224
	ds_read_b128 v[186:189], v137 offset:53248
	ds_read_b128 v[190:193], v137 offset:54272
	ds_read_b128 v[194:197], v137 offset:55296
	ds_read_b128 v[198:201], v137 offset:56320
	global_load_lds_dwordx4 v[202:203], off
	v_lshl_add_u64 v[202:203], v[204:205], 0, s[52:53]
	s_mov_b32 m0, s40
	s_addc_u32 s49, s13, 0
	s_add_i32 s12, s51, s18
	global_load_lds_dwordx4 v[202:203], off
	v_lshl_add_u64 v[202:203], s[48:49], 0, v[64:65]
	s_mov_b32 m0, s12
	s_add_i32 s13, s12, 0x2000
	global_load_lds_dwordx4 v[202:203], off
	v_lshl_add_u64 v[202:203], s[48:49], 0, v[130:131]
	s_mov_b32 m0, s13
	s_nop 0
	global_load_lds_dwordx4 v[202:203], off
	v_lshl_add_u64 v[202:203], v[206:207], 0, s[52:53]
	s_mov_b32 m0, s25
	s_nop 0
	global_load_lds_dwordx4 v[202:203], off
	v_lshl_add_u64 v[202:203], v[208:209], 0, s[52:53]
	s_mov_b32 m0, s26
	s_nop 0
	global_load_lds_dwordx4 v[202:203], off
	s_waitcnt vmcnt(8)
	s_waitcnt lgkmcnt(0)
	s_barrier
	s_setprio 1
	s_waitcnt lgkmcnt(0)
	v_mfma_f32_16x16x32_bf16 v[0:3], v[24:27], v[194:197], v[0:3]
	v_mfma_f32_16x16x32_bf16 v[4:7], v[114:117], v[194:197], v[4:7]
	v_mfma_f32_16x16x32_bf16 v[138:141], v[24:27], v[170:173], v[138:141]
	v_mfma_f32_16x16x32_bf16 v[142:145], v[114:117], v[170:173], v[142:145]
	v_mfma_f32_16x16x32_bf16 v[146:149], v[24:27], v[178:181], v[146:149]
	v_mfma_f32_16x16x32_bf16 v[150:153], v[114:117], v[178:181], v[150:153]
	v_mfma_f32_16x16x32_bf16 v[154:157], v[24:27], v[186:189], v[154:157]
	v_mfma_f32_16x16x32_bf16 v[158:161], v[114:117], v[186:189], v[158:161]
	v_mfma_f32_16x16x32_bf16 v[0:3], v[28:31], v[198:201], v[0:3]
	v_mfma_f32_16x16x32_bf16 v[4:7], v[118:121], v[198:201], v[4:7]
	v_mfma_f32_16x16x32_bf16 v[138:141], v[28:31], v[174:177], v[138:141]
	v_mfma_f32_16x16x32_bf16 v[142:145], v[118:121], v[174:177], v[142:145]
	v_mfma_f32_16x16x32_bf16 v[146:149], v[28:31], v[182:185], v[146:149]
	v_mfma_f32_16x16x32_bf16 v[150:153], v[118:121], v[182:185], v[150:153]
	v_mfma_f32_16x16x32_bf16 v[154:157], v[28:31], v[190:193], v[154:157]
	v_mfma_f32_16x16x32_bf16 v[158:161], v[118:121], v[190:193], v[158:161]
	v_mfma_f32_16x16x32_bf16 v[8:11], v[122:125], v[170:173], v[8:11]
	v_mfma_f32_16x16x32_bf16 v[12:15], v[162:165], v[170:173], v[12:15]
	v_mfma_f32_16x16x32_bf16 v[24:27], v[122:125], v[178:181], v[60:63]
	v_mfma_f32_16x16x32_bf16 v[28:31], v[162:165], v[178:181], v[102:105]
	v_mfma_f32_16x16x32_bf16 v[60:63], v[122:125], v[186:189], v[106:109]
	v_mfma_f32_16x16x32_bf16 v[102:105], v[162:165], v[186:189], v[110:113]
	v_mfma_f32_16x16x32_bf16 v[16:19], v[122:125], v[194:197], v[16:19]
	v_mfma_f32_16x16x32_bf16 v[20:23], v[162:165], v[194:197], v[20:23]
	v_mfma_f32_16x16x32_bf16 v[8:11], v[126:129], v[174:177], v[8:11]
	v_mfma_f32_16x16x32_bf16 v[12:15], v[166:169], v[174:177], v[12:15]
	v_mfma_f32_16x16x32_bf16 v[24:27], v[126:129], v[182:185], v[24:27]
	v_mfma_f32_16x16x32_bf16 v[28:31], v[166:169], v[182:185], v[28:31]
	v_mfma_f32_16x16x32_bf16 v[60:63], v[126:129], v[190:193], v[60:63]
	v_mfma_f32_16x16x32_bf16 v[102:105], v[166:169], v[190:193], v[102:105]
	v_mfma_f32_16x16x32_bf16 v[16:19], v[126:129], v[198:201], v[16:19]
	v_mfma_f32_16x16x32_bf16 v[20:23], v[166:169], v[198:201], v[20:23]
	s_setprio 0
	s_barrier
	ds_read_b128 v[106:109], v212
	ds_read_b128 v[110:113], v212 offset:1024
	ds_read_b128 v[114:117], v212 offset:2048
	ds_read_b128 v[118:121], v212 offset:3072
	ds_read_b128 v[122:125], v213
	ds_read_b128 v[126:129], v213 offset:1024
	ds_read_b128 v[162:165], v213 offset:2048
	ds_read_b128 v[166:169], v213 offset:3072
	s_add_u32 s10, s10, 0xb0180
	s_addc_u32 s11, s11, 0
	s_mov_b32 m0, s41
	v_lshl_add_u64 v[202:203], s[10:11], 0, v[134:135]
	ds_read_b128 v[170:173], v137
	ds_read_b128 v[174:177], v137 offset:1024
	ds_read_b128 v[178:181], v137 offset:2048
	ds_read_b128 v[182:185], v137 offset:3072
	ds_read_b128 v[186:189], v137 offset:4096
	ds_read_b128 v[190:193], v137 offset:5120
	ds_read_b128 v[194:197], v137 offset:6144
	ds_read_b128 v[198:201], v137 offset:7168
	global_load_lds_dwordx4 v[202:203], off
	v_lshl_add_u64 v[202:203], s[10:11], 0, v[132:133]
	s_mov_b32 m0, s35
	s_nop 0
	global_load_lds_dwordx4 v[202:203], off
	s_waitcnt vmcnt(8)
	s_waitcnt lgkmcnt(0)
	s_barrier
	s_setprio 1
	s_waitcnt lgkmcnt(0)
	v_mfma_f32_16x16x32_bf16 v[66:69], v[106:109], v[170:173], v[66:69]
	v_mfma_f32_16x16x32_bf16 v[70:73], v[114:117], v[170:173], v[70:73]
	v_mfma_f32_16x16x32_bf16 v[74:77], v[106:109], v[178:181], v[74:77]
	v_mfma_f32_16x16x32_bf16 v[78:81], v[114:117], v[178:181], v[78:81]
	v_mfma_f32_16x16x32_bf16 v[82:85], v[106:109], v[186:189], v[82:85]
	v_mfma_f32_16x16x32_bf16 v[86:89], v[114:117], v[186:189], v[86:89]
	v_mfma_f32_16x16x32_bf16 v[90:93], v[106:109], v[194:197], v[90:93]
	v_mfma_f32_16x16x32_bf16 v[94:97], v[114:117], v[194:197], v[94:97]
	v_mfma_f32_16x16x32_bf16 v[66:69], v[110:113], v[174:177], v[66:69]
	v_mfma_f32_16x16x32_bf16 v[70:73], v[118:121], v[174:177], v[70:73]
	v_mfma_f32_16x16x32_bf16 v[74:77], v[110:113], v[182:185], v[74:77]
	v_mfma_f32_16x16x32_bf16 v[78:81], v[118:121], v[182:185], v[78:81]
	v_mfma_f32_16x16x32_bf16 v[82:85], v[110:113], v[190:193], v[82:85]
	v_mfma_f32_16x16x32_bf16 v[86:89], v[118:121], v[190:193], v[86:89]
	v_mfma_f32_16x16x32_bf16 v[90:93], v[110:113], v[198:201], v[90:93]
	v_mfma_f32_16x16x32_bf16 v[94:97], v[118:121], v[198:201], v[94:97]
	v_mfma_f32_16x16x32_bf16 v[44:47], v[122:125], v[186:189], v[44:47]
	v_mfma_f32_16x16x32_bf16 v[98:101], v[122:125], v[170:173], v[98:101]
	v_mfma_f32_16x16x32_bf16 v[32:35], v[162:165], v[170:173], v[32:35]
	v_mfma_f32_16x16x32_bf16 v[170:173], v[126:129], v[190:193], v[44:47]
	v_mfma_f32_16x16x32_bf16 v[44:47], v[162:165], v[186:189], v[48:51]
	v_mfma_f32_16x16x32_bf16 v[36:39], v[122:125], v[178:181], v[36:39]
	v_mfma_f32_16x16x32_bf16 v[40:43], v[162:165], v[178:181], v[40:43]
	v_mfma_f32_16x16x32_bf16 v[48:51], v[166:169], v[190:193], v[44:47]
	v_mfma_f32_16x16x32_bf16 v[44:47], v[122:125], v[194:197], v[52:55]
	v_mfma_f32_16x16x32_bf16 v[98:101], v[126:129], v[174:177], v[98:101]
	v_mfma_f32_16x16x32_bf16 v[32:35], v[166:169], v[174:177], v[32:35]
	v_mfma_f32_16x16x32_bf16 v[36:39], v[126:129], v[182:185], v[36:39]
	v_mfma_f32_16x16x32_bf16 v[40:43], v[166:169], v[182:185], v[40:43]
	v_mfma_f32_16x16x32_bf16 v[174:177], v[126:129], v[198:201], v[44:47]
	v_mfma_f32_16x16x32_bf16 v[44:47], v[162:165], v[194:197], v[56:59]
	v_mfma_f32_16x16x32_bf16 v[178:181], v[166:169], v[198:201], v[44:47]
	s_setprio 0
	s_barrier
	s_mov_b32 m0, s39
	v_lshl_add_u64 v[226:227], s[8:9], 0, v[64:65]
	s_add_u32 s10, s8, 0xb0000
	s_nop 1
	ds_read_b128 v[44:47], v137 offset:16384
	ds_read_b128 v[52:55], v137 offset:17408
	ds_read_b128 v[56:59], v137 offset:18432
	ds_read_b128 v[182:185], v137 offset:19456
	ds_read_b128 v[186:189], v137 offset:20480
	ds_read_b128 v[190:193], v137 offset:21504
	ds_read_b128 v[194:197], v137 offset:22528
	ds_read_b128 v[198:201], v137 offset:23552
	global_load_lds_dwordx4 v[226:227], off
	v_lshl_add_u64 v[232:233], s[8:9], 0, v[130:131]
	s_mov_b32 m0, s36
	s_addc_u32 s11, s9, 0
	global_load_lds_dwordx4 v[232:233], off
	v_lshl_add_u64 v[202:203], s[10:11], 0, v[64:65]
	s_mov_b32 m0, s37
	v_lshl_add_u64 v[236:237], s[6:7], 0, v[134:135]
	global_load_lds_dwordx4 v[202:203], off
	v_lshl_add_u64 v[202:203], s[10:11], 0, v[130:131]
	s_mov_b32 m0, s38
	v_lshl_add_u64 v[250:251], s[6:7], 0, v[132:133]
	global_load_lds_dwordx4 v[202:203], off
	s_mov_b32 m0, s19
	s_nop 0
	global_load_lds_dwordx4 v[236:237], off
	s_mov_b32 m0, s20
	s_nop 0
	global_load_lds_dwordx4 v[250:251], off
	s_waitcnt vmcnt(8)
	s_waitcnt lgkmcnt(0)
	s_barrier
	s_setprio 1
	s_waitcnt lgkmcnt(0)
	v_mfma_f32_16x16x32_bf16 v[0:3], v[106:109], v[194:197], v[0:3]
	v_mfma_f32_16x16x32_bf16 v[138:141], v[106:109], v[44:47], v[138:141]
	v_mfma_f32_16x16x32_bf16 v[146:149], v[106:109], v[56:59], v[146:149]
	v_mfma_f32_16x16x32_bf16 v[154:157], v[106:109], v[186:189], v[154:157]
	v_mfma_f32_16x16x32_bf16 v[106:109], v[110:113], v[198:201], v[0:3]
	v_mfma_f32_16x16x32_bf16 v[0:3], v[114:117], v[194:197], v[4:7]
	v_mfma_f32_16x16x32_bf16 v[138:141], v[110:113], v[52:55], v[138:141]
	v_mfma_f32_16x16x32_bf16 v[142:145], v[114:117], v[44:47], v[142:145]
	v_mfma_f32_16x16x32_bf16 v[146:149], v[110:113], v[182:185], v[146:149]
	v_mfma_f32_16x16x32_bf16 v[150:153], v[114:117], v[56:59], v[150:153]
	v_mfma_f32_16x16x32_bf16 v[154:157], v[110:113], v[190:193], v[154:157]
	v_mfma_f32_16x16x32_bf16 v[158:161], v[114:117], v[186:189], v[158:161]
	v_mfma_f32_16x16x32_bf16 v[110:113], v[118:121], v[198:201], v[0:3]
	v_mfma_f32_16x16x32_bf16 v[142:145], v[118:121], v[52:55], v[142:145]
	v_mfma_f32_16x16x32_bf16 v[150:153], v[118:121], v[182:185], v[150:153]
	v_mfma_f32_16x16x32_bf16 v[158:161], v[118:121], v[190:193], v[158:161]
	v_mfma_f32_16x16x32_bf16 v[0:3], v[122:125], v[44:47], v[8:11]
	v_mfma_f32_16x16x32_bf16 v[114:117], v[126:129], v[52:55], v[0:3]
	v_mfma_f32_16x16x32_bf16 v[0:3], v[162:165], v[44:47], v[12:15]
	v_mfma_f32_16x16x32_bf16 v[202:205], v[166:169], v[52:55], v[0:3]
	v_mfma_f32_16x16x32_bf16 v[0:3], v[122:125], v[56:59], v[24:27]
	v_mfma_f32_16x16x32_bf16 v[206:209], v[126:129], v[182:185], v[0:3]
	v_mfma_f32_16x16x32_bf16 v[0:3], v[162:165], v[56:59], v[28:31]
	v_mfma_f32_16x16x32_bf16 v[182:185], v[166:169], v[182:185], v[0:3]
	v_mfma_f32_16x16x32_bf16 v[0:3], v[122:125], v[186:189], v[60:63]
	v_mfma_f32_16x16x32_bf16 v[210:213], v[126:129], v[190:193], v[0:3]
	v_mfma_f32_16x16x32_bf16 v[0:3], v[162:165], v[186:189], v[102:105]
	v_mfma_f32_16x16x32_bf16 v[186:189], v[166:169], v[190:193], v[0:3]
	v_mfma_f32_16x16x32_bf16 v[0:3], v[122:125], v[194:197], v[16:19]
	v_mfma_f32_16x16x32_bf16 v[190:193], v[126:129], v[198:201], v[0:3]
	v_mfma_f32_16x16x32_bf16 v[0:3], v[162:165], v[194:197], v[20:23]
	v_mfma_f32_16x16x32_bf16 v[162:165], v[166:169], v[198:201], v[0:3]
	s_setprio 0
	s_barrier
	ds_read_b128 v[102:105], v214
	ds_read_b128 v[118:121], v214 offset:1024
	ds_read_b128 v[122:125], v214 offset:2048
	ds_read_b128 v[126:129], v214 offset:3072
	ds_read_b128 v[166:169], v215
	ds_read_b128 v[194:197], v215 offset:1024
	ds_read_b128 v[198:201], v215 offset:2048
	ds_read_b128 v[214:217], v215 offset:3072
	s_add_u32 s10, s6, 0xb0000
	s_addc_u32 s11, s7, 0
	s_mov_b32 m0, s21
	v_lshl_add_u64 v[0:1], s[10:11], 0, v[134:135]
	ds_read_b128 v[44:47], v137 offset:32768
	ds_read_b128 v[56:59], v137 offset:33792
	ds_read_b128 v[218:221], v137 offset:34816
	ds_read_b128 v[222:225], v137 offset:35840
	ds_read_b128 v[228:231], v137 offset:36864
	ds_read_b128 v[238:241], v137 offset:37888
	ds_read_b128 v[242:245], v137 offset:38912
	ds_read_b128 v[246:249], v137 offset:39936
	global_load_lds_dwordx4 v[0:1], off
	v_lshl_add_u64 v[0:1], s[10:11], 0, v[132:133]
	s_mov_b32 m0, s22
	s_nop 0
	global_load_lds_dwordx4 v[0:1], off
	s_waitcnt vmcnt(8)
	s_waitcnt lgkmcnt(0)
	s_barrier
	s_setprio 1
	s_waitcnt lgkmcnt(0)
	v_mfma_f32_16x16x32_bf16 v[0:3], v[102:105], v[44:47], v[66:69]
	v_mfma_f32_16x16x32_bf16 v[20:23], v[118:121], v[56:59], v[0:3]
	v_mfma_f32_16x16x32_bf16 v[0:3], v[122:125], v[44:47], v[70:73]
	v_mfma_f32_16x16x32_bf16 v[28:31], v[126:129], v[56:59], v[0:3]
	v_mfma_f32_16x16x32_bf16 v[0:3], v[102:105], v[218:221], v[74:77]
	v_mfma_f32_16x16x32_bf16 v[12:15], v[118:121], v[222:225], v[0:3]
	v_mfma_f32_16x16x32_bf16 v[0:3], v[122:125], v[218:221], v[78:81]
	v_mfma_f32_16x16x32_bf16 v[24:27], v[126:129], v[222:225], v[0:3]
	v_mfma_f32_16x16x32_bf16 v[0:3], v[102:105], v[228:231], v[82:85]
	v_mfma_f32_16x16x32_bf16 v[4:7], v[118:121], v[238:241], v[0:3]
	v_mfma_f32_16x16x32_bf16 v[0:3], v[122:125], v[228:231], v[86:89]
	v_mfma_f32_16x16x32_bf16 v[16:19], v[126:129], v[238:241], v[0:3]
	v_mfma_f32_16x16x32_bf16 v[0:3], v[102:105], v[242:245], v[90:93]
	v_mfma_f32_16x16x32_bf16 v[8:11], v[122:125], v[242:245], v[94:97]
	v_mfma_f32_16x16x32_bf16 v[0:3], v[118:121], v[246:249], v[0:3]
	v_mfma_f32_16x16x32_bf16 v[8:11], v[126:129], v[246:249], v[8:11]
	v_mfma_f32_16x16x32_bf16 v[32:35], v[198:201], v[44:47], v[32:35]
	v_mfma_f32_16x16x32_bf16 v[60:63], v[214:217], v[56:59], v[32:35]
	v_mfma_f32_16x16x32_bf16 v[32:35], v[166:169], v[218:221], v[36:39]
	v_mfma_f32_16x16x32_bf16 v[52:55], v[166:169], v[44:47], v[98:101]
	v_mfma_f32_16x16x32_bf16 v[44:47], v[194:197], v[222:225], v[32:35]
	v_mfma_f32_16x16x32_bf16 v[32:35], v[198:201], v[218:221], v[40:43]
	v_mfma_f32_16x16x32_bf16 v[52:55], v[194:197], v[56:59], v[52:55]
	v_mfma_f32_16x16x32_bf16 v[56:59], v[214:217], v[222:225], v[32:35]
	v_mfma_f32_16x16x32_bf16 v[32:35], v[166:169], v[228:231], v[170:173]
	v_mfma_f32_16x16x32_bf16 v[36:39], v[194:197], v[238:241], v[32:35]
	v_mfma_f32_16x16x32_bf16 v[32:35], v[198:201], v[228:231], v[48:51]
	v_mfma_f32_16x16x32_bf16 v[48:51], v[214:217], v[238:241], v[32:35]
	v_mfma_f32_16x16x32_bf16 v[32:35], v[166:169], v[242:245], v[174:177]
	v_mfma_f32_16x16x32_bf16 v[40:43], v[198:201], v[242:245], v[178:181]
	v_mfma_f32_16x16x32_bf16 v[32:35], v[194:197], v[246:249], v[32:35]
	v_mfma_f32_16x16x32_bf16 v[40:43], v[214:217], v[246:249], v[40:43]
	s_setprio 0
	s_barrier
	s_mov_b32 m0, s43
	v_lshl_add_u64 v[66:67], v[226:227], 0, s[96:97]
	s_add_u32 s10, s8, 0xb0080
	ds_read_b128 v[98:101], v137 offset:49152
	ds_read_b128 v[170:173], v137 offset:50176
	ds_read_b128 v[174:177], v137 offset:51200
	ds_read_b128 v[178:181], v137 offset:52224
	ds_read_b128 v[218:221], v137 offset:53248
	ds_read_b128 v[222:225], v137 offset:54272
	ds_read_b128 v[228:231], v137 offset:55296
	ds_read_b128 v[238:241], v137 offset:56320
	global_load_lds_dwordx4 v[66:67], off
	v_lshl_add_u64 v[66:67], v[232:233], 0, s[96:97]
	s_mov_b32 m0, s40
	s_addc_u32 s11, s9, 0
	global_load_lds_dwordx4 v[66:67], off
	v_lshl_add_u64 v[66:67], s[10:11], 0, v[64:65]
	s_mov_b32 m0, s12
	s_nop 0
	global_load_lds_dwordx4 v[66:67], off
	v_lshl_add_u64 v[66:67], s[10:11], 0, v[130:131]
	s_mov_b32 m0, s13
	s_nop 0
	global_load_lds_dwordx4 v[66:67], off
	v_lshl_add_u64 v[66:67], v[236:237], 0, s[96:97]
	s_mov_b32 m0, s25
	s_nop 0
	global_load_lds_dwordx4 v[66:67], off
	v_lshl_add_u64 v[66:67], v[250:251], 0, s[96:97]
	s_mov_b32 m0, s26
	s_nop 0
	global_load_lds_dwordx4 v[66:67], off
	s_waitcnt vmcnt(8)
	s_waitcnt lgkmcnt(0)
	s_barrier
	s_setprio 1
	s_waitcnt lgkmcnt(0)
	v_mfma_f32_16x16x32_bf16 v[66:69], v[102:105], v[98:101], v[138:141]
	v_mfma_f32_16x16x32_bf16 v[86:89], v[118:121], v[170:173], v[66:69]
	v_mfma_f32_16x16x32_bf16 v[66:69], v[122:125], v[98:101], v[142:145]
	v_mfma_f32_16x16x32_bf16 v[94:97], v[126:129], v[170:173], v[66:69]
	v_mfma_f32_16x16x32_bf16 v[66:69], v[102:105], v[174:177], v[146:149]
	v_mfma_f32_16x16x32_bf16 v[78:81], v[118:121], v[178:181], v[66:69]
	v_mfma_f32_16x16x32_bf16 v[66:69], v[122:125], v[174:177], v[150:153]
	v_mfma_f32_16x16x32_bf16 v[90:93], v[126:129], v[178:181], v[66:69]
	v_mfma_f32_16x16x32_bf16 v[66:69], v[102:105], v[218:221], v[154:157]
	v_mfma_f32_16x16x32_bf16 v[70:73], v[118:121], v[222:225], v[66:69]
	v_mfma_f32_16x16x32_bf16 v[66:69], v[122:125], v[218:221], v[158:161]
	v_mfma_f32_16x16x32_bf16 v[82:85], v[126:129], v[222:225], v[66:69]
	v_mfma_f32_16x16x32_bf16 v[66:69], v[102:105], v[228:231], v[106:109]
	v_mfma_f32_16x16x32_bf16 v[74:77], v[122:125], v[228:231], v[110:113]
	v_mfma_f32_16x16x32_bf16 v[66:69], v[118:121], v[238:241], v[66:69]
	v_mfma_f32_16x16x32_bf16 v[74:77], v[126:129], v[238:241], v[74:77]
	v_mfma_f32_16x16x32_bf16 v[102:105], v[166:169], v[98:101], v[114:117]
	v_mfma_f32_16x16x32_bf16 v[98:101], v[198:201], v[98:101], v[202:205]
	v_mfma_f32_16x16x32_bf16 v[126:129], v[214:217], v[170:173], v[98:101]
	v_mfma_f32_16x16x32_bf16 v[98:101], v[166:169], v[174:177], v[206:209]
	v_mfma_f32_16x16x32_bf16 v[110:113], v[194:197], v[178:181], v[98:101]
	v_mfma_f32_16x16x32_bf16 v[98:101], v[198:201], v[174:177], v[182:185]
	v_mfma_f32_16x16x32_bf16 v[122:125], v[214:217], v[178:181], v[98:101]
	v_mfma_f32_16x16x32_bf16 v[98:101], v[166:169], v[218:221], v[210:213]
	v_mfma_f32_16x16x32_bf16 v[118:121], v[194:197], v[170:173], v[102:105]
	v_mfma_f32_16x16x32_bf16 v[102:105], v[194:197], v[222:225], v[98:101]
	v_mfma_f32_16x16x32_bf16 v[98:101], v[198:201], v[218:221], v[186:189]
	v_mfma_f32_16x16x32_bf16 v[114:117], v[214:217], v[222:225], v[98:101]
	v_mfma_f32_16x16x32_bf16 v[98:101], v[166:169], v[228:231], v[190:193]
	v_mfma_f32_16x16x32_bf16 v[106:109], v[198:201], v[228:231], v[162:165]
	v_mfma_f32_16x16x32_bf16 v[98:101], v[194:197], v[238:241], v[98:101]
	v_mfma_f32_16x16x32_bf16 v[106:109], v[214:217], v[238:241], v[106:109]
	s_setprio 0
	s_barrier
	s_andn2_b64 vcc, exec, s[4:5]
	s_cbranch_vccnz .LBB0_2523
	s_barrier
